# v86 + rec in-proj log-f epilogue: lower-bound vectors loaded once per tile instead of once per row block; per-block vmcnt(0) dropped
# baseline (speedup 1.0000x reference)
.LBB0_422:
	s_nop 1
	v_lshlrev_b64 v[130:131], 11, v[150:151]
	s_and_b64 vcc, exec, s[4:5]
	v_ashrrev_i32_e32 v149, 31, v148
	v_lshl_add_u64 v[154:155], s[10:11], 0, v[154:155]
	v_lshl_add_u64 v[156:157], v[130:131], 2, s[12:13]
	s_cbranch_vccz .LBB0_424
	v_lshl_add_u64 v[160:161], v[148:149], 2, s[2:3]
	v_lshl_add_u64 v[130:131], s[14:15], 0, v[160:161]
	global_load_dwordx4 v[206:209], v[130:131], off
	global_load_dwordx4 v[210:213], v[130:131], off offset:16
	global_load_dwordx4 v[214:217], v[130:131], off offset:512
	global_load_dwordx4 v[218:221], v[130:131], off offset:528
	v_max_f32_e32 v151, v122, v122
	v_mul_f32_e64 v159, |v122|, s82
	v_mul_f32_e64 v165, |v126|, s82
	v_min_f32_e32 v162, 0, v151
	v_exp_f32_e32 v151, v159
	v_max_f32_e32 v163, v126, v126
	v_max_f32_e32 v168, v123, v123
	v_mul_f32_e64 v169, |v123|, s82
	v_mul_f32_e64 v170, |v127|, s82
	v_exp_f32_e32 v159, v165
	v_min_f32_e32 v164, 0, v163
	v_min_f32_e32 v163, 0, v168
	v_exp_f32_e32 v165, v169
	v_exp_f32_e32 v168, v170
	v_add_f32_e32 v151, 1.0, v151
	v_add_f32_e32 v159, 1.0, v159
	v_cmp_gt_f32_e32 vcc, s81, v151
	v_add_f32_e32 v165, 1.0, v165
	v_add_f32_e32 v171, 1.0, v168
	v_cndmask_b32_e64 v168, 0, 32, vcc
	v_cmp_gt_f32_e64 s[4:5], s81, v159
	v_cmp_gt_f32_e64 s[6:7], s81, v165
	v_ldexp_f32 v151, v151, v168
	v_cndmask_b32_e64 v169, 0, 32, s[4:5]
	v_cndmask_b32_e64 v170, 0, 32, s[6:7]
	v_ldexp_f32 v159, v159, v169
	v_log_f32_e32 v151, v151
	v_ldexp_f32 v165, v165, v170
	v_log_f32_e32 v159, v159
	v_log_f32_e32 v165, v165
	v_mul_f32_e32 v170, 0x3f317217, v151
	v_fma_f32 v170, v151, s65, -v170
	v_mul_f32_e32 v173, 0x3f317217, v159
	v_mul_f32_e32 v174, 0x3f317217, v165
	v_fma_f32 v173, v159, s65, -v173
	v_fmac_f32_e32 v170, 0x3377d1cf, v151
	v_cndmask_b32_e32 v168, 0, v203, vcc
	v_fma_f32 v174, v165, s65, -v174
	v_fmac_f32_e32 v173, 0x3377d1cf, v159
	v_fmac_f32_e32 v170, 0x3f317217, v151
	v_cmp_lt_f32_e64 vcc, |v151|, s56
	v_fmac_f32_e32 v174, 0x3377d1cf, v165
	v_fmac_f32_e32 v173, 0x3f317217, v159
	v_cndmask_b32_e32 v151, v151, v170, vcc
	v_cmp_lt_f32_e64 vcc, |v159|, s56
	v_fmac_f32_e32 v174, 0x3f317217, v165
	v_mul_f32_e32 v122, 0x3fb8aa3b, v122
	v_cndmask_b32_e32 v159, v159, v173, vcc
	v_cmp_lt_f32_e64 vcc, |v165|, s56
	v_cndmask_b32_e64 v169, 0, v203, s[4:5]
	v_cndmask_b32_e64 v172, 0, v203, s[6:7]
	v_cndmask_b32_e32 v165, v165, v174, vcc
	v_exp_f32_e32 v122, v122
	v_sub_f32_e32 v168, v151, v168
	v_sub_f32_e32 v170, v159, v169
	v_sub_f32_e32 v169, v165, v172
	v_pk_add_f32 v[162:163], v[162:163], v[168:169] neg_lo:[0,1] neg_hi:[0,1]
	v_add_f32_e32 v122, 1.0, v122
	v_mul_f32_e32 v151, 0x3fb8aa3b, v162
	v_exp_f32_e32 v151, v151
	v_rcp_f32_e32 v122, v122
	v_mul_f32_e32 v126, 0x3fb8aa3b, v126
	v_exp_f32_e32 v126, v126
	v_mul_f32_e32 v159, 0x3fb8aa3b, v163
	v_exp_f32_e32 v159, v159
	v_mul_f32_e32 v123, 0x3fb8aa3b, v123
	v_add_f32_e32 v126, 1.0, v126
	v_rcp_f32_e32 v126, v126
	v_exp_f32_e32 v123, v123
	s_waitcnt vmcnt(0)
	v_mov_b32_e32 v134, v206
	v_mov_b32_e32 v135, v207
	v_mov_b32_e32 v136, v208
	v_mov_b32_e32 v137, v209
	v_mov_b32_e32 v130, v210
	v_mov_b32_e32 v131, v211
	v_mov_b32_e32 v132, v212
	v_mov_b32_e32 v133, v213
	v_sub_f32_e32 v165, 1.0, v134
	v_fma_f32 v151, v151, v165, v134
	v_cmp_gt_f32_e64 s[4:5], s81, v151
	v_mul_f32_e32 v122, v122, v165
	v_sub_f32_e32 v168, 1.0, v130
	v_cndmask_b32_e64 v165, 0, 32, s[4:5]
	v_ldexp_f32 v151, v151, v165
	v_log_f32_e32 v151, v151
	v_mul_f32_e32 v174, v126, v168
	v_cndmask_b32_e64 v126, 0, v203, s[4:5]
	v_sub_f32_e32 v169, 1.0, v135
	v_mul_f32_e32 v165, 0x3f317217, v151
	v_fma_f32 v165, v151, s65, -v165
	v_fmac_f32_e32 v165, 0x3377d1cf, v151
	v_fmac_f32_e32 v165, 0x3f317217, v151
	v_cmp_lt_f32_e64 s[4:5], |v151|, s56
	v_fma_f32 v159, v159, v169, v135
	v_cmp_gt_f32_e32 vcc, s81, v159
	v_cndmask_b32_e64 v151, v151, v165, s[4:5]
	v_cmp_gt_f32_e64 s[4:5], s81, v171
	v_sub_f32_e32 v151, v151, v126
	v_cndmask_b32_e64 v172, 0, 32, vcc
	v_cndmask_b32_e64 v126, 0, 32, s[4:5]
	v_ldexp_f32 v126, v171, v126
	v_log_f32_e32 v126, v126
	v_ldexp_f32 v159, v159, v172
	v_max_f32_e32 v165, v127, v127
	v_log_f32_e32 v159, v159
	v_mul_f32_e32 v171, 0x3f317217, v126
	v_fma_f32 v171, v126, s65, -v171
	v_fmac_f32_e32 v171, 0x3377d1cf, v126
	v_fmac_f32_e32 v171, 0x3f317217, v126
	v_cmp_lt_f32_e64 s[6:7], |v126|, s56
	v_min_f32_e32 v165, 0, v165
	v_mul_f32_e32 v172, 0x3f317217, v159
	v_cndmask_b32_e64 v126, v126, v171, s[6:7]
	v_cndmask_b32_e64 v171, 0, v203, s[4:5]
	v_sub_f32_e32 v171, v126, v171
	v_pk_add_f32 v[164:165], v[164:165], v[170:171] neg_lo:[0,1] neg_hi:[0,1]
	v_fma_f32 v172, v159, s65, -v172
	v_mul_f32_e32 v126, 0x3fb8aa3b, v164
	v_exp_f32_e32 v126, v126
	v_fmac_f32_e32 v172, 0x3377d1cf, v159
	v_fmac_f32_e32 v172, 0x3f317217, v159
	v_cmp_lt_f32_e64 s[4:5], |v159|, s56
	v_fma_f32 v126, v126, v168, v130
	v_mul_f32_e32 v171, 0x3fb8aa3b, v165
	v_cndmask_b32_e64 v159, v159, v172, s[4:5]
	v_cmp_gt_f32_e64 s[4:5], s81, v126
	v_exp_f32_e32 v171, v171
	v_add_f32_e32 v123, 1.0, v123
	v_cndmask_b32_e64 v168, 0, 32, s[4:5]
	v_ldexp_f32 v126, v126, v168
	v_cndmask_b32_e32 v168, 0, v203, vcc
	v_log_f32_e32 v126, v126
	v_sub_f32_e32 v159, v159, v168
	v_sub_f32_e32 v168, 1.0, v131
	v_fma_f32 v171, v171, v168, v131
	v_cmp_gt_f32_e32 vcc, s81, v171
	v_mul_f32_e32 v170, 0x3f317217, v126
	v_fma_f32 v170, v126, s65, -v170
	v_cndmask_b32_e64 v172, 0, 32, vcc
	v_ldexp_f32 v171, v171, v172
	v_log_f32_e32 v171, v171
	v_fmac_f32_e32 v170, 0x3377d1cf, v126
	v_fmac_f32_e32 v170, 0x3f317217, v126
	v_cmp_lt_f32_e64 s[6:7], |v126|, s56
	v_rcp_f32_e32 v123, v123
	v_sub_f32_e32 v178, 1.0, v132
	v_cndmask_b32_e64 v126, v126, v170, s[6:7]
	v_cndmask_b32_e64 v170, 0, v203, s[4:5]
	v_sub_f32_e32 v175, v126, v170
	v_mul_f32_e32 v126, 0x3f317217, v171
	v_fma_f32 v126, v171, s65, -v126
	v_fmac_f32_e32 v126, 0x3377d1cf, v171
	v_fmac_f32_e32 v126, 0x3f317217, v171
	v_cmp_lt_f32_e64 s[4:5], |v171|, s56
	v_cndmask_b32_e32 v170, 0, v203, vcc
	v_mul_f32_e32 v123, v123, v169
	v_cndmask_b32_e64 v126, v171, v126, s[4:5]
	v_sub_f32_e32 v176, v126, v170
	v_mul_f32_e32 v126, 0x3fb8aa3b, v127
	v_mul_f32_e64 v127, |v124|, s82
	v_exp_f32_e32 v127, v127
	v_exp_f32_e32 v126, v126
	v_sub_f32_e32 v171, 1.0, v136
	v_add_f32_e32 v127, 1.0, v127
	v_cmp_gt_f32_e32 vcc, s81, v127
	v_add_f32_e32 v126, 1.0, v126
	v_rcp_f32_e32 v126, v126
	v_cndmask_b32_e64 v169, 0, 32, vcc
	v_ldexp_f32 v127, v127, v169
	v_log_f32_e32 v127, v127
	v_mul_f32_e32 v177, v126, v168
	v_mul_f32_e64 v169, |v128|, s82
	v_exp_f32_e32 v169, v169
	v_mul_f32_e32 v168, 0x3f317217, v127
	v_fma_f32 v168, v127, s65, -v168
	v_fmac_f32_e32 v168, 0x3377d1cf, v127
	v_fmac_f32_e32 v168, 0x3f317217, v127
	v_cmp_lt_f32_e64 s[4:5], |v127|, s56
	v_max_f32_e32 v126, v124, v124
	v_min_f32_e32 v126, 0, v126
	v_cndmask_b32_e64 v127, v127, v168, s[4:5]
	v_cndmask_b32_e32 v168, 0, v203, vcc
	v_sub_f32_e32 v168, v127, v168
	v_add_f32_e32 v127, 1.0, v169
	v_cmp_gt_f32_e32 vcc, s81, v127
	v_mul_f32_e32 v124, 0x3fb8aa3b, v124
	v_exp_f32_e32 v124, v124
	v_cndmask_b32_e64 v169, 0, 32, vcc
	v_ldexp_f32 v127, v127, v169
	v_log_f32_e32 v127, v127
	v_max_f32_e32 v169, v128, v128
	v_min_f32_e32 v170, 0, v169
	v_mul_f32_e32 v128, 0x3fb8aa3b, v128
	v_mul_f32_e32 v169, 0x3f317217, v127
	v_fma_f32 v169, v127, s65, -v169
	v_fmac_f32_e32 v169, 0x3377d1cf, v127
	v_fmac_f32_e32 v169, 0x3f317217, v127
	v_cmp_lt_f32_e64 s[4:5], |v127|, s56
	v_add_f32_e32 v124, 1.0, v124
	v_exp_f32_e32 v128, v128
	v_cndmask_b32_e64 v127, v127, v169, s[4:5]
	v_cndmask_b32_e32 v169, 0, v203, vcc
	v_sub_f32_e32 v172, v127, v169
	v_mul_f32_e64 v127, |v125|, s82
	v_exp_f32_e32 v127, v127
	v_rcp_f32_e32 v124, v124
	v_add_f32_e32 v128, 1.0, v128
	v_rcp_f32_e32 v128, v128
	v_add_f32_e32 v127, 1.0, v127
	v_cmp_gt_f32_e32 vcc, s81, v127
	v_mul_f32_e32 v179, v128, v178
	s_nop 0
	v_cndmask_b32_e64 v169, 0, 32, vcc
	v_ldexp_f32 v127, v127, v169
	v_log_f32_e32 v169, v127
	v_max_f32_e32 v127, v125, v125
	v_min_f32_e32 v127, 0, v127
	v_sub_f32_e32 v128, 1.0, v137
	v_mul_f32_e32 v173, 0x3f317217, v169
	v_fma_f32 v173, v169, s65, -v173
	v_fmac_f32_e32 v173, 0x3377d1cf, v169
	v_fmac_f32_e32 v173, 0x3f317217, v169
	v_cmp_lt_f32_e64 s[4:5], |v169|, s56
	v_mul_f32_e32 v125, 0x3fb8aa3b, v125
	v_exp_f32_e32 v125, v125
	v_cndmask_b32_e64 v169, v169, v173, s[4:5]
	v_cndmask_b32_e32 v173, 0, v203, vcc
	v_sub_f32_e32 v169, v169, v173
	v_pk_add_f32 v[126:127], v[126:127], v[168:169] neg_lo:[0,1] neg_hi:[0,1]
	s_nop 0
	v_mul_f32_e32 v168, 0x3fb8aa3b, v126
	v_exp_f32_e32 v168, v168
	s_nop 0
	v_fma_f32 v168, v168, v171, v136
	v_cmp_gt_f32_e32 vcc, s81, v168
	s_nop 1
	v_cndmask_b32_e64 v169, 0, 32, vcc
	v_ldexp_f32 v168, v168, v169
	v_mul_f32_e32 v169, v124, v171
	v_mul_f32_e32 v171, 0x3fb8aa3b, v127
	v_exp_f32_e32 v171, v171
	v_log_f32_e32 v168, v168
	v_fma_f32 v171, v171, v128, v137
	v_cmp_gt_f32_e64 s[4:5], s81, v171
	v_mul_f32_e32 v124, 0x3f317217, v168
	v_fma_f32 v124, v168, s65, -v124
	v_cndmask_b32_e64 v173, 0, 32, s[4:5]
	v_ldexp_f32 v171, v171, v173
	v_log_f32_e32 v171, v171
	v_fmac_f32_e32 v124, 0x3377d1cf, v168
	v_fmac_f32_e32 v124, 0x3f317217, v168
	v_cmp_lt_f32_e64 s[6:7], |v168|, s56
	v_mul_f32_e64 v173, |v129|, s82
	v_exp_f32_e32 v173, v173
	v_cndmask_b32_e64 v124, v168, v124, s[6:7]
	v_cndmask_b32_e32 v168, 0, v203, vcc
	v_sub_f32_e32 v124, v124, v168
	v_mul_f32_e32 v168, 0x3f317217, v171
	v_fma_f32 v168, v171, s65, -v168
	v_fmac_f32_e32 v168, 0x3377d1cf, v171
	v_fmac_f32_e32 v168, 0x3f317217, v171
	v_cmp_lt_f32_e64 vcc, |v171|, s56
	s_nop 1
	v_cndmask_b32_e32 v168, v171, v168, vcc
	v_cmp_lt_f32_e32 vcc, 0, v135
	v_cndmask_b32_e64 v171, 0, v203, s[4:5]
	v_cmp_lt_f32_e64 s[4:5], 0, v134
	v_cndmask_b32_e32 v135, v163, v159, vcc
	v_add_f32_e32 v159, 1.0, v173
	v_cmp_gt_f32_e32 vcc, s81, v159
	v_cndmask_b32_e64 v134, v162, v151, s[4:5]
	v_max_f32_e32 v151, v129, v129
	v_cndmask_b32_e64 v163, 0, 32, vcc
	v_ldexp_f32 v159, v159, v163
	v_log_f32_e32 v159, v159
	v_sub_f32_e32 v168, v168, v171
	v_min_f32_e32 v171, 0, v151
	v_pk_mul_f32 v[134:135], v[134:135], s[68:69] op_sel_hi:[1,0]
	v_mul_f32_e32 v151, 0x3f317217, v159
	v_fma_f32 v151, v159, s65, -v151
	v_fmac_f32_e32 v151, 0x3377d1cf, v159
	v_fmac_f32_e32 v151, 0x3f317217, v159
	v_cmp_lt_f32_e64 s[4:5], |v159|, s56
	s_nop 1
	v_cndmask_b32_e64 v151, v159, v151, s[4:5]
	v_cndmask_b32_e32 v159, 0, v203, vcc
	v_sub_f32_e32 v173, v151, v159
	v_pk_add_f32 v[162:163], v[170:171], v[172:173] neg_lo:[0,1] neg_hi:[0,1]
	v_cmp_lt_f32_e32 vcc, 0, v137
	v_mul_f32_e32 v151, 0x3fb8aa3b, v162
	v_exp_f32_e32 v151, v151
	v_cndmask_b32_e32 v127, v127, v168, vcc
	v_cmp_lt_f32_e32 vcc, 0, v136
	s_nop 1
	v_cndmask_b32_e32 v126, v126, v124, vcc
	v_fma_f32 v124, v151, v178, v132
	v_cmp_gt_f32_e32 vcc, s81, v124
	v_sub_f32_e32 v151, 1.0, v133
	s_nop 0
	v_cndmask_b32_e64 v136, 0, 32, vcc
	v_ldexp_f32 v124, v124, v136
	v_pk_mul_f32 v[136:137], v[126:127], s[68:69] op_sel_hi:[1,0]
	v_mul_f32_e32 v127, 0x3fb8aa3b, v163
	v_exp_f32_e32 v127, v127
	v_log_f32_e32 v124, v124
	v_fma_f32 v127, v127, v151, v133
	v_cmp_gt_f32_e64 s[4:5], s81, v127
	v_mul_f32_e32 v126, 0x3f317217, v124
	v_fma_f32 v126, v124, s65, -v126
	v_cndmask_b32_e64 v159, 0, 32, s[4:5]
	v_ldexp_f32 v127, v127, v159
	v_log_f32_e32 v127, v127
	v_fmac_f32_e32 v126, 0x3377d1cf, v124
	v_fmac_f32_e32 v126, 0x3f317217, v124
	v_cmp_lt_f32_e64 s[6:7], |v124|, s56
	s_nop 1
	v_cndmask_b32_e64 v124, v124, v126, s[6:7]
	v_cndmask_b32_e32 v126, 0, v203, vcc
	v_sub_f32_e32 v124, v124, v126
	v_mul_f32_e32 v126, 0x3f317217, v127
	v_fma_f32 v126, v127, s65, -v126
	v_fmac_f32_e32 v126, 0x3377d1cf, v127
	v_fmac_f32_e32 v126, 0x3f317217, v127
	v_cmp_lt_f32_e64 vcc, |v127|, s56
	s_nop 1
	v_cndmask_b32_e32 v126, v127, v126, vcc
	v_cmp_lt_f32_e32 vcc, 0, v131
	v_cndmask_b32_e64 v127, 0, v203, s[4:5]
	v_sub_f32_e32 v126, v126, v127
	v_cndmask_b32_e32 v131, v165, v176, vcc
	v_cmp_lt_f32_e32 vcc, 0, v130
	s_nop 1
	v_cndmask_b32_e32 v130, v164, v175, vcc
	v_cmp_lt_f32_e32 vcc, 0, v133
	s_nop 1
	v_cndmask_b32_e32 v127, v163, v126, vcc
	v_mul_f32_e32 v126, 0x3fb8aa3b, v129
	v_exp_f32_e32 v129, v126
	v_cmp_lt_f32_e32 vcc, 0, v132
	s_nop 1
	v_cndmask_b32_e32 v126, v162, v124, vcc
	v_add_f32_e32 v124, 1.0, v125
	v_rcp_f32_e32 v132, v124
	v_add_f32_e32 v124, 1.0, v129
	v_rcp_f32_e32 v129, v124
	v_pk_mul_f32 v[126:127], v[126:127], s[68:69] op_sel_hi:[1,0]
	v_pk_mul_f32 v[124:125], v[130:131], s[68:69] op_sel_hi:[1,0]
	v_mul_f32_e32 v130, v132, v128
	v_mul_f32_e32 v131, v129, v151
	v_lshl_add_u64 v[128:129], v[156:157], 0, v[160:161]
	global_store_dwordx4 v[128:129], v[134:137], off
	global_store_dwordx4 v[128:129], v[124:127], off offset:16
	v_cvt_pk_bf16_f32 v122, v122, v123
	v_cvt_pk_bf16_f32 v123, v169, v130
	s_nop 1
	v_lshl_add_u64 v[126:127], v[148:149], 1, v[154:155]
	v_cvt_pk_bf16_f32 v124, v174, v177
	v_cvt_pk_bf16_f32 v125, v179, v131
	global_store_dwordx4 v[126:127], v[122:125], off

.LBB0_435:
	v_lshl_add_u64 v[130:131], v[148:149], 2, s[26:27]
	v_lshl_add_u64 v[122:123], s[14:15], 0, v[130:131]
	v_mov_b32_e32 v126, v214
	v_mov_b32_e32 v127, v215
	v_mov_b32_e32 v128, v216
	v_mov_b32_e32 v129, v217
	v_mov_b32_e32 v122, v218
	v_mov_b32_e32 v123, v219
	v_mov_b32_e32 v124, v220
	v_mov_b32_e32 v125, v221
	v_mul_f32_e64 v133, |v118|, s82
	v_mul_f32_e64 v135, |v114|, s82
	v_max_f32_e32 v136, v119, v119
	v_mul_f32_e64 v137, |v119|, s82
	v_exp_f32_e32 v158, v133
	v_max_f32_e32 v134, v114, v114
	v_mul_f32_e32 v114, 0x3fb8aa3b, v114
	v_mul_f32_e64 v151, |v115|, s82
	v_exp_f32_e32 v135, v135
	v_min_f32_e32 v133, 0, v136
	v_exp_f32_e32 v136, v137
	v_exp_f32_e32 v114, v114
	v_exp_f32_e32 v137, v151
	v_add_f32_e32 v151, 1.0, v158
	v_add_f32_e32 v135, 1.0, v135
	v_add_f32_e32 v136, 1.0, v136
	v_cmp_gt_f32_e32 vcc, s81, v151
	v_add_f32_e32 v114, 1.0, v114
	v_add_f32_e32 v159, 1.0, v137
	v_cndmask_b32_e64 v137, 0, 32, vcc
	v_cmp_gt_f32_e64 s[4:5], s81, v135
	v_cmp_gt_f32_e64 s[6:7], s81, v136
	v_rcp_f32_e32 v160, v114
	v_cndmask_b32_e64 v158, 0, 32, s[4:5]
	v_cndmask_b32_e64 v114, 0, 32, s[6:7]
	v_ldexp_f32 v137, v151, v137
	v_ldexp_f32 v135, v135, v158
	v_ldexp_f32 v114, v136, v114
	v_log_f32_e32 v136, v137
	v_log_f32_e32 v135, v135
	v_log_f32_e32 v114, v114
	v_cndmask_b32_e32 v151, 0, v203, vcc
	v_mul_f32_e32 v161, 0x3f317217, v136
	v_mul_f32_e32 v162, 0x3f317217, v135
	v_fma_f32 v161, v136, s65, -v161
	v_mul_f32_e32 v163, 0x3f317217, v114
	v_fma_f32 v162, v135, s65, -v162
	v_fmac_f32_e32 v161, 0x3377d1cf, v136
	v_fma_f32 v163, v114, s65, -v163
	v_fmac_f32_e32 v162, 0x3377d1cf, v135
	v_fmac_f32_e32 v161, 0x3f317217, v136
	v_cmp_lt_f32_e64 vcc, |v136|, s56
	v_max_f32_e32 v132, v118, v118
	v_mul_f32_e32 v118, 0x3fb8aa3b, v118
	v_fmac_f32_e32 v163, 0x3377d1cf, v114
	v_fmac_f32_e32 v162, 0x3f317217, v135
	v_cndmask_b32_e32 v136, v136, v161, vcc
	v_cmp_lt_f32_e64 vcc, |v135|, s56
	v_exp_f32_e32 v118, v118
	v_fmac_f32_e32 v163, 0x3f317217, v114
	v_cndmask_b32_e32 v135, v135, v162, vcc
	v_cmp_lt_f32_e64 vcc, |v114|, s56
	v_cndmask_b32_e64 v137, 0, v203, s[6:7]
	v_min_f32_e32 v132, 0, v132
	v_cndmask_b32_e32 v114, v114, v163, vcc
	v_sub_f32_e32 v136, v136, v151
	v_sub_f32_e32 v137, v114, v137
	v_pk_add_f32 v[132:133], v[132:133], v[136:137] neg_lo:[0,1] neg_hi:[0,1]
	v_add_f32_e32 v118, 1.0, v118
	v_mul_f32_e32 v114, 0x3fb8aa3b, v132
	v_rcp_f32_e32 v118, v118
	v_exp_f32_e32 v136, v114
	v_cndmask_b32_e64 v158, 0, v203, s[4:5]
	v_sub_f32_e32 v158, v135, v158
	v_mul_f32_e32 v135, 0x3fb8aa3b, v133
	v_exp_f32_e32 v135, v135
	v_min_f32_e32 v134, 0, v134
	v_mul_f32_e32 v119, 0x3fb8aa3b, v119
	v_exp_f32_e32 v119, v119
	v_sub_f32_e32 v137, 1.0, v126
	v_mul_f32_e32 v114, v118, v137
	v_fma_f32 v118, v136, v137, v126
	v_cmp_gt_f32_e64 s[4:5], s81, v118
	v_sub_f32_e32 v161, 1.0, v127
	v_fma_f32 v135, v135, v161, v127
	v_cndmask_b32_e64 v136, 0, 32, s[4:5]
	v_ldexp_f32 v118, v118, v136
	v_log_f32_e32 v118, v118
	v_cmp_gt_f32_e32 vcc, s81, v135
	v_sub_f32_e32 v151, 1.0, v122
	v_mul_f32_e32 v162, v160, v151
	v_cndmask_b32_e64 v137, 0, 32, vcc
	v_ldexp_f32 v135, v135, v137
	v_mul_f32_e32 v137, 0x3f317217, v118
	v_fma_f32 v137, v118, s65, -v137
	v_fmac_f32_e32 v137, 0x3377d1cf, v118
	v_log_f32_e32 v136, v135
	v_cndmask_b32_e64 v135, 0, v203, s[4:5]
	v_fmac_f32_e32 v137, 0x3f317217, v118
	v_cmp_lt_f32_e64 s[4:5], |v118|, s56
	v_mul_f32_e32 v160, 0x3f317217, v136
	v_fma_f32 v160, v136, s65, -v160
	v_cndmask_b32_e64 v118, v118, v137, s[4:5]
	v_cmp_gt_f32_e64 s[4:5], s81, v159
	v_sub_f32_e32 v163, v118, v135
	v_max_f32_e32 v135, v115, v115
	v_cndmask_b32_e64 v118, 0, 32, s[4:5]
	v_ldexp_f32 v118, v159, v118
	v_log_f32_e32 v118, v118
	v_min_f32_e32 v135, 0, v135
	v_fmac_f32_e32 v160, 0x3377d1cf, v136
	v_fmac_f32_e32 v160, 0x3f317217, v136
	v_mul_f32_e32 v137, 0x3f317217, v118
	v_fma_f32 v137, v118, s65, -v137
	v_fmac_f32_e32 v137, 0x3377d1cf, v118
	v_fmac_f32_e32 v137, 0x3f317217, v118
	v_cmp_lt_f32_e64 s[6:7], |v118|, s56
	v_mul_f32_e32 v115, 0x3fb8aa3b, v115
	v_exp_f32_e32 v115, v115
	v_cndmask_b32_e64 v118, v118, v137, s[6:7]
	v_cndmask_b32_e64 v137, 0, v203, s[4:5]
	v_sub_f32_e32 v159, v118, v137
	v_pk_add_f32 v[134:135], v[134:135], v[158:159] neg_lo:[0,1] neg_hi:[0,1]
	v_cmp_lt_f32_e64 s[4:5], |v136|, s56
	v_mul_f32_e32 v118, 0x3fb8aa3b, v134
	v_exp_f32_e32 v118, v118
	v_mul_f32_e32 v158, 0x3fb8aa3b, v135
	v_cndmask_b32_e64 v136, v136, v160, s[4:5]
	v_exp_f32_e32 v158, v158
	v_fma_f32 v118, v118, v151, v122
	v_cmp_gt_f32_e64 s[4:5], s81, v118
	v_add_f32_e32 v115, 1.0, v115
	v_rcp_f32_e32 v115, v115
	v_cndmask_b32_e64 v137, 0, 32, s[4:5]
	v_ldexp_f32 v118, v118, v137
	v_cndmask_b32_e32 v137, 0, v203, vcc
	v_log_f32_e32 v118, v118
	v_sub_f32_e32 v151, v136, v137
	v_sub_f32_e32 v136, 1.0, v123
	v_fma_f32 v158, v158, v136, v123
	v_cmp_gt_f32_e32 vcc, s81, v158
	v_mul_f32_e32 v137, 0x3f317217, v118
	v_fma_f32 v137, v118, s65, -v137
	v_cndmask_b32_e64 v159, 0, 32, vcc
	v_ldexp_f32 v158, v158, v159
	v_log_f32_e32 v158, v158
	v_fmac_f32_e32 v137, 0x3377d1cf, v118
	v_fmac_f32_e32 v137, 0x3f317217, v118
	v_cmp_lt_f32_e64 s[6:7], |v118|, s56
	v_mul_f32_e32 v169, v115, v136
	v_max_f32_e32 v115, v120, v120
	v_cndmask_b32_e64 v118, v118, v137, s[6:7]
	v_cndmask_b32_e64 v137, 0, v203, s[4:5]
	v_sub_f32_e32 v164, v118, v137
	v_mul_f32_e32 v118, 0x3f317217, v158
	v_fma_f32 v118, v158, s65, -v118
	v_fmac_f32_e32 v118, 0x3377d1cf, v158
	v_fmac_f32_e32 v118, 0x3f317217, v158
	v_cmp_lt_f32_e64 s[4:5], |v158|, s56
	v_cndmask_b32_e32 v137, 0, v203, vcc
	v_mul_f32_e64 v136, |v116|, s82
	v_cndmask_b32_e64 v118, v158, v118, s[4:5]
	v_sub_f32_e32 v165, v118, v137
	v_add_f32_e32 v118, 1.0, v119
	v_mul_f32_e64 v119, |v120|, s82
	v_rcp_f32_e32 v118, v118
	v_exp_f32_e32 v119, v119
	v_exp_f32_e32 v137, v136
	v_sub_f32_e32 v159, 1.0, v128
	v_mul_f32_e32 v168, v118, v161
	v_add_f32_e32 v118, 1.0, v119
	v_cmp_gt_f32_e32 vcc, s81, v118
	v_sub_f32_e32 v170, 1.0, v129
	s_nop 0
	v_cndmask_b32_e64 v119, 0, 32, vcc
	v_ldexp_f32 v118, v118, v119
	v_log_f32_e32 v119, v118
	v_min_f32_e32 v118, 0, v115
	v_mul_f32_e32 v115, 0x3f317217, v119
	v_fma_f32 v115, v119, s65, -v115
	v_fmac_f32_e32 v115, 0x3377d1cf, v119
	v_fmac_f32_e32 v115, 0x3f317217, v119
	v_cmp_lt_f32_e64 s[4:5], |v119|, s56
	s_nop 1
	v_cndmask_b32_e64 v115, v119, v115, s[4:5]
	v_cndmask_b32_e32 v119, 0, v203, vcc
	v_sub_f32_e32 v136, v115, v119
	v_add_f32_e32 v115, 1.0, v137
	v_cmp_gt_f32_e32 vcc, s81, v115
	s_nop 1
	v_cndmask_b32_e64 v119, 0, 32, vcc
	v_ldexp_f32 v115, v115, v119
	v_log_f32_e32 v115, v115
	v_max_f32_e32 v119, v116, v116
	v_min_f32_e32 v158, 0, v119
	v_mul_f32_e32 v116, 0x3fb8aa3b, v116
	v_mul_f32_e32 v119, 0x3f317217, v115
	v_fma_f32 v119, v115, s65, -v119
	v_fmac_f32_e32 v119, 0x3377d1cf, v115
	v_fmac_f32_e32 v119, 0x3f317217, v115
	v_cmp_lt_f32_e64 s[4:5], |v115|, s56
	v_exp_f32_e32 v116, v116
	s_nop 0
	v_cndmask_b32_e64 v115, v115, v119, s[4:5]
	v_cndmask_b32_e32 v119, 0, v203, vcc
	v_sub_f32_e32 v160, v115, v119
	v_mul_f32_e64 v119, |v121|, s82
	v_exp_f32_e32 v119, v119
	v_mul_f32_e32 v115, 0x3fb8aa3b, v120
	v_exp_f32_e32 v115, v115
	v_add_f32_e32 v116, 1.0, v116
	v_add_f32_e32 v119, 1.0, v119
	v_cmp_gt_f32_e32 vcc, s81, v119
	v_add_f32_e32 v115, 1.0, v115
	v_rcp_f32_e32 v115, v115
	v_cndmask_b32_e64 v137, 0, 32, vcc
	v_ldexp_f32 v119, v119, v137
	v_log_f32_e32 v137, v119
	v_max_f32_e32 v119, v121, v121
	v_min_f32_e32 v119, 0, v119
	v_mul_f32_e32 v115, v115, v159
	v_mul_f32_e32 v161, 0x3f317217, v137
	v_fma_f32 v161, v137, s65, -v161
	v_fmac_f32_e32 v161, 0x3377d1cf, v137
	v_fmac_f32_e32 v161, 0x3f317217, v137
	v_cmp_lt_f32_e64 s[4:5], |v137|, s56
	v_rcp_f32_e32 v116, v116
	v_sub_f32_e32 v120, 1.0, v124
	v_cndmask_b32_e64 v137, v137, v161, s[4:5]
	v_cndmask_b32_e32 v161, 0, v203, vcc
	v_sub_f32_e32 v137, v137, v161
	v_pk_add_f32 v[118:119], v[118:119], v[136:137] neg_lo:[0,1] neg_hi:[0,1]
	s_nop 0
	v_mul_f32_e32 v136, 0x3fb8aa3b, v118
	v_exp_f32_e32 v136, v136
	s_nop 0
	v_fma_f32 v136, v136, v159, v128
	v_mul_f32_e32 v159, 0x3fb8aa3b, v119
	v_cmp_gt_f32_e32 vcc, s81, v136
	v_exp_f32_e32 v159, v159
	s_nop 0
	v_cndmask_b32_e64 v137, 0, 32, vcc
	v_ldexp_f32 v136, v136, v137
	v_log_f32_e32 v136, v136
	v_fma_f32 v159, v159, v170, v129
	v_cmp_gt_f32_e64 s[4:5], s81, v159
	v_mul_f32_e32 v137, v116, v120
	v_mul_f32_e32 v116, 0x3f317217, v136
	v_cndmask_b32_e64 v161, 0, 32, s[4:5]
	v_ldexp_f32 v159, v159, v161
	v_fma_f32 v116, v136, s65, -v116
	v_log_f32_e32 v159, v159
	v_fmac_f32_e32 v116, 0x3377d1cf, v136
	v_fmac_f32_e32 v116, 0x3f317217, v136
	v_cmp_lt_f32_e64 s[6:7], |v136|, s56
	v_mul_f32_e64 v161, |v117|, s82
	v_exp_f32_e32 v161, v161
	v_cndmask_b32_e64 v116, v136, v116, s[6:7]
	v_cndmask_b32_e32 v136, 0, v203, vcc
	v_sub_f32_e32 v116, v116, v136
	v_mul_f32_e32 v136, 0x3f317217, v159
	v_fma_f32 v136, v159, s65, -v136
	v_fmac_f32_e32 v136, 0x3377d1cf, v159
	v_fmac_f32_e32 v136, 0x3f317217, v159
	v_cmp_lt_f32_e64 vcc, |v159|, s56
	s_nop 1
	v_cndmask_b32_e32 v136, v159, v136, vcc
	v_cmp_lt_f32_e32 vcc, 0, v127
	v_cndmask_b32_e64 v159, 0, v203, s[4:5]
	v_cmp_lt_f32_e64 s[4:5], 0, v126
	v_cndmask_b32_e32 v127, v133, v151, vcc
	v_add_f32_e32 v133, 1.0, v161
	v_cmp_gt_f32_e32 vcc, s81, v133
	v_cndmask_b32_e64 v126, v132, v163, s[4:5]
	v_max_f32_e32 v132, v117, v117
	v_cndmask_b32_e64 v151, 0, 32, vcc
	v_ldexp_f32 v133, v133, v151
	v_log_f32_e32 v133, v133
	v_sub_f32_e32 v136, v136, v159
	v_min_f32_e32 v159, 0, v132
	v_mul_f32_e32 v117, 0x3fb8aa3b, v117
	v_mul_f32_e32 v132, 0x3f317217, v133
	v_fma_f32 v132, v133, s65, -v132
	v_fmac_f32_e32 v132, 0x3377d1cf, v133
	v_fmac_f32_e32 v132, 0x3f317217, v133
	v_cmp_lt_f32_e64 s[4:5], |v133|, s56
	v_exp_f32_e32 v117, v117
	v_pk_mul_f32 v[126:127], v[126:127], s[68:69] op_sel_hi:[1,0]
	v_cndmask_b32_e64 v132, v133, v132, s[4:5]
	v_cndmask_b32_e32 v133, 0, v203, vcc
	v_sub_f32_e32 v161, v132, v133
	v_pk_add_f32 v[132:133], v[158:159], v[160:161] neg_lo:[0,1] neg_hi:[0,1]
	v_cmp_lt_f32_e32 vcc, 0, v129
	v_mul_f32_e32 v151, 0x3fb8aa3b, v132
	v_exp_f32_e32 v151, v151
	v_cndmask_b32_e32 v119, v119, v136, vcc
	v_cmp_lt_f32_e32 vcc, 0, v128
	s_nop 1
	v_cndmask_b32_e32 v118, v118, v116, vcc
	v_fma_f32 v116, v151, v120, v124
	v_pk_mul_f32 v[128:129], v[118:119], s[68:69] op_sel_hi:[1,0]
	v_mul_f32_e32 v119, 0x3fb8aa3b, v133
	v_cmp_gt_f32_e32 vcc, s81, v116
	v_exp_f32_e32 v119, v119
	s_nop 0
	v_cndmask_b32_e64 v120, 0, 32, vcc
	v_ldexp_f32 v116, v116, v120
	v_log_f32_e32 v116, v116
	v_sub_f32_e32 v120, 1.0, v125
	v_fma_f32 v119, v119, v120, v125
	v_cmp_gt_f32_e64 s[4:5], s81, v119
	v_mul_f32_e32 v118, 0x3f317217, v116
	v_fma_f32 v118, v116, s65, -v118
	v_cndmask_b32_e64 v136, 0, 32, s[4:5]
	v_ldexp_f32 v119, v119, v136
	v_log_f32_e32 v119, v119
	v_fmac_f32_e32 v118, 0x3377d1cf, v116
	v_fmac_f32_e32 v118, 0x3f317217, v116
	v_cmp_lt_f32_e64 s[6:7], |v116|, s56
	s_nop 1
	v_cndmask_b32_e64 v116, v116, v118, s[6:7]
	v_cndmask_b32_e32 v118, 0, v203, vcc
	v_sub_f32_e32 v116, v116, v118
	v_mul_f32_e32 v118, 0x3f317217, v119
	v_fma_f32 v118, v119, s65, -v118
	v_fmac_f32_e32 v118, 0x3377d1cf, v119
	v_fmac_f32_e32 v118, 0x3f317217, v119
	v_cmp_lt_f32_e64 vcc, |v119|, s56
	s_nop 1
	v_cndmask_b32_e32 v118, v119, v118, vcc
	v_cmp_lt_f32_e32 vcc, 0, v123
	v_cndmask_b32_e64 v119, 0, v203, s[4:5]
	v_sub_f32_e32 v118, v118, v119
	v_cndmask_b32_e32 v123, v135, v165, vcc
	v_cmp_lt_f32_e32 vcc, 0, v122
	s_nop 1
	v_cndmask_b32_e32 v122, v134, v164, vcc
	v_cmp_lt_f32_e32 vcc, 0, v125
	s_nop 1
	v_cndmask_b32_e32 v119, v133, v118, vcc
	v_mul_f32_e32 v118, 0x3fb8aa3b, v121
	v_exp_f32_e32 v121, v118
	v_cmp_lt_f32_e32 vcc, 0, v124
	s_nop 1
	v_cndmask_b32_e32 v118, v132, v116, vcc
	v_add_f32_e32 v116, 1.0, v121
	v_rcp_f32_e32 v121, v116
	v_add_f32_e32 v116, 1.0, v117
	v_rcp_f32_e32 v124, v116
	v_pk_mul_f32 v[118:119], v[118:119], s[68:69] op_sel_hi:[1,0]
	v_pk_mul_f32 v[116:117], v[122:123], s[68:69] op_sel_hi:[1,0]
	v_mul_f32_e32 v122, v121, v170
	v_mul_f32_e32 v123, v124, v120
	v_lshl_add_u64 v[120:121], v[156:157], 0, v[130:131]
	global_store_dwordx4 v[120:121], v[126:129], off
	global_store_dwordx4 v[120:121], v[116:119], off offset:16
	v_cvt_pk_bf16_f32 v114, v114, v168
	v_cvt_pk_bf16_f32 v115, v115, v122
	s_nop 1
	v_lshl_add_u64 v[118:119], v[148:149], 1, v[154:155]
	v_cvt_pk_bf16_f32 v116, v162, v169
	v_cvt_pk_bf16_f32 v117, v137, v123
	global_store_dwordx4 v[118:119], v[114:117], off offset:256
	s_and_b64 vcc, exec, s[90:91]
	s_cbranch_vccz .LBB0_427

.LBB0_445:
	v_ashrrev_i32_e32 v125, 31, v124
	s_nop 0
	v_lshlrev_b64 v[114:115], 11, v[124:125]
	s_and_b64 vcc, exec, s[0:1]
	v_lshl_add_u64 v[122:123], s[10:11], 0, v[122:123]
	v_lshl_add_u64 v[124:125], v[114:115], 2, s[12:13]
	s_cbranch_vccz .LBB0_447
	v_lshl_add_u64 v[128:129], v[148:149], 2, s[2:3]
	v_lshl_add_u64 v[114:115], s[14:15], 0, v[128:129]
	v_mov_b32_e32 v118, v206
	v_mov_b32_e32 v119, v207
	v_mov_b32_e32 v120, v208
	v_mov_b32_e32 v121, v209
	v_mov_b32_e32 v114, v210
	v_mov_b32_e32 v115, v211
	v_mov_b32_e32 v116, v212
	v_mov_b32_e32 v117, v213
	v_max_f32_e32 v127, v110, v110
	v_mul_f32_e64 v131, |v110|, s82
	v_mul_f32_e64 v133, |v106|, s82
	v_min_f32_e32 v130, 0, v127
	v_exp_f32_e32 v127, v131
	v_max_f32_e32 v134, v111, v111
	v_mul_f32_e64 v135, |v111|, s82
	v_mul_f32_e64 v136, |v107|, s82
	v_exp_f32_e32 v133, v133
	v_max_f32_e32 v132, v106, v106
	v_mul_f32_e32 v106, 0x3fb8aa3b, v106
	v_min_f32_e32 v131, 0, v134
	v_exp_f32_e32 v134, v135
	v_exp_f32_e32 v135, v136
	v_exp_f32_e32 v106, v106
	v_add_f32_e32 v127, 1.0, v127
	v_add_f32_e32 v133, 1.0, v133
	v_cmp_gt_f32_e32 vcc, s81, v127
	v_add_f32_e32 v134, 1.0, v134
	v_add_f32_e32 v137, 1.0, v135
	v_cndmask_b32_e64 v135, 0, 32, vcc
	v_cmp_gt_f32_e64 s[4:5], s81, v133
	v_add_f32_e32 v106, 1.0, v106
	v_cmp_gt_f32_e64 s[6:7], s81, v134
	v_cndmask_b32_e64 v136, 0, 32, s[4:5]
	v_ldexp_f32 v127, v127, v135
	v_rcp_f32_e32 v151, v106
	v_cndmask_b32_e64 v106, 0, 32, s[6:7]
	v_ldexp_f32 v133, v133, v136
	v_log_f32_e32 v127, v127
	v_ldexp_f32 v106, v134, v106
	v_log_f32_e32 v133, v133
	v_log_f32_e32 v106, v106
	v_mul_f32_e32 v134, 0x3f317217, v127
	v_fma_f32 v134, v127, s65, -v134
	v_mul_f32_e32 v155, 0x3f317217, v133
	v_mul_f32_e32 v156, 0x3f317217, v106
	v_fma_f32 v155, v133, s65, -v155
	v_fmac_f32_e32 v134, 0x3377d1cf, v127
	v_cndmask_b32_e32 v135, 0, v203, vcc
	v_fma_f32 v156, v106, s65, -v156
	v_fmac_f32_e32 v155, 0x3377d1cf, v133
	v_fmac_f32_e32 v134, 0x3f317217, v127
	v_cmp_lt_f32_e64 vcc, |v127|, s56
	v_mul_f32_e32 v110, 0x3fb8aa3b, v110
	v_fmac_f32_e32 v156, 0x3377d1cf, v106
	v_fmac_f32_e32 v155, 0x3f317217, v133
	v_cndmask_b32_e32 v127, v127, v134, vcc
	v_cmp_lt_f32_e64 vcc, |v133|, s56
	v_exp_f32_e32 v110, v110
	v_fmac_f32_e32 v156, 0x3f317217, v106
	v_cndmask_b32_e32 v133, v133, v155, vcc
	v_cmp_lt_f32_e64 vcc, |v106|, s56
	v_cndmask_b32_e64 v154, 0, v203, s[6:7]
	v_sub_f32_e32 v134, v127, v135
	v_cndmask_b32_e32 v106, v106, v156, vcc
	v_sub_f32_e32 v135, v106, v154
	v_pk_add_f32 v[130:131], v[130:131], v[134:135] neg_lo:[0,1] neg_hi:[0,1]
	v_add_f32_e32 v110, 1.0, v110
	v_cndmask_b32_e64 v136, 0, v203, s[4:5]
	v_mul_f32_e32 v106, 0x3fb8aa3b, v130
	v_rcp_f32_e32 v110, v110
	v_sub_f32_e32 v136, v133, v136
	v_exp_f32_e32 v133, v106
	v_mul_f32_e32 v127, 0x3fb8aa3b, v131
	v_exp_f32_e32 v127, v127
	v_min_f32_e32 v132, 0, v132
	v_mul_f32_e32 v111, 0x3fb8aa3b, v111
	v_exp_f32_e32 v111, v111
	v_sub_f32_e32 v134, 1.0, v118
	v_mul_f32_e32 v106, v110, v134
	v_fma_f32 v110, v133, v134, v118
	v_cmp_gt_f32_e64 s[4:5], s81, v110
	v_sub_f32_e32 v154, 1.0, v119
	v_fma_f32 v127, v127, v154, v119
	v_cndmask_b32_e64 v133, 0, 32, s[4:5]
	v_ldexp_f32 v110, v110, v133
	v_log_f32_e32 v110, v110
	v_cmp_gt_f32_e32 vcc, s81, v127
	v_cndmask_b32_e64 v133, 0, v203, s[4:5]
	v_sub_f32_e32 v135, 1.0, v114
	v_cndmask_b32_e64 v134, 0, 32, vcc
	v_ldexp_f32 v127, v127, v134
	v_mul_f32_e32 v134, 0x3f317217, v110
	v_fma_f32 v134, v110, s65, -v134
	v_fmac_f32_e32 v134, 0x3377d1cf, v110
	v_fmac_f32_e32 v134, 0x3f317217, v110
	v_cmp_lt_f32_e64 s[4:5], |v110|, s56
	v_log_f32_e32 v127, v127
	v_mul_f32_e32 v151, v151, v135
	v_cndmask_b32_e64 v110, v110, v134, s[4:5]
	v_cmp_gt_f32_e64 s[4:5], s81, v137
	v_sub_f32_e32 v156, v110, v133
	v_max_f32_e32 v133, v107, v107
	v_cndmask_b32_e64 v110, 0, 32, s[4:5]
	v_ldexp_f32 v110, v137, v110
	v_log_f32_e32 v110, v110
	v_min_f32_e32 v133, 0, v133
	v_mul_f32_e32 v155, 0x3f317217, v127
	v_fma_f32 v155, v127, s65, -v155
	v_mul_f32_e32 v134, 0x3f317217, v110
	v_fma_f32 v134, v110, s65, -v134
	v_fmac_f32_e32 v134, 0x3377d1cf, v110
	v_fmac_f32_e32 v134, 0x3f317217, v110
	v_cmp_lt_f32_e64 s[6:7], |v110|, s56
	v_fmac_f32_e32 v155, 0x3377d1cf, v127
	v_fmac_f32_e32 v155, 0x3f317217, v127
	v_cndmask_b32_e64 v110, v110, v134, s[6:7]
	v_cndmask_b32_e64 v134, 0, v203, s[4:5]
	v_sub_f32_e32 v137, v110, v134
	v_pk_add_f32 v[132:133], v[132:133], v[136:137] neg_lo:[0,1] neg_hi:[0,1]
	v_cmp_lt_f32_e64 s[4:5], |v127|, s56
	v_mul_f32_e32 v110, 0x3fb8aa3b, v132
	v_exp_f32_e32 v110, v110
	v_mul_f32_e32 v136, 0x3fb8aa3b, v133
	v_cndmask_b32_e64 v127, v127, v155, s[4:5]
	v_exp_f32_e32 v136, v136
	v_fma_f32 v110, v110, v135, v114
	v_cmp_gt_f32_e64 s[4:5], s81, v110
	v_mul_f32_e32 v107, 0x3fb8aa3b, v107
	v_exp_f32_e32 v107, v107
	v_cndmask_b32_e64 v134, 0, 32, s[4:5]
	v_ldexp_f32 v110, v110, v134
	v_cndmask_b32_e32 v134, 0, v203, vcc
	v_log_f32_e32 v110, v110
	v_sub_f32_e32 v127, v127, v134
	v_sub_f32_e32 v134, 1.0, v115
	v_fma_f32 v136, v136, v134, v115
	v_cmp_gt_f32_e32 vcc, s81, v136
	v_mul_f32_e32 v135, 0x3f317217, v110
	v_fma_f32 v135, v110, s65, -v135
	v_cndmask_b32_e64 v137, 0, 32, vcc
	v_ldexp_f32 v136, v136, v137
	v_log_f32_e32 v136, v136
	v_fmac_f32_e32 v135, 0x3377d1cf, v110
	v_fmac_f32_e32 v135, 0x3f317217, v110
	v_cmp_lt_f32_e64 s[6:7], |v110|, s56
	v_add_f32_e32 v107, 1.0, v107
	v_rcp_f32_e32 v107, v107
	v_cndmask_b32_e64 v110, v110, v135, s[6:7]
	v_cndmask_b32_e64 v135, 0, v203, s[4:5]
	v_sub_f32_e32 v157, v110, v135
	v_mul_f32_e32 v110, 0x3f317217, v136
	v_fma_f32 v110, v136, s65, -v110
	v_fmac_f32_e32 v110, 0x3377d1cf, v136
	v_fmac_f32_e32 v110, 0x3f317217, v136
	v_cmp_lt_f32_e64 s[4:5], |v136|, s56
	v_cndmask_b32_e32 v135, 0, v203, vcc
	v_mul_f32_e32 v160, v107, v134
	v_cndmask_b32_e64 v110, v136, v110, s[4:5]
	v_sub_f32_e32 v158, v110, v135
	v_add_f32_e32 v110, 1.0, v111
	v_mul_f32_e64 v111, |v112|, s82
	v_rcp_f32_e32 v110, v110
	v_exp_f32_e32 v111, v111
	v_max_f32_e32 v107, v112, v112
	v_mul_f32_e64 v134, |v108|, s82
	v_mul_f32_e32 v159, v110, v154
	v_add_f32_e32 v110, 1.0, v111
	v_cmp_gt_f32_e32 vcc, s81, v110
	v_exp_f32_e32 v135, v134
	v_sub_f32_e32 v137, 1.0, v120
	v_cndmask_b32_e64 v111, 0, 32, vcc
	v_ldexp_f32 v110, v110, v111
	v_log_f32_e32 v111, v110
	v_min_f32_e32 v110, 0, v107
	v_sub_f32_e32 v161, 1.0, v121
	v_mul_f32_e32 v107, 0x3f317217, v111
	v_fma_f32 v107, v111, s65, -v107
	v_fmac_f32_e32 v107, 0x3377d1cf, v111
	v_fmac_f32_e32 v107, 0x3f317217, v111
	v_cmp_lt_f32_e64 s[4:5], |v111|, s56
	s_nop 1
	v_cndmask_b32_e64 v107, v111, v107, s[4:5]
	v_cndmask_b32_e32 v111, 0, v203, vcc
	v_sub_f32_e32 v134, v107, v111
	v_add_f32_e32 v107, 1.0, v135
	v_cmp_gt_f32_e32 vcc, s81, v107
	s_nop 1
	v_cndmask_b32_e64 v111, 0, 32, vcc
	v_ldexp_f32 v107, v107, v111
	v_log_f32_e32 v107, v107
	v_max_f32_e32 v111, v108, v108
	v_min_f32_e32 v136, 0, v111
	v_mul_f32_e32 v108, 0x3fb8aa3b, v108
	v_mul_f32_e32 v111, 0x3f317217, v107
	v_fma_f32 v111, v107, s65, -v111
	v_fmac_f32_e32 v111, 0x3377d1cf, v107
	v_fmac_f32_e32 v111, 0x3f317217, v107
	v_cmp_lt_f32_e64 s[4:5], |v107|, s56
	v_exp_f32_e32 v108, v108
	s_nop 0
	v_cndmask_b32_e64 v107, v107, v111, s[4:5]
	v_cndmask_b32_e32 v111, 0, v203, vcc
	v_sub_f32_e32 v154, v107, v111
	v_mul_f32_e64 v111, |v113|, s82
	v_exp_f32_e32 v111, v111
	v_mul_f32_e32 v107, 0x3fb8aa3b, v112
	v_exp_f32_e32 v107, v107
	v_add_f32_e32 v108, 1.0, v108
	v_add_f32_e32 v111, 1.0, v111
	v_cmp_gt_f32_e32 vcc, s81, v111
	v_add_f32_e32 v107, 1.0, v107
	v_rcp_f32_e32 v107, v107
	v_cndmask_b32_e64 v135, 0, 32, vcc
	v_ldexp_f32 v111, v111, v135
	v_log_f32_e32 v135, v111
	v_max_f32_e32 v111, v113, v113
	v_min_f32_e32 v111, 0, v111
	v_mul_f32_e32 v107, v107, v137
	v_mul_f32_e32 v155, 0x3f317217, v135
	v_fma_f32 v155, v135, s65, -v155
	v_fmac_f32_e32 v155, 0x3377d1cf, v135
	v_fmac_f32_e32 v155, 0x3f317217, v135
	v_cmp_lt_f32_e64 s[4:5], |v135|, s56
	v_rcp_f32_e32 v108, v108
	v_sub_f32_e32 v112, 1.0, v116
	v_cndmask_b32_e64 v135, v135, v155, s[4:5]
	v_cndmask_b32_e32 v155, 0, v203, vcc
	v_sub_f32_e32 v135, v135, v155
	v_pk_add_f32 v[110:111], v[110:111], v[134:135] neg_lo:[0,1] neg_hi:[0,1]
	s_nop 0
	v_mul_f32_e32 v134, 0x3fb8aa3b, v110
	v_exp_f32_e32 v134, v134
	s_nop 0
	v_fma_f32 v134, v134, v137, v120
	v_mul_f32_e32 v137, 0x3fb8aa3b, v111
	v_cmp_gt_f32_e32 vcc, s81, v134
	v_exp_f32_e32 v137, v137
	s_nop 0
	v_cndmask_b32_e64 v135, 0, 32, vcc
	v_ldexp_f32 v134, v134, v135
	v_log_f32_e32 v134, v134
	v_fma_f32 v137, v137, v161, v121
	v_cmp_gt_f32_e64 s[4:5], s81, v137
	v_mul_f32_e32 v135, v108, v112
	v_mul_f32_e32 v108, 0x3f317217, v134
	v_cndmask_b32_e64 v155, 0, 32, s[4:5]
	v_ldexp_f32 v137, v137, v155
	v_fma_f32 v108, v134, s65, -v108
	v_log_f32_e32 v137, v137
	v_fmac_f32_e32 v108, 0x3377d1cf, v134
	v_fmac_f32_e32 v108, 0x3f317217, v134
	v_cmp_lt_f32_e64 s[6:7], |v134|, s56
	v_mul_f32_e64 v155, |v109|, s82
	v_exp_f32_e32 v155, v155
	v_cndmask_b32_e64 v108, v134, v108, s[6:7]
	v_cndmask_b32_e32 v134, 0, v203, vcc
	v_sub_f32_e32 v108, v108, v134
	v_mul_f32_e32 v134, 0x3f317217, v137
	v_fma_f32 v134, v137, s65, -v134
	v_fmac_f32_e32 v134, 0x3377d1cf, v137
	v_fmac_f32_e32 v134, 0x3f317217, v137
	v_cmp_lt_f32_e64 vcc, |v137|, s56
	s_nop 1
	v_cndmask_b32_e32 v134, v137, v134, vcc
	v_cmp_lt_f32_e32 vcc, 0, v119
	v_cndmask_b32_e64 v137, 0, v203, s[4:5]
	v_cmp_lt_f32_e64 s[4:5], 0, v118
	v_cndmask_b32_e32 v119, v131, v127, vcc
	v_add_f32_e32 v127, 1.0, v155
	v_cmp_gt_f32_e32 vcc, s81, v127
	v_cndmask_b32_e64 v118, v130, v156, s[4:5]
	v_max_f32_e32 v130, v109, v109
	v_cndmask_b32_e64 v131, 0, 32, vcc
	v_ldexp_f32 v127, v127, v131
	v_log_f32_e32 v127, v127
	v_sub_f32_e32 v134, v134, v137
	v_min_f32_e32 v137, 0, v130
	v_mul_f32_e32 v109, 0x3fb8aa3b, v109
	v_mul_f32_e32 v130, 0x3f317217, v127
	v_fma_f32 v130, v127, s65, -v130
	v_fmac_f32_e32 v130, 0x3377d1cf, v127
	v_fmac_f32_e32 v130, 0x3f317217, v127
	v_cmp_lt_f32_e64 s[4:5], |v127|, s56
	v_exp_f32_e32 v109, v109
	v_pk_mul_f32 v[118:119], v[118:119], s[68:69] op_sel_hi:[1,0]
	v_cndmask_b32_e64 v127, v127, v130, s[4:5]
	v_cndmask_b32_e32 v130, 0, v203, vcc
	v_sub_f32_e32 v155, v127, v130
	v_pk_add_f32 v[130:131], v[136:137], v[154:155] neg_lo:[0,1] neg_hi:[0,1]
	v_cmp_lt_f32_e32 vcc, 0, v121
	v_mul_f32_e32 v127, 0x3fb8aa3b, v130
	v_exp_f32_e32 v127, v127
	v_cndmask_b32_e32 v111, v111, v134, vcc
	v_cmp_lt_f32_e32 vcc, 0, v120
	s_nop 1
	v_cndmask_b32_e32 v110, v110, v108, vcc
	v_fma_f32 v108, v127, v112, v116
	v_pk_mul_f32 v[120:121], v[110:111], s[68:69] op_sel_hi:[1,0]
	v_mul_f32_e32 v111, 0x3fb8aa3b, v131
	v_cmp_gt_f32_e32 vcc, s81, v108
	v_exp_f32_e32 v111, v111
	s_nop 0
	v_cndmask_b32_e64 v112, 0, 32, vcc
	v_ldexp_f32 v108, v108, v112
	v_log_f32_e32 v108, v108
	v_sub_f32_e32 v112, 1.0, v117
	v_fma_f32 v111, v111, v112, v117
	v_cmp_gt_f32_e64 s[4:5], s81, v111
	v_mul_f32_e32 v110, 0x3f317217, v108
	v_fma_f32 v110, v108, s65, -v110
	v_cndmask_b32_e64 v127, 0, 32, s[4:5]
	v_ldexp_f32 v111, v111, v127
	v_log_f32_e32 v111, v111
	v_fmac_f32_e32 v110, 0x3377d1cf, v108
	v_fmac_f32_e32 v110, 0x3f317217, v108
	v_cmp_lt_f32_e64 s[6:7], |v108|, s56
	s_nop 1
	v_cndmask_b32_e64 v108, v108, v110, s[6:7]
	v_cndmask_b32_e32 v110, 0, v203, vcc
	v_sub_f32_e32 v108, v108, v110
	v_mul_f32_e32 v110, 0x3f317217, v111
	v_fma_f32 v110, v111, s65, -v110
	v_fmac_f32_e32 v110, 0x3377d1cf, v111
	v_fmac_f32_e32 v110, 0x3f317217, v111
	v_cmp_lt_f32_e64 vcc, |v111|, s56
	s_nop 1
	v_cndmask_b32_e32 v110, v111, v110, vcc
	v_cmp_lt_f32_e32 vcc, 0, v115
	v_cndmask_b32_e64 v111, 0, v203, s[4:5]
	v_sub_f32_e32 v110, v110, v111
	v_cndmask_b32_e32 v115, v133, v158, vcc
	v_cmp_lt_f32_e32 vcc, 0, v114
	s_nop 1
	v_cndmask_b32_e32 v114, v132, v157, vcc
	v_cmp_lt_f32_e32 vcc, 0, v117
	s_nop 1
	v_cndmask_b32_e32 v111, v131, v110, vcc
	v_mul_f32_e32 v110, 0x3fb8aa3b, v113
	v_exp_f32_e32 v113, v110
	v_cmp_lt_f32_e32 vcc, 0, v116
	s_nop 1
	v_cndmask_b32_e32 v110, v130, v108, vcc
	v_add_f32_e32 v108, 1.0, v113
	v_rcp_f32_e32 v113, v108
	v_add_f32_e32 v108, 1.0, v109
	v_rcp_f32_e32 v116, v108
	v_pk_mul_f32 v[110:111], v[110:111], s[68:69] op_sel_hi:[1,0]
	v_pk_mul_f32 v[108:109], v[114:115], s[68:69] op_sel_hi:[1,0]
	v_mul_f32_e32 v114, v113, v161
	v_mul_f32_e32 v115, v116, v112
	v_lshl_add_u64 v[112:113], v[124:125], 0, v[128:129]
	global_store_dwordx4 v[112:113], v[118:121], off
	global_store_dwordx4 v[112:113], v[108:111], off offset:16
	v_cvt_pk_bf16_f32 v106, v106, v159
	v_cvt_pk_bf16_f32 v107, v107, v114
	s_nop 1
	v_lshl_add_u64 v[110:111], v[148:149], 1, v[122:123]
	v_cvt_pk_bf16_f32 v108, v151, v160
	v_cvt_pk_bf16_f32 v109, v135, v115
	global_store_dwordx4 v[110:111], v[106:109], off

.LBB0_458:
	v_lshl_add_u64 v[114:115], v[148:149], 2, s[26:27]
	v_lshl_add_u64 v[106:107], s[14:15], 0, v[114:115]
	v_mov_b32_e32 v110, v214
	v_mov_b32_e32 v111, v215
	v_mov_b32_e32 v112, v216
	v_mov_b32_e32 v113, v217
	v_mov_b32_e32 v106, v218
	v_mov_b32_e32 v107, v219
	v_mov_b32_e32 v108, v220
	v_mov_b32_e32 v109, v221
	v_mul_f32_e64 v117, |v102|, s82
	v_mul_f32_e64 v119, |v98|, s82
	v_max_f32_e32 v120, v103, v103
	v_mul_f32_e64 v121, |v103|, s82
	v_exp_f32_e32 v127, v117
	v_max_f32_e32 v118, v98, v98
	v_mul_f32_e32 v98, 0x3fb8aa3b, v98
	v_mul_f32_e64 v126, |v99|, s82
	v_exp_f32_e32 v119, v119
	v_min_f32_e32 v117, 0, v120
	v_exp_f32_e32 v120, v121
	v_exp_f32_e32 v98, v98
	v_exp_f32_e32 v121, v126
	v_add_f32_e32 v126, 1.0, v127
	v_add_f32_e32 v119, 1.0, v119
	v_add_f32_e32 v120, 1.0, v120
	v_cmp_gt_f32_e32 vcc, s81, v126
	v_add_f32_e32 v98, 1.0, v98
	v_add_f32_e32 v127, 1.0, v121
	v_cndmask_b32_e64 v121, 0, 32, vcc
	v_cmp_gt_f32_e64 s[4:5], s81, v119
	v_cmp_gt_f32_e64 s[6:7], s81, v120
	v_rcp_f32_e32 v129, v98
	v_cndmask_b32_e64 v128, 0, 32, s[4:5]
	v_cndmask_b32_e64 v98, 0, 32, s[6:7]
	v_ldexp_f32 v121, v126, v121
	v_ldexp_f32 v119, v119, v128
	v_ldexp_f32 v98, v120, v98
	v_log_f32_e32 v120, v121
	v_log_f32_e32 v119, v119
	v_log_f32_e32 v98, v98
	v_cndmask_b32_e32 v126, 0, v203, vcc
	v_mul_f32_e32 v130, 0x3f317217, v120
	v_mul_f32_e32 v131, 0x3f317217, v119
	v_fma_f32 v130, v120, s65, -v130
	v_mul_f32_e32 v132, 0x3f317217, v98
	v_fma_f32 v131, v119, s65, -v131
	v_fmac_f32_e32 v130, 0x3377d1cf, v120
	v_fma_f32 v132, v98, s65, -v132
	v_fmac_f32_e32 v131, 0x3377d1cf, v119
	v_fmac_f32_e32 v130, 0x3f317217, v120
	v_cmp_lt_f32_e64 vcc, |v120|, s56
	v_max_f32_e32 v116, v102, v102
	v_mul_f32_e32 v102, 0x3fb8aa3b, v102
	v_fmac_f32_e32 v132, 0x3377d1cf, v98
	v_fmac_f32_e32 v131, 0x3f317217, v119
	v_cndmask_b32_e32 v120, v120, v130, vcc
	v_cmp_lt_f32_e64 vcc, |v119|, s56
	v_exp_f32_e32 v102, v102
	v_fmac_f32_e32 v132, 0x3f317217, v98
	v_cndmask_b32_e32 v119, v119, v131, vcc
	v_cmp_lt_f32_e64 vcc, |v98|, s56
	v_cndmask_b32_e64 v121, 0, v203, s[6:7]
	v_min_f32_e32 v116, 0, v116
	v_cndmask_b32_e32 v98, v98, v132, vcc
	v_sub_f32_e32 v120, v120, v126
	v_sub_f32_e32 v121, v98, v121
	v_pk_add_f32 v[116:117], v[116:117], v[120:121] neg_lo:[0,1] neg_hi:[0,1]
	v_add_f32_e32 v102, 1.0, v102
	v_mul_f32_e32 v98, 0x3fb8aa3b, v116
	v_rcp_f32_e32 v102, v102
	v_exp_f32_e32 v120, v98
	v_cndmask_b32_e64 v128, 0, v203, s[4:5]
	v_sub_f32_e32 v126, v119, v128
	v_mul_f32_e32 v119, 0x3fb8aa3b, v117
	v_exp_f32_e32 v119, v119
	v_min_f32_e32 v118, 0, v118
	v_mul_f32_e32 v103, 0x3fb8aa3b, v103
	v_exp_f32_e32 v103, v103
	v_sub_f32_e32 v121, 1.0, v110
	v_mul_f32_e32 v98, v102, v121
	v_fma_f32 v102, v120, v121, v110
	v_cmp_gt_f32_e64 s[4:5], s81, v102
	v_sub_f32_e32 v130, 1.0, v111
	v_fma_f32 v119, v119, v130, v111
	v_cndmask_b32_e64 v120, 0, 32, s[4:5]
	v_ldexp_f32 v102, v102, v120
	v_log_f32_e32 v102, v102
	v_cmp_gt_f32_e32 vcc, s81, v119
	v_sub_f32_e32 v128, 1.0, v106
	v_mul_f32_e32 v131, v129, v128
	v_cndmask_b32_e64 v121, 0, 32, vcc
	v_ldexp_f32 v119, v119, v121
	v_mul_f32_e32 v121, 0x3f317217, v102
	v_fma_f32 v121, v102, s65, -v121
	v_fmac_f32_e32 v121, 0x3377d1cf, v102
	v_log_f32_e32 v120, v119
	v_cndmask_b32_e64 v119, 0, v203, s[4:5]
	v_fmac_f32_e32 v121, 0x3f317217, v102
	v_cmp_lt_f32_e64 s[4:5], |v102|, s56
	v_mul_f32_e32 v129, 0x3f317217, v120
	v_fma_f32 v129, v120, s65, -v129
	v_cndmask_b32_e64 v102, v102, v121, s[4:5]
	v_cmp_gt_f32_e64 s[4:5], s81, v127
	v_sub_f32_e32 v132, v102, v119
	v_max_f32_e32 v119, v99, v99
	v_cndmask_b32_e64 v102, 0, 32, s[4:5]
	v_ldexp_f32 v102, v127, v102
	v_log_f32_e32 v102, v102
	v_min_f32_e32 v119, 0, v119
	v_fmac_f32_e32 v129, 0x3377d1cf, v120
	v_fmac_f32_e32 v129, 0x3f317217, v120
	v_mul_f32_e32 v121, 0x3f317217, v102
	v_fma_f32 v121, v102, s65, -v121
	v_fmac_f32_e32 v121, 0x3377d1cf, v102
	v_fmac_f32_e32 v121, 0x3f317217, v102
	v_cmp_lt_f32_e64 s[6:7], |v102|, s56
	v_mul_f32_e32 v99, 0x3fb8aa3b, v99
	v_exp_f32_e32 v99, v99
	v_cndmask_b32_e64 v102, v102, v121, s[6:7]
	v_cndmask_b32_e64 v121, 0, v203, s[4:5]
	v_sub_f32_e32 v127, v102, v121
	v_pk_add_f32 v[118:119], v[118:119], v[126:127] neg_lo:[0,1] neg_hi:[0,1]
	v_cmp_lt_f32_e64 s[4:5], |v120|, s56
	v_mul_f32_e32 v102, 0x3fb8aa3b, v118
	v_exp_f32_e32 v102, v102
	v_mul_f32_e32 v126, 0x3fb8aa3b, v119
	v_cndmask_b32_e64 v120, v120, v129, s[4:5]
	v_exp_f32_e32 v126, v126
	v_fma_f32 v102, v102, v128, v106
	v_cmp_gt_f32_e64 s[4:5], s81, v102
	v_add_f32_e32 v99, 1.0, v99
	v_rcp_f32_e32 v99, v99
	v_cndmask_b32_e64 v121, 0, 32, s[4:5]
	v_ldexp_f32 v102, v102, v121
	v_cndmask_b32_e32 v121, 0, v203, vcc
	v_log_f32_e32 v102, v102
	v_sub_f32_e32 v127, v120, v121
	v_sub_f32_e32 v120, 1.0, v107
	v_fma_f32 v126, v126, v120, v107
	v_cmp_gt_f32_e32 vcc, s81, v126
	v_mul_f32_e32 v121, 0x3f317217, v102
	v_fma_f32 v121, v102, s65, -v121
	v_cndmask_b32_e64 v128, 0, 32, vcc
	v_ldexp_f32 v126, v126, v128
	v_log_f32_e32 v126, v126
	v_fmac_f32_e32 v121, 0x3377d1cf, v102
	v_fmac_f32_e32 v121, 0x3f317217, v102
	v_cmp_lt_f32_e64 s[6:7], |v102|, s56
	v_mul_f32_e32 v135, v99, v120
	v_max_f32_e32 v99, v104, v104
	v_cndmask_b32_e64 v102, v102, v121, s[6:7]
	v_cndmask_b32_e64 v121, 0, v203, s[4:5]
	v_sub_f32_e32 v133, v102, v121
	v_mul_f32_e32 v102, 0x3f317217, v126
	v_fma_f32 v102, v126, s65, -v102
	v_fmac_f32_e32 v102, 0x3377d1cf, v126
	v_fmac_f32_e32 v102, 0x3f317217, v126
	v_cmp_lt_f32_e64 s[4:5], |v126|, s56
	v_cndmask_b32_e32 v121, 0, v203, vcc
	v_mul_f32_e64 v120, |v100|, s82
	v_cndmask_b32_e64 v102, v126, v102, s[4:5]
	v_sub_f32_e32 v134, v102, v121
	v_add_f32_e32 v102, 1.0, v103
	v_mul_f32_e64 v103, |v104|, s82
	v_rcp_f32_e32 v102, v102
	v_exp_f32_e32 v103, v103
	v_exp_f32_e32 v121, v120
	v_sub_f32_e32 v129, 1.0, v112
	v_mul_f32_e32 v130, v102, v130
	v_add_f32_e32 v102, 1.0, v103
	v_cmp_gt_f32_e32 vcc, s81, v102
	s_nop 1
	v_cndmask_b32_e64 v103, 0, 32, vcc
	v_ldexp_f32 v102, v102, v103
	v_log_f32_e32 v103, v102
	v_min_f32_e32 v102, 0, v99
	v_mul_f32_e32 v99, 0x3f317217, v103
	v_fma_f32 v99, v103, s65, -v99
	v_fmac_f32_e32 v99, 0x3377d1cf, v103
	v_fmac_f32_e32 v99, 0x3f317217, v103
	v_cmp_lt_f32_e64 s[4:5], |v103|, s56
	s_nop 1
	v_cndmask_b32_e64 v99, v103, v99, s[4:5]
	v_cndmask_b32_e32 v103, 0, v203, vcc
	v_sub_f32_e32 v120, v99, v103
	v_add_f32_e32 v99, 1.0, v121
	v_cmp_gt_f32_e32 vcc, s81, v99
	s_nop 1
	v_cndmask_b32_e64 v103, 0, 32, vcc
	v_ldexp_f32 v99, v99, v103
	v_log_f32_e32 v99, v99
	v_max_f32_e32 v103, v100, v100
	v_min_f32_e32 v126, 0, v103
	v_mul_f32_e32 v100, 0x3fb8aa3b, v100
	v_mul_f32_e32 v103, 0x3f317217, v99
	v_fma_f32 v103, v99, s65, -v103
	v_fmac_f32_e32 v103, 0x3377d1cf, v99
	v_fmac_f32_e32 v103, 0x3f317217, v99
	v_cmp_lt_f32_e64 s[4:5], |v99|, s56
	v_exp_f32_e32 v100, v100
	s_nop 0
	v_cndmask_b32_e64 v99, v99, v103, s[4:5]
	v_cndmask_b32_e32 v103, 0, v203, vcc
	v_sub_f32_e32 v128, v99, v103
	v_mul_f32_e64 v103, |v105|, s82
	v_exp_f32_e32 v103, v103
	v_mul_f32_e32 v99, 0x3fb8aa3b, v104
	v_exp_f32_e32 v99, v99
	v_add_f32_e32 v100, 1.0, v100
	v_add_f32_e32 v103, 1.0, v103
	v_cmp_gt_f32_e32 vcc, s81, v103
	v_add_f32_e32 v99, 1.0, v99
	v_rcp_f32_e32 v99, v99
	v_cndmask_b32_e64 v121, 0, 32, vcc
	v_ldexp_f32 v103, v103, v121
	v_log_f32_e32 v121, v103
	v_max_f32_e32 v103, v105, v105
	v_min_f32_e32 v103, 0, v103
	v_mul_f32_e32 v99, v99, v129
	v_mul_f32_e32 v136, 0x3f317217, v121
	v_fma_f32 v136, v121, s65, -v136
	v_fmac_f32_e32 v136, 0x3377d1cf, v121
	v_fmac_f32_e32 v136, 0x3f317217, v121
	v_cmp_lt_f32_e64 s[4:5], |v121|, s56
	v_rcp_f32_e32 v100, v100
	v_sub_f32_e32 v104, 1.0, v108
	v_cndmask_b32_e64 v121, v121, v136, s[4:5]
	v_cndmask_b32_e32 v136, 0, v203, vcc
	v_sub_f32_e32 v121, v121, v136
	v_pk_add_f32 v[102:103], v[102:103], v[120:121] neg_lo:[0,1] neg_hi:[0,1]
	v_sub_f32_e32 v136, 1.0, v113
	v_mul_f32_e32 v120, 0x3fb8aa3b, v102
	v_exp_f32_e32 v120, v120
	s_nop 0
	v_fma_f32 v120, v120, v129, v112
	v_mul_f32_e32 v129, 0x3fb8aa3b, v103
	v_cmp_gt_f32_e32 vcc, s81, v120
	v_exp_f32_e32 v129, v129
	s_nop 0
	v_cndmask_b32_e64 v121, 0, 32, vcc
	v_ldexp_f32 v120, v120, v121
	v_log_f32_e32 v120, v120
	v_fma_f32 v129, v129, v136, v113
	v_cmp_gt_f32_e64 s[4:5], s81, v129
	v_mul_f32_e32 v121, v100, v104
	v_mul_f32_e32 v100, 0x3f317217, v120
	v_cndmask_b32_e64 v137, 0, 32, s[4:5]
	v_ldexp_f32 v129, v129, v137
	v_fma_f32 v100, v120, s65, -v100
	v_log_f32_e32 v129, v129
	v_fmac_f32_e32 v100, 0x3377d1cf, v120
	v_fmac_f32_e32 v100, 0x3f317217, v120
	v_cmp_lt_f32_e64 s[6:7], |v120|, s56
	v_mul_f32_e64 v137, |v101|, s82
	v_exp_f32_e32 v137, v137
	v_cndmask_b32_e64 v100, v120, v100, s[6:7]
	v_cndmask_b32_e32 v120, 0, v203, vcc
	v_sub_f32_e32 v100, v100, v120
	v_mul_f32_e32 v120, 0x3f317217, v129
	v_fma_f32 v120, v129, s65, -v120
	v_fmac_f32_e32 v120, 0x3377d1cf, v129
	v_fmac_f32_e32 v120, 0x3f317217, v129
	v_cmp_lt_f32_e64 vcc, |v129|, s56
	s_nop 1
	v_cndmask_b32_e32 v120, v129, v120, vcc
	v_cmp_lt_f32_e32 vcc, 0, v111
	v_cndmask_b32_e64 v129, 0, v203, s[4:5]
	v_cmp_lt_f32_e64 s[4:5], 0, v110
	v_cndmask_b32_e32 v111, v117, v127, vcc
	v_add_f32_e32 v117, 1.0, v137
	v_cmp_gt_f32_e32 vcc, s81, v117
	v_cndmask_b32_e64 v110, v116, v132, s[4:5]
	v_max_f32_e32 v116, v101, v101
	v_cndmask_b32_e64 v127, 0, 32, vcc
	v_ldexp_f32 v117, v117, v127
	v_log_f32_e32 v117, v117
	v_min_f32_e32 v127, 0, v116
	v_sub_f32_e32 v120, v120, v129
	v_mul_f32_e32 v101, 0x3fb8aa3b, v101
	v_mul_f32_e32 v116, 0x3f317217, v117
	v_fma_f32 v116, v117, s65, -v116
	v_fmac_f32_e32 v116, 0x3377d1cf, v117
	v_fmac_f32_e32 v116, 0x3f317217, v117
	v_cmp_lt_f32_e64 s[4:5], |v117|, s56
	v_exp_f32_e32 v101, v101
	v_pk_mul_f32 v[110:111], v[110:111], s[68:69] op_sel_hi:[1,0]
	v_cndmask_b32_e64 v116, v117, v116, s[4:5]
	v_cndmask_b32_e32 v117, 0, v203, vcc
	v_sub_f32_e32 v129, v116, v117
	v_pk_add_f32 v[116:117], v[126:127], v[128:129] neg_lo:[0,1] neg_hi:[0,1]
	v_cmp_lt_f32_e32 vcc, 0, v113
	v_mul_f32_e32 v126, 0x3fb8aa3b, v116
	v_exp_f32_e32 v126, v126
	v_cndmask_b32_e32 v103, v103, v120, vcc
	v_cmp_lt_f32_e32 vcc, 0, v112
	s_nop 1
	v_cndmask_b32_e32 v102, v102, v100, vcc
	v_fma_f32 v100, v126, v104, v108
	v_pk_mul_f32 v[112:113], v[102:103], s[68:69] op_sel_hi:[1,0]
	v_mul_f32_e32 v103, 0x3fb8aa3b, v117
	v_cmp_gt_f32_e32 vcc, s81, v100
	v_exp_f32_e32 v103, v103
	s_nop 0
	v_cndmask_b32_e64 v104, 0, 32, vcc
	v_ldexp_f32 v100, v100, v104
	v_log_f32_e32 v100, v100
	v_sub_f32_e32 v104, 1.0, v109
	v_fma_f32 v103, v103, v104, v109
	v_cmp_gt_f32_e64 s[4:5], s81, v103
	v_mul_f32_e32 v102, 0x3f317217, v100
	v_fma_f32 v102, v100, s65, -v102
	v_cndmask_b32_e64 v120, 0, 32, s[4:5]
	v_ldexp_f32 v103, v103, v120
	v_log_f32_e32 v103, v103
	v_fmac_f32_e32 v102, 0x3377d1cf, v100
	v_fmac_f32_e32 v102, 0x3f317217, v100
	v_cmp_lt_f32_e64 s[6:7], |v100|, s56
	s_nop 1
	v_cndmask_b32_e64 v100, v100, v102, s[6:7]
	v_cndmask_b32_e32 v102, 0, v203, vcc
	v_sub_f32_e32 v100, v100, v102
	v_mul_f32_e32 v102, 0x3f317217, v103
	v_fma_f32 v102, v103, s65, -v102
	v_fmac_f32_e32 v102, 0x3377d1cf, v103
	v_fmac_f32_e32 v102, 0x3f317217, v103
	v_cmp_lt_f32_e64 vcc, |v103|, s56
	s_nop 1
	v_cndmask_b32_e32 v102, v103, v102, vcc
	v_cmp_lt_f32_e32 vcc, 0, v107
	v_cndmask_b32_e64 v103, 0, v203, s[4:5]
	v_sub_f32_e32 v102, v102, v103
	v_cndmask_b32_e32 v107, v119, v134, vcc
	v_cmp_lt_f32_e32 vcc, 0, v106
	s_nop 1
	v_cndmask_b32_e32 v106, v118, v133, vcc
	v_cmp_lt_f32_e32 vcc, 0, v109
	s_nop 1
	v_cndmask_b32_e32 v103, v117, v102, vcc
	v_mul_f32_e32 v102, 0x3fb8aa3b, v105
	v_exp_f32_e32 v105, v102
	v_cmp_lt_f32_e32 vcc, 0, v108
	s_nop 1
	v_cndmask_b32_e32 v102, v116, v100, vcc
	v_add_f32_e32 v100, 1.0, v105
	v_rcp_f32_e32 v105, v100
	v_add_f32_e32 v100, 1.0, v101
	v_rcp_f32_e32 v108, v100
	v_pk_mul_f32 v[102:103], v[102:103], s[68:69] op_sel_hi:[1,0]
	v_pk_mul_f32 v[100:101], v[106:107], s[68:69] op_sel_hi:[1,0]
	v_mul_f32_e32 v106, v105, v136
	v_mul_f32_e32 v107, v108, v104
	v_lshl_add_u64 v[104:105], v[124:125], 0, v[114:115]
	global_store_dwordx4 v[104:105], v[110:113], off
	global_store_dwordx4 v[104:105], v[100:103], off offset:16
	v_cvt_pk_bf16_f32 v98, v98, v130
	v_cvt_pk_bf16_f32 v99, v99, v106
	s_nop 1
	v_lshl_add_u64 v[102:103], v[148:149], 1, v[122:123]
	v_cvt_pk_bf16_f32 v100, v131, v135
	v_cvt_pk_bf16_f32 v101, v121, v107
	global_store_dwordx4 v[102:103], v[98:101], off offset:256
	s_and_b64 vcc, exec, s[90:91]
	s_cbranch_vccz .LBB0_450

.LBB0_468:
	v_ashrrev_i32_e32 v109, 31, v108
	s_nop 0
	v_lshlrev_b64 v[98:99], 11, v[108:109]
	s_and_b64 vcc, exec, s[0:1]
	v_lshl_add_u64 v[106:107], s[10:11], 0, v[106:107]
	v_lshl_add_u64 v[108:109], v[98:99], 2, s[12:13]
	s_cbranch_vccz .LBB0_470
	v_lshl_add_u64 v[112:113], v[148:149], 2, s[2:3]
	v_lshl_add_u64 v[98:99], s[14:15], 0, v[112:113]
	v_mov_b32_e32 v102, v206
	v_mov_b32_e32 v103, v207
	v_mov_b32_e32 v104, v208
	v_mov_b32_e32 v105, v209
	v_mov_b32_e32 v98, v210
	v_mov_b32_e32 v99, v211
	v_mov_b32_e32 v100, v212
	v_mov_b32_e32 v101, v213
	v_max_f32_e32 v111, v94, v94
	v_mul_f32_e64 v115, |v94|, s82
	v_mul_f32_e64 v117, |v90|, s82
	v_min_f32_e32 v114, 0, v111
	v_exp_f32_e32 v111, v115
	v_max_f32_e32 v118, v95, v95
	v_mul_f32_e64 v119, |v95|, s82
	v_mul_f32_e64 v120, |v91|, s82
	v_exp_f32_e32 v117, v117
	v_max_f32_e32 v116, v90, v90
	v_mul_f32_e32 v90, 0x3fb8aa3b, v90
	v_min_f32_e32 v115, 0, v118
	v_exp_f32_e32 v118, v119
	v_exp_f32_e32 v119, v120
	v_exp_f32_e32 v90, v90
	v_add_f32_e32 v111, 1.0, v111
	v_add_f32_e32 v117, 1.0, v117
	v_cmp_gt_f32_e32 vcc, s81, v111
	v_add_f32_e32 v118, 1.0, v118
	v_add_f32_e32 v121, 1.0, v119
	v_cndmask_b32_e64 v119, 0, 32, vcc
	v_cmp_gt_f32_e64 s[4:5], s81, v117
	v_add_f32_e32 v90, 1.0, v90
	v_cmp_gt_f32_e64 s[6:7], s81, v118
	v_cndmask_b32_e64 v120, 0, 32, s[4:5]
	v_ldexp_f32 v111, v111, v119
	v_rcp_f32_e32 v122, v90
	v_cndmask_b32_e64 v90, 0, 32, s[6:7]
	v_ldexp_f32 v117, v117, v120
	v_log_f32_e32 v111, v111
	v_ldexp_f32 v90, v118, v90
	v_log_f32_e32 v117, v117
	v_log_f32_e32 v90, v90
	v_mul_f32_e32 v118, 0x3f317217, v111
	v_fma_f32 v118, v111, s65, -v118
	v_mul_f32_e32 v124, 0x3f317217, v117
	v_mul_f32_e32 v125, 0x3f317217, v90
	v_fma_f32 v124, v117, s65, -v124
	v_fmac_f32_e32 v118, 0x3377d1cf, v111
	v_cndmask_b32_e32 v119, 0, v203, vcc
	v_fma_f32 v125, v90, s65, -v125
	v_fmac_f32_e32 v124, 0x3377d1cf, v117
	v_fmac_f32_e32 v118, 0x3f317217, v111
	v_cmp_lt_f32_e64 vcc, |v111|, s56
	v_mul_f32_e32 v94, 0x3fb8aa3b, v94
	v_fmac_f32_e32 v125, 0x3377d1cf, v90
	v_fmac_f32_e32 v124, 0x3f317217, v117
	v_cndmask_b32_e32 v111, v111, v118, vcc
	v_cmp_lt_f32_e64 vcc, |v117|, s56
	v_exp_f32_e32 v94, v94
	v_fmac_f32_e32 v125, 0x3f317217, v90
	v_cndmask_b32_e32 v117, v117, v124, vcc
	v_cmp_lt_f32_e64 vcc, |v90|, s56
	v_cndmask_b32_e64 v123, 0, v203, s[6:7]
	v_sub_f32_e32 v118, v111, v119
	v_cndmask_b32_e32 v90, v90, v125, vcc
	v_sub_f32_e32 v119, v90, v123
	v_pk_add_f32 v[114:115], v[114:115], v[118:119] neg_lo:[0,1] neg_hi:[0,1]
	v_add_f32_e32 v94, 1.0, v94
	v_cndmask_b32_e64 v120, 0, v203, s[4:5]
	v_mul_f32_e32 v90, 0x3fb8aa3b, v114
	v_rcp_f32_e32 v94, v94
	v_sub_f32_e32 v120, v117, v120
	v_exp_f32_e32 v117, v90
	v_mul_f32_e32 v111, 0x3fb8aa3b, v115
	v_exp_f32_e32 v111, v111
	v_min_f32_e32 v116, 0, v116
	v_mul_f32_e32 v95, 0x3fb8aa3b, v95
	v_exp_f32_e32 v95, v95
	v_sub_f32_e32 v118, 1.0, v102
	v_mul_f32_e32 v90, v94, v118
	v_fma_f32 v94, v117, v118, v102
	v_cmp_gt_f32_e64 s[4:5], s81, v94
	v_sub_f32_e32 v123, 1.0, v103
	v_fma_f32 v111, v111, v123, v103
	v_cndmask_b32_e64 v117, 0, 32, s[4:5]
	v_ldexp_f32 v94, v94, v117
	v_log_f32_e32 v94, v94
	v_cmp_gt_f32_e32 vcc, s81, v111
	v_cndmask_b32_e64 v117, 0, v203, s[4:5]
	v_sub_f32_e32 v119, 1.0, v98
	v_cndmask_b32_e64 v118, 0, 32, vcc
	v_ldexp_f32 v111, v111, v118
	v_mul_f32_e32 v118, 0x3f317217, v94
	v_fma_f32 v118, v94, s65, -v118
	v_fmac_f32_e32 v118, 0x3377d1cf, v94
	v_fmac_f32_e32 v118, 0x3f317217, v94
	v_cmp_lt_f32_e64 s[4:5], |v94|, s56
	v_log_f32_e32 v111, v111
	v_mul_f32_e32 v124, v122, v119
	v_cndmask_b32_e64 v94, v94, v118, s[4:5]
	v_cmp_gt_f32_e64 s[4:5], s81, v121
	v_sub_f32_e32 v125, v94, v117
	v_max_f32_e32 v117, v91, v91
	v_cndmask_b32_e64 v94, 0, 32, s[4:5]
	v_ldexp_f32 v94, v121, v94
	v_log_f32_e32 v94, v94
	v_min_f32_e32 v117, 0, v117
	v_mul_f32_e32 v122, 0x3f317217, v111
	v_fma_f32 v122, v111, s65, -v122
	v_mul_f32_e32 v118, 0x3f317217, v94
	v_fma_f32 v118, v94, s65, -v118
	v_fmac_f32_e32 v118, 0x3377d1cf, v94
	v_fmac_f32_e32 v118, 0x3f317217, v94
	v_cmp_lt_f32_e64 s[6:7], |v94|, s56
	v_fmac_f32_e32 v122, 0x3377d1cf, v111
	v_fmac_f32_e32 v122, 0x3f317217, v111
	v_cndmask_b32_e64 v94, v94, v118, s[6:7]
	v_cndmask_b32_e64 v118, 0, v203, s[4:5]
	v_sub_f32_e32 v121, v94, v118
	v_pk_add_f32 v[116:117], v[116:117], v[120:121] neg_lo:[0,1] neg_hi:[0,1]
	v_cmp_lt_f32_e64 s[4:5], |v111|, s56
	v_mul_f32_e32 v94, 0x3fb8aa3b, v116
	v_exp_f32_e32 v94, v94
	v_mul_f32_e32 v120, 0x3fb8aa3b, v117
	v_cndmask_b32_e64 v111, v111, v122, s[4:5]
	v_exp_f32_e32 v120, v120
	v_fma_f32 v94, v94, v119, v98
	v_cmp_gt_f32_e64 s[4:5], s81, v94
	v_mul_f32_e32 v91, 0x3fb8aa3b, v91
	v_exp_f32_e32 v91, v91
	v_cndmask_b32_e64 v118, 0, 32, s[4:5]
	v_ldexp_f32 v94, v94, v118
	v_cndmask_b32_e32 v118, 0, v203, vcc
	v_log_f32_e32 v94, v94
	v_sub_f32_e32 v111, v111, v118
	v_sub_f32_e32 v118, 1.0, v99
	v_fma_f32 v120, v120, v118, v99
	v_cmp_gt_f32_e32 vcc, s81, v120
	v_mul_f32_e32 v119, 0x3f317217, v94
	v_fma_f32 v119, v94, s65, -v119
	v_cndmask_b32_e64 v121, 0, 32, vcc
	v_ldexp_f32 v120, v120, v121
	v_log_f32_e32 v120, v120
	v_fmac_f32_e32 v119, 0x3377d1cf, v94
	v_fmac_f32_e32 v119, 0x3f317217, v94
	v_cmp_lt_f32_e64 s[6:7], |v94|, s56
	v_add_f32_e32 v91, 1.0, v91
	v_rcp_f32_e32 v91, v91
	v_cndmask_b32_e64 v94, v94, v119, s[6:7]
	v_cndmask_b32_e64 v119, 0, v203, s[4:5]
	v_sub_f32_e32 v126, v94, v119
	v_mul_f32_e32 v94, 0x3f317217, v120
	v_fma_f32 v94, v120, s65, -v94
	v_fmac_f32_e32 v94, 0x3377d1cf, v120
	v_fmac_f32_e32 v94, 0x3f317217, v120
	v_cmp_lt_f32_e64 s[4:5], |v120|, s56
	v_cndmask_b32_e32 v119, 0, v203, vcc
	v_mul_f32_e32 v129, v91, v118
	v_cndmask_b32_e64 v94, v120, v94, s[4:5]
	v_sub_f32_e32 v127, v94, v119
	v_add_f32_e32 v94, 1.0, v95
	v_mul_f32_e64 v95, |v96|, s82
	v_rcp_f32_e32 v94, v94
	v_exp_f32_e32 v95, v95
	v_max_f32_e32 v91, v96, v96
	v_mul_f32_e64 v118, |v92|, s82
	v_mul_f32_e32 v128, v94, v123
	v_add_f32_e32 v94, 1.0, v95
	v_cmp_gt_f32_e32 vcc, s81, v94
	v_exp_f32_e32 v119, v118
	v_sub_f32_e32 v121, 1.0, v104
	v_cndmask_b32_e64 v95, 0, 32, vcc
	v_ldexp_f32 v94, v94, v95
	v_log_f32_e32 v95, v94
	v_min_f32_e32 v94, 0, v91
	v_sub_f32_e32 v130, 1.0, v105
	v_mul_f32_e32 v91, 0x3f317217, v95
	v_fma_f32 v91, v95, s65, -v91
	v_fmac_f32_e32 v91, 0x3377d1cf, v95
	v_fmac_f32_e32 v91, 0x3f317217, v95
	v_cmp_lt_f32_e64 s[4:5], |v95|, s56
	s_nop 1
	v_cndmask_b32_e64 v91, v95, v91, s[4:5]
	v_cndmask_b32_e32 v95, 0, v203, vcc
	v_sub_f32_e32 v118, v91, v95
	v_add_f32_e32 v91, 1.0, v119
	v_cmp_gt_f32_e32 vcc, s81, v91
	s_nop 1
	v_cndmask_b32_e64 v95, 0, 32, vcc
	v_ldexp_f32 v91, v91, v95
	v_log_f32_e32 v91, v91
	v_max_f32_e32 v95, v92, v92
	v_min_f32_e32 v120, 0, v95
	v_mul_f32_e32 v92, 0x3fb8aa3b, v92
	v_mul_f32_e32 v95, 0x3f317217, v91
	v_fma_f32 v95, v91, s65, -v95
	v_fmac_f32_e32 v95, 0x3377d1cf, v91
	v_fmac_f32_e32 v95, 0x3f317217, v91
	v_cmp_lt_f32_e64 s[4:5], |v91|, s56
	v_exp_f32_e32 v92, v92
	s_nop 0
	v_cndmask_b32_e64 v91, v91, v95, s[4:5]
	v_cndmask_b32_e32 v95, 0, v203, vcc
	v_sub_f32_e32 v122, v91, v95
	v_mul_f32_e64 v95, |v97|, s82
	v_exp_f32_e32 v95, v95
	v_mul_f32_e32 v91, 0x3fb8aa3b, v96
	v_exp_f32_e32 v91, v91
	v_add_f32_e32 v92, 1.0, v92
	v_add_f32_e32 v95, 1.0, v95
	v_cmp_gt_f32_e32 vcc, s81, v95
	v_add_f32_e32 v91, 1.0, v91
	v_rcp_f32_e32 v91, v91
	v_cndmask_b32_e64 v119, 0, 32, vcc
	v_ldexp_f32 v95, v95, v119
	v_log_f32_e32 v119, v95
	v_max_f32_e32 v95, v97, v97
	v_min_f32_e32 v95, 0, v95
	v_mul_f32_e32 v91, v91, v121
	v_mul_f32_e32 v123, 0x3f317217, v119
	v_fma_f32 v123, v119, s65, -v123
	v_fmac_f32_e32 v123, 0x3377d1cf, v119
	v_fmac_f32_e32 v123, 0x3f317217, v119
	v_cmp_lt_f32_e64 s[4:5], |v119|, s56
	v_rcp_f32_e32 v92, v92
	v_sub_f32_e32 v96, 1.0, v100
	v_cndmask_b32_e64 v119, v119, v123, s[4:5]
	v_cndmask_b32_e32 v123, 0, v203, vcc
	v_sub_f32_e32 v119, v119, v123
	v_pk_add_f32 v[94:95], v[94:95], v[118:119] neg_lo:[0,1] neg_hi:[0,1]
	s_nop 0
	v_mul_f32_e32 v118, 0x3fb8aa3b, v94
	v_exp_f32_e32 v118, v118
	s_nop 0
	v_fma_f32 v118, v118, v121, v104
	v_mul_f32_e32 v121, 0x3fb8aa3b, v95
	v_cmp_gt_f32_e32 vcc, s81, v118
	v_exp_f32_e32 v121, v121
	s_nop 0
	v_cndmask_b32_e64 v119, 0, 32, vcc
	v_ldexp_f32 v118, v118, v119
	v_log_f32_e32 v118, v118
	v_fma_f32 v121, v121, v130, v105
	v_cmp_gt_f32_e64 s[4:5], s81, v121
	v_mul_f32_e32 v119, v92, v96
	v_mul_f32_e32 v92, 0x3f317217, v118
	v_cndmask_b32_e64 v123, 0, 32, s[4:5]
	v_ldexp_f32 v121, v121, v123
	v_fma_f32 v92, v118, s65, -v92
	v_log_f32_e32 v121, v121
	v_fmac_f32_e32 v92, 0x3377d1cf, v118
	v_fmac_f32_e32 v92, 0x3f317217, v118
	v_cmp_lt_f32_e64 s[6:7], |v118|, s56
	v_mul_f32_e64 v123, |v93|, s82
	v_exp_f32_e32 v123, v123
	v_cndmask_b32_e64 v92, v118, v92, s[6:7]
	v_cndmask_b32_e32 v118, 0, v203, vcc
	v_sub_f32_e32 v92, v92, v118
	v_mul_f32_e32 v118, 0x3f317217, v121
	v_fma_f32 v118, v121, s65, -v118
	v_fmac_f32_e32 v118, 0x3377d1cf, v121
	v_fmac_f32_e32 v118, 0x3f317217, v121
	v_cmp_lt_f32_e64 vcc, |v121|, s56
	s_nop 1
	v_cndmask_b32_e32 v118, v121, v118, vcc
	v_cmp_lt_f32_e32 vcc, 0, v103
	v_cndmask_b32_e64 v121, 0, v203, s[4:5]
	v_cmp_lt_f32_e64 s[4:5], 0, v102
	v_cndmask_b32_e32 v103, v115, v111, vcc
	v_add_f32_e32 v111, 1.0, v123
	v_cmp_gt_f32_e32 vcc, s81, v111
	v_cndmask_b32_e64 v102, v114, v125, s[4:5]
	v_max_f32_e32 v114, v93, v93
	v_cndmask_b32_e64 v115, 0, 32, vcc
	v_ldexp_f32 v111, v111, v115
	v_log_f32_e32 v111, v111
	v_sub_f32_e32 v118, v118, v121
	v_min_f32_e32 v121, 0, v114
	v_mul_f32_e32 v93, 0x3fb8aa3b, v93
	v_mul_f32_e32 v114, 0x3f317217, v111
	v_fma_f32 v114, v111, s65, -v114
	v_fmac_f32_e32 v114, 0x3377d1cf, v111
	v_fmac_f32_e32 v114, 0x3f317217, v111
	v_cmp_lt_f32_e64 s[4:5], |v111|, s56
	v_exp_f32_e32 v93, v93
	v_pk_mul_f32 v[102:103], v[102:103], s[68:69] op_sel_hi:[1,0]
	v_cndmask_b32_e64 v111, v111, v114, s[4:5]
	v_cndmask_b32_e32 v114, 0, v203, vcc
	v_sub_f32_e32 v123, v111, v114
	v_pk_add_f32 v[114:115], v[120:121], v[122:123] neg_lo:[0,1] neg_hi:[0,1]
	v_cmp_lt_f32_e32 vcc, 0, v105
	v_mul_f32_e32 v111, 0x3fb8aa3b, v114
	v_exp_f32_e32 v111, v111
	v_cndmask_b32_e32 v95, v95, v118, vcc
	v_cmp_lt_f32_e32 vcc, 0, v104
	s_nop 1
	v_cndmask_b32_e32 v94, v94, v92, vcc
	v_fma_f32 v92, v111, v96, v100
	v_pk_mul_f32 v[104:105], v[94:95], s[68:69] op_sel_hi:[1,0]
	v_mul_f32_e32 v95, 0x3fb8aa3b, v115
	v_cmp_gt_f32_e32 vcc, s81, v92
	v_exp_f32_e32 v95, v95
	s_nop 0
	v_cndmask_b32_e64 v96, 0, 32, vcc
	v_ldexp_f32 v92, v92, v96
	v_log_f32_e32 v92, v92
	v_sub_f32_e32 v96, 1.0, v101
	v_fma_f32 v95, v95, v96, v101
	v_cmp_gt_f32_e64 s[4:5], s81, v95
	v_mul_f32_e32 v94, 0x3f317217, v92
	v_fma_f32 v94, v92, s65, -v94
	v_cndmask_b32_e64 v111, 0, 32, s[4:5]
	v_ldexp_f32 v95, v95, v111
	v_log_f32_e32 v95, v95
	v_fmac_f32_e32 v94, 0x3377d1cf, v92
	v_fmac_f32_e32 v94, 0x3f317217, v92
	v_cmp_lt_f32_e64 s[6:7], |v92|, s56
	s_nop 1
	v_cndmask_b32_e64 v92, v92, v94, s[6:7]
	v_cndmask_b32_e32 v94, 0, v203, vcc
	v_sub_f32_e32 v92, v92, v94
	v_mul_f32_e32 v94, 0x3f317217, v95
	v_fma_f32 v94, v95, s65, -v94
	v_fmac_f32_e32 v94, 0x3377d1cf, v95
	v_fmac_f32_e32 v94, 0x3f317217, v95
	v_cmp_lt_f32_e64 vcc, |v95|, s56
	s_nop 1
	v_cndmask_b32_e32 v94, v95, v94, vcc
	v_cmp_lt_f32_e32 vcc, 0, v99
	v_cndmask_b32_e64 v95, 0, v203, s[4:5]
	v_sub_f32_e32 v94, v94, v95
	v_cndmask_b32_e32 v99, v117, v127, vcc
	v_cmp_lt_f32_e32 vcc, 0, v98
	s_nop 1
	v_cndmask_b32_e32 v98, v116, v126, vcc
	v_cmp_lt_f32_e32 vcc, 0, v101
	s_nop 1
	v_cndmask_b32_e32 v95, v115, v94, vcc
	v_mul_f32_e32 v94, 0x3fb8aa3b, v97
	v_exp_f32_e32 v97, v94
	v_cmp_lt_f32_e32 vcc, 0, v100
	s_nop 1
	v_cndmask_b32_e32 v94, v114, v92, vcc
	v_add_f32_e32 v92, 1.0, v97
	v_rcp_f32_e32 v97, v92
	v_add_f32_e32 v92, 1.0, v93
	v_rcp_f32_e32 v100, v92
	v_pk_mul_f32 v[94:95], v[94:95], s[68:69] op_sel_hi:[1,0]
	v_pk_mul_f32 v[92:93], v[98:99], s[68:69] op_sel_hi:[1,0]
	v_mul_f32_e32 v98, v97, v130
	v_mul_f32_e32 v99, v100, v96
	v_lshl_add_u64 v[96:97], v[108:109], 0, v[112:113]
	global_store_dwordx4 v[96:97], v[102:105], off
	global_store_dwordx4 v[96:97], v[92:95], off offset:16
	v_cvt_pk_bf16_f32 v90, v90, v128
	v_cvt_pk_bf16_f32 v91, v91, v98
	s_nop 1
	v_lshl_add_u64 v[94:95], v[148:149], 1, v[106:107]
	v_cvt_pk_bf16_f32 v92, v124, v129
	v_cvt_pk_bf16_f32 v93, v119, v99
	global_store_dwordx4 v[94:95], v[90:93], off

.LBB0_481:
	v_lshl_add_u64 v[98:99], v[148:149], 2, s[26:27]
	v_lshl_add_u64 v[90:91], s[14:15], 0, v[98:99]
	v_mov_b32_e32 v94, v214
	v_mov_b32_e32 v95, v215
	v_mov_b32_e32 v96, v216
	v_mov_b32_e32 v97, v217
	v_mov_b32_e32 v90, v218
	v_mov_b32_e32 v91, v219
	v_mov_b32_e32 v92, v220
	v_mov_b32_e32 v93, v221
	v_mul_f32_e64 v101, |v86|, s82
	v_mul_f32_e64 v103, |v82|, s82
	v_max_f32_e32 v104, v87, v87
	v_mul_f32_e64 v105, |v87|, s82
	v_exp_f32_e32 v111, v101
	v_max_f32_e32 v102, v82, v82
	v_mul_f32_e32 v82, 0x3fb8aa3b, v82
	v_mul_f32_e64 v110, |v83|, s82
	v_exp_f32_e32 v103, v103
	v_min_f32_e32 v101, 0, v104
	v_exp_f32_e32 v104, v105
	v_exp_f32_e32 v82, v82
	v_exp_f32_e32 v105, v110
	v_add_f32_e32 v110, 1.0, v111
	v_add_f32_e32 v103, 1.0, v103
	v_add_f32_e32 v104, 1.0, v104
	v_cmp_gt_f32_e32 vcc, s81, v110
	v_add_f32_e32 v82, 1.0, v82
	v_add_f32_e32 v111, 1.0, v105
	v_cndmask_b32_e64 v105, 0, 32, vcc
	v_cmp_gt_f32_e64 s[4:5], s81, v103
	v_cmp_gt_f32_e64 s[6:7], s81, v104
	v_rcp_f32_e32 v113, v82
	v_cndmask_b32_e64 v112, 0, 32, s[4:5]
	v_cndmask_b32_e64 v82, 0, 32, s[6:7]
	v_ldexp_f32 v105, v110, v105
	v_ldexp_f32 v103, v103, v112
	v_ldexp_f32 v82, v104, v82
	v_log_f32_e32 v104, v105
	v_log_f32_e32 v103, v103
	v_log_f32_e32 v82, v82
	v_cndmask_b32_e32 v110, 0, v203, vcc
	v_mul_f32_e32 v114, 0x3f317217, v104
	v_mul_f32_e32 v115, 0x3f317217, v103
	v_fma_f32 v114, v104, s65, -v114
	v_mul_f32_e32 v116, 0x3f317217, v82
	v_fma_f32 v115, v103, s65, -v115
	v_fmac_f32_e32 v114, 0x3377d1cf, v104
	v_fma_f32 v116, v82, s65, -v116
	v_fmac_f32_e32 v115, 0x3377d1cf, v103
	v_fmac_f32_e32 v114, 0x3f317217, v104
	v_cmp_lt_f32_e64 vcc, |v104|, s56
	v_max_f32_e32 v100, v86, v86
	v_mul_f32_e32 v86, 0x3fb8aa3b, v86
	v_fmac_f32_e32 v116, 0x3377d1cf, v82
	v_fmac_f32_e32 v115, 0x3f317217, v103
	v_cndmask_b32_e32 v104, v104, v114, vcc
	v_cmp_lt_f32_e64 vcc, |v103|, s56
	v_exp_f32_e32 v86, v86
	v_fmac_f32_e32 v116, 0x3f317217, v82
	v_cndmask_b32_e32 v103, v103, v115, vcc
	v_cmp_lt_f32_e64 vcc, |v82|, s56
	v_cndmask_b32_e64 v105, 0, v203, s[6:7]
	v_min_f32_e32 v100, 0, v100
	v_cndmask_b32_e32 v82, v82, v116, vcc
	v_sub_f32_e32 v104, v104, v110
	v_sub_f32_e32 v105, v82, v105
	v_pk_add_f32 v[100:101], v[100:101], v[104:105] neg_lo:[0,1] neg_hi:[0,1]
	v_add_f32_e32 v86, 1.0, v86
	v_mul_f32_e32 v82, 0x3fb8aa3b, v100
	v_rcp_f32_e32 v86, v86
	v_exp_f32_e32 v104, v82
	v_cndmask_b32_e64 v112, 0, v203, s[4:5]
	v_sub_f32_e32 v110, v103, v112
	v_mul_f32_e32 v103, 0x3fb8aa3b, v101
	v_exp_f32_e32 v103, v103
	v_min_f32_e32 v102, 0, v102
	v_mul_f32_e32 v87, 0x3fb8aa3b, v87
	v_exp_f32_e32 v87, v87
	v_sub_f32_e32 v105, 1.0, v94
	v_mul_f32_e32 v82, v86, v105
	v_fma_f32 v86, v104, v105, v94
	v_cmp_gt_f32_e64 s[4:5], s81, v86
	v_sub_f32_e32 v114, 1.0, v95
	v_fma_f32 v103, v103, v114, v95
	v_cndmask_b32_e64 v104, 0, 32, s[4:5]
	v_ldexp_f32 v86, v86, v104
	v_log_f32_e32 v86, v86
	v_cmp_gt_f32_e32 vcc, s81, v103
	v_sub_f32_e32 v112, 1.0, v90
	v_mul_f32_e32 v115, v113, v112
	v_cndmask_b32_e64 v105, 0, 32, vcc
	v_ldexp_f32 v103, v103, v105
	v_mul_f32_e32 v105, 0x3f317217, v86
	v_fma_f32 v105, v86, s65, -v105
	v_fmac_f32_e32 v105, 0x3377d1cf, v86
	v_log_f32_e32 v104, v103
	v_cndmask_b32_e64 v103, 0, v203, s[4:5]
	v_fmac_f32_e32 v105, 0x3f317217, v86
	v_cmp_lt_f32_e64 s[4:5], |v86|, s56
	v_mul_f32_e32 v113, 0x3f317217, v104
	v_fma_f32 v113, v104, s65, -v113
	v_cndmask_b32_e64 v86, v86, v105, s[4:5]
	v_cmp_gt_f32_e64 s[4:5], s81, v111
	v_sub_f32_e32 v116, v86, v103
	v_max_f32_e32 v103, v83, v83
	v_cndmask_b32_e64 v86, 0, 32, s[4:5]
	v_ldexp_f32 v86, v111, v86
	v_log_f32_e32 v86, v86
	v_min_f32_e32 v103, 0, v103
	v_fmac_f32_e32 v113, 0x3377d1cf, v104
	v_fmac_f32_e32 v113, 0x3f317217, v104
	v_mul_f32_e32 v105, 0x3f317217, v86
	v_fma_f32 v105, v86, s65, -v105
	v_fmac_f32_e32 v105, 0x3377d1cf, v86
	v_fmac_f32_e32 v105, 0x3f317217, v86
	v_cmp_lt_f32_e64 s[6:7], |v86|, s56
	v_mul_f32_e32 v83, 0x3fb8aa3b, v83
	v_exp_f32_e32 v83, v83
	v_cndmask_b32_e64 v86, v86, v105, s[6:7]
	v_cndmask_b32_e64 v105, 0, v203, s[4:5]
	v_sub_f32_e32 v111, v86, v105
	v_pk_add_f32 v[102:103], v[102:103], v[110:111] neg_lo:[0,1] neg_hi:[0,1]
	v_cmp_lt_f32_e64 s[4:5], |v104|, s56
	v_mul_f32_e32 v86, 0x3fb8aa3b, v102
	v_exp_f32_e32 v86, v86
	v_mul_f32_e32 v110, 0x3fb8aa3b, v103
	v_cndmask_b32_e64 v104, v104, v113, s[4:5]
	v_exp_f32_e32 v110, v110
	v_fma_f32 v86, v86, v112, v90
	v_cmp_gt_f32_e64 s[4:5], s81, v86
	v_add_f32_e32 v83, 1.0, v83
	v_rcp_f32_e32 v83, v83
	v_cndmask_b32_e64 v105, 0, 32, s[4:5]
	v_ldexp_f32 v86, v86, v105
	v_cndmask_b32_e32 v105, 0, v203, vcc
	v_log_f32_e32 v86, v86
	v_sub_f32_e32 v111, v104, v105
	v_sub_f32_e32 v104, 1.0, v91
	v_fma_f32 v110, v110, v104, v91
	v_cmp_gt_f32_e32 vcc, s81, v110
	v_mul_f32_e32 v105, 0x3f317217, v86
	v_fma_f32 v105, v86, s65, -v105
	v_cndmask_b32_e64 v112, 0, 32, vcc
	v_ldexp_f32 v110, v110, v112
	v_log_f32_e32 v110, v110
	v_fmac_f32_e32 v105, 0x3377d1cf, v86
	v_fmac_f32_e32 v105, 0x3f317217, v86
	v_cmp_lt_f32_e64 s[6:7], |v86|, s56
	v_mul_f32_e32 v119, v83, v104
	v_max_f32_e32 v83, v88, v88
	v_cndmask_b32_e64 v86, v86, v105, s[6:7]
	v_cndmask_b32_e64 v105, 0, v203, s[4:5]
	v_sub_f32_e32 v117, v86, v105
	v_mul_f32_e32 v86, 0x3f317217, v110
	v_fma_f32 v86, v110, s65, -v86
	v_fmac_f32_e32 v86, 0x3377d1cf, v110
	v_fmac_f32_e32 v86, 0x3f317217, v110
	v_cmp_lt_f32_e64 s[4:5], |v110|, s56
	v_cndmask_b32_e32 v105, 0, v203, vcc
	v_mul_f32_e64 v104, |v84|, s82
	v_cndmask_b32_e64 v86, v110, v86, s[4:5]
	v_sub_f32_e32 v118, v86, v105
	v_add_f32_e32 v86, 1.0, v87
	v_mul_f32_e64 v87, |v88|, s82
	v_rcp_f32_e32 v86, v86
	v_exp_f32_e32 v87, v87
	v_exp_f32_e32 v105, v104
	v_sub_f32_e32 v113, 1.0, v96
	v_mul_f32_e32 v114, v86, v114
	v_add_f32_e32 v86, 1.0, v87
	v_cmp_gt_f32_e32 vcc, s81, v86
	s_nop 1
	v_cndmask_b32_e64 v87, 0, 32, vcc
	v_ldexp_f32 v86, v86, v87
	v_log_f32_e32 v87, v86
	v_min_f32_e32 v86, 0, v83
	v_mul_f32_e32 v83, 0x3f317217, v87
	v_fma_f32 v83, v87, s65, -v83
	v_fmac_f32_e32 v83, 0x3377d1cf, v87
	v_fmac_f32_e32 v83, 0x3f317217, v87
	v_cmp_lt_f32_e64 s[4:5], |v87|, s56
	s_nop 1
	v_cndmask_b32_e64 v83, v87, v83, s[4:5]
	v_cndmask_b32_e32 v87, 0, v203, vcc
	v_sub_f32_e32 v104, v83, v87
	v_add_f32_e32 v83, 1.0, v105
	v_cmp_gt_f32_e32 vcc, s81, v83
	s_nop 1
	v_cndmask_b32_e64 v87, 0, 32, vcc
	v_ldexp_f32 v83, v83, v87
	v_log_f32_e32 v83, v83
	v_max_f32_e32 v87, v84, v84
	v_min_f32_e32 v110, 0, v87
	v_mul_f32_e32 v84, 0x3fb8aa3b, v84
	v_mul_f32_e32 v87, 0x3f317217, v83
	v_fma_f32 v87, v83, s65, -v87
	v_fmac_f32_e32 v87, 0x3377d1cf, v83
	v_fmac_f32_e32 v87, 0x3f317217, v83
	v_cmp_lt_f32_e64 s[4:5], |v83|, s56
	v_exp_f32_e32 v84, v84
	s_nop 0
	v_cndmask_b32_e64 v83, v83, v87, s[4:5]
	v_cndmask_b32_e32 v87, 0, v203, vcc
	v_sub_f32_e32 v112, v83, v87
	v_mul_f32_e64 v87, |v89|, s82
	v_exp_f32_e32 v87, v87
	v_mul_f32_e32 v83, 0x3fb8aa3b, v88
	v_exp_f32_e32 v83, v83
	v_add_f32_e32 v84, 1.0, v84
	v_add_f32_e32 v87, 1.0, v87
	v_cmp_gt_f32_e32 vcc, s81, v87
	v_add_f32_e32 v83, 1.0, v83
	v_rcp_f32_e32 v83, v83
	v_cndmask_b32_e64 v105, 0, 32, vcc
	v_ldexp_f32 v87, v87, v105
	v_log_f32_e32 v105, v87
	v_max_f32_e32 v87, v89, v89
	v_min_f32_e32 v87, 0, v87
	v_mul_f32_e32 v83, v83, v113
	v_mul_f32_e32 v120, 0x3f317217, v105
	v_fma_f32 v120, v105, s65, -v120
	v_fmac_f32_e32 v120, 0x3377d1cf, v105
	v_fmac_f32_e32 v120, 0x3f317217, v105
	v_cmp_lt_f32_e64 s[4:5], |v105|, s56
	v_rcp_f32_e32 v84, v84
	v_sub_f32_e32 v88, 1.0, v92
	v_cndmask_b32_e64 v105, v105, v120, s[4:5]
	v_cndmask_b32_e32 v120, 0, v203, vcc
	v_sub_f32_e32 v105, v105, v120
	v_pk_add_f32 v[86:87], v[86:87], v[104:105] neg_lo:[0,1] neg_hi:[0,1]
	v_sub_f32_e32 v120, 1.0, v97
	v_mul_f32_e32 v104, 0x3fb8aa3b, v86
	v_exp_f32_e32 v104, v104
	s_nop 0
	v_fma_f32 v104, v104, v113, v96
	v_mul_f32_e32 v113, 0x3fb8aa3b, v87
	v_cmp_gt_f32_e32 vcc, s81, v104
	v_exp_f32_e32 v113, v113
	s_nop 0
	v_cndmask_b32_e64 v105, 0, 32, vcc
	v_ldexp_f32 v104, v104, v105
	v_log_f32_e32 v104, v104
	v_fma_f32 v113, v113, v120, v97
	v_cmp_gt_f32_e64 s[4:5], s81, v113
	v_mul_f32_e32 v105, v84, v88
	v_mul_f32_e32 v84, 0x3f317217, v104
	v_cndmask_b32_e64 v121, 0, 32, s[4:5]
	v_ldexp_f32 v113, v113, v121
	v_fma_f32 v84, v104, s65, -v84
	v_log_f32_e32 v113, v113
	v_fmac_f32_e32 v84, 0x3377d1cf, v104
	v_fmac_f32_e32 v84, 0x3f317217, v104
	v_cmp_lt_f32_e64 s[6:7], |v104|, s56
	v_mul_f32_e64 v121, |v85|, s82
	v_exp_f32_e32 v121, v121
	v_cndmask_b32_e64 v84, v104, v84, s[6:7]
	v_cndmask_b32_e32 v104, 0, v203, vcc
	v_sub_f32_e32 v84, v84, v104
	v_mul_f32_e32 v104, 0x3f317217, v113
	v_fma_f32 v104, v113, s65, -v104
	v_fmac_f32_e32 v104, 0x3377d1cf, v113
	v_fmac_f32_e32 v104, 0x3f317217, v113
	v_cmp_lt_f32_e64 vcc, |v113|, s56
	s_nop 1
	v_cndmask_b32_e32 v104, v113, v104, vcc
	v_cmp_lt_f32_e32 vcc, 0, v95
	v_cndmask_b32_e64 v113, 0, v203, s[4:5]
	v_cmp_lt_f32_e64 s[4:5], 0, v94
	v_cndmask_b32_e32 v95, v101, v111, vcc
	v_add_f32_e32 v101, 1.0, v121
	v_cmp_gt_f32_e32 vcc, s81, v101
	v_cndmask_b32_e64 v94, v100, v116, s[4:5]
	v_max_f32_e32 v100, v85, v85
	v_cndmask_b32_e64 v111, 0, 32, vcc
	v_ldexp_f32 v101, v101, v111
	v_log_f32_e32 v101, v101
	v_min_f32_e32 v111, 0, v100
	v_sub_f32_e32 v104, v104, v113
	v_mul_f32_e32 v85, 0x3fb8aa3b, v85
	v_mul_f32_e32 v100, 0x3f317217, v101
	v_fma_f32 v100, v101, s65, -v100
	v_fmac_f32_e32 v100, 0x3377d1cf, v101
	v_fmac_f32_e32 v100, 0x3f317217, v101
	v_cmp_lt_f32_e64 s[4:5], |v101|, s56
	v_exp_f32_e32 v85, v85
	v_pk_mul_f32 v[94:95], v[94:95], s[68:69] op_sel_hi:[1,0]
	v_cndmask_b32_e64 v100, v101, v100, s[4:5]
	v_cndmask_b32_e32 v101, 0, v203, vcc
	v_sub_f32_e32 v113, v100, v101
	v_pk_add_f32 v[100:101], v[110:111], v[112:113] neg_lo:[0,1] neg_hi:[0,1]
	v_cmp_lt_f32_e32 vcc, 0, v97
	v_mul_f32_e32 v110, 0x3fb8aa3b, v100
	v_exp_f32_e32 v110, v110
	v_cndmask_b32_e32 v87, v87, v104, vcc
	v_cmp_lt_f32_e32 vcc, 0, v96
	s_nop 1
	v_cndmask_b32_e32 v86, v86, v84, vcc
	v_fma_f32 v84, v110, v88, v92
	v_pk_mul_f32 v[96:97], v[86:87], s[68:69] op_sel_hi:[1,0]
	v_mul_f32_e32 v87, 0x3fb8aa3b, v101
	v_cmp_gt_f32_e32 vcc, s81, v84
	v_exp_f32_e32 v87, v87
	s_nop 0
	v_cndmask_b32_e64 v88, 0, 32, vcc
	v_ldexp_f32 v84, v84, v88
	v_log_f32_e32 v84, v84
	v_sub_f32_e32 v88, 1.0, v93
	v_fma_f32 v87, v87, v88, v93
	v_cmp_gt_f32_e64 s[4:5], s81, v87
	v_mul_f32_e32 v86, 0x3f317217, v84
	v_fma_f32 v86, v84, s65, -v86
	v_cndmask_b32_e64 v104, 0, 32, s[4:5]
	v_ldexp_f32 v87, v87, v104
	v_log_f32_e32 v87, v87
	v_fmac_f32_e32 v86, 0x3377d1cf, v84
	v_fmac_f32_e32 v86, 0x3f317217, v84
	v_cmp_lt_f32_e64 s[6:7], |v84|, s56
	s_nop 1
	v_cndmask_b32_e64 v84, v84, v86, s[6:7]
	v_cndmask_b32_e32 v86, 0, v203, vcc
	v_sub_f32_e32 v84, v84, v86
	v_mul_f32_e32 v86, 0x3f317217, v87
	v_fma_f32 v86, v87, s65, -v86
	v_fmac_f32_e32 v86, 0x3377d1cf, v87
	v_fmac_f32_e32 v86, 0x3f317217, v87
	v_cmp_lt_f32_e64 vcc, |v87|, s56
	s_nop 1
	v_cndmask_b32_e32 v86, v87, v86, vcc
	v_cmp_lt_f32_e32 vcc, 0, v91
	v_cndmask_b32_e64 v87, 0, v203, s[4:5]
	v_sub_f32_e32 v86, v86, v87
	v_cndmask_b32_e32 v91, v103, v118, vcc
	v_cmp_lt_f32_e32 vcc, 0, v90
	s_nop 1
	v_cndmask_b32_e32 v90, v102, v117, vcc
	v_cmp_lt_f32_e32 vcc, 0, v93
	s_nop 1
	v_cndmask_b32_e32 v87, v101, v86, vcc
	v_mul_f32_e32 v86, 0x3fb8aa3b, v89
	v_exp_f32_e32 v89, v86
	v_cmp_lt_f32_e32 vcc, 0, v92
	s_nop 1
	v_cndmask_b32_e32 v86, v100, v84, vcc
	v_add_f32_e32 v84, 1.0, v89
	v_rcp_f32_e32 v89, v84
	v_add_f32_e32 v84, 1.0, v85
	v_rcp_f32_e32 v92, v84
	v_pk_mul_f32 v[86:87], v[86:87], s[68:69] op_sel_hi:[1,0]
	v_pk_mul_f32 v[84:85], v[90:91], s[68:69] op_sel_hi:[1,0]
	v_mul_f32_e32 v90, v89, v120
	v_mul_f32_e32 v91, v92, v88
	v_lshl_add_u64 v[88:89], v[108:109], 0, v[98:99]
	global_store_dwordx4 v[88:89], v[94:97], off
	global_store_dwordx4 v[88:89], v[84:87], off offset:16
	v_cvt_pk_bf16_f32 v82, v82, v114
	v_cvt_pk_bf16_f32 v83, v83, v90
	s_nop 1
	v_lshl_add_u64 v[86:87], v[148:149], 1, v[106:107]
	v_cvt_pk_bf16_f32 v84, v115, v119
	v_cvt_pk_bf16_f32 v85, v105, v91
	global_store_dwordx4 v[86:87], v[82:85], off offset:256
	s_and_b64 vcc, exec, s[90:91]
	s_cbranch_vccz .LBB0_473

.LBB0_491:
	v_ashrrev_i32_e32 v93, 31, v92
	s_nop 0
	v_lshlrev_b64 v[82:83], 11, v[92:93]
	s_and_b64 vcc, exec, s[0:1]
	v_lshl_add_u64 v[90:91], s[10:11], 0, v[90:91]
	v_lshl_add_u64 v[92:93], v[82:83], 2, s[12:13]
	s_cbranch_vccz .LBB0_493
	v_lshl_add_u64 v[96:97], v[148:149], 2, s[2:3]
	v_lshl_add_u64 v[82:83], s[14:15], 0, v[96:97]
	v_mov_b32_e32 v86, v206
	v_mov_b32_e32 v87, v207
	v_mov_b32_e32 v88, v208
	v_mov_b32_e32 v89, v209
	v_mov_b32_e32 v82, v210
	v_mov_b32_e32 v83, v211
	v_mov_b32_e32 v84, v212
	v_mov_b32_e32 v85, v213
	v_max_f32_e32 v95, v78, v78
	v_mul_f32_e64 v99, |v78|, s82
	v_mul_f32_e64 v101, |v74|, s82
	v_min_f32_e32 v98, 0, v95
	v_exp_f32_e32 v95, v99
	v_max_f32_e32 v102, v79, v79
	v_mul_f32_e64 v103, |v79|, s82
	v_mul_f32_e64 v104, |v75|, s82
	v_exp_f32_e32 v101, v101
	v_max_f32_e32 v100, v74, v74
	v_mul_f32_e32 v74, 0x3fb8aa3b, v74
	v_min_f32_e32 v99, 0, v102
	v_exp_f32_e32 v102, v103
	v_exp_f32_e32 v103, v104
	v_exp_f32_e32 v74, v74
	v_add_f32_e32 v95, 1.0, v95
	v_add_f32_e32 v101, 1.0, v101
	v_cmp_gt_f32_e32 vcc, s81, v95
	v_add_f32_e32 v102, 1.0, v102
	v_add_f32_e32 v105, 1.0, v103
	v_cndmask_b32_e64 v103, 0, 32, vcc
	v_cmp_gt_f32_e64 s[4:5], s81, v101
	v_add_f32_e32 v74, 1.0, v74
	v_cmp_gt_f32_e64 s[6:7], s81, v102
	v_cndmask_b32_e64 v104, 0, 32, s[4:5]
	v_ldexp_f32 v95, v95, v103
	v_rcp_f32_e32 v106, v74
	v_cndmask_b32_e64 v74, 0, 32, s[6:7]
	v_ldexp_f32 v101, v101, v104
	v_log_f32_e32 v95, v95
	v_ldexp_f32 v74, v102, v74
	v_log_f32_e32 v101, v101
	v_log_f32_e32 v74, v74
	v_mul_f32_e32 v102, 0x3f317217, v95
	v_fma_f32 v102, v95, s65, -v102
	v_mul_f32_e32 v108, 0x3f317217, v101
	v_mul_f32_e32 v109, 0x3f317217, v74
	v_fma_f32 v108, v101, s65, -v108
	v_fmac_f32_e32 v102, 0x3377d1cf, v95
	v_cndmask_b32_e32 v103, 0, v203, vcc
	v_fma_f32 v109, v74, s65, -v109
	v_fmac_f32_e32 v108, 0x3377d1cf, v101
	v_fmac_f32_e32 v102, 0x3f317217, v95
	v_cmp_lt_f32_e64 vcc, |v95|, s56
	v_mul_f32_e32 v78, 0x3fb8aa3b, v78
	v_fmac_f32_e32 v109, 0x3377d1cf, v74
	v_fmac_f32_e32 v108, 0x3f317217, v101
	v_cndmask_b32_e32 v95, v95, v102, vcc
	v_cmp_lt_f32_e64 vcc, |v101|, s56
	v_exp_f32_e32 v78, v78
	v_fmac_f32_e32 v109, 0x3f317217, v74
	v_cndmask_b32_e32 v101, v101, v108, vcc
	v_cmp_lt_f32_e64 vcc, |v74|, s56
	v_cndmask_b32_e64 v107, 0, v203, s[6:7]
	v_sub_f32_e32 v102, v95, v103
	v_cndmask_b32_e32 v74, v74, v109, vcc
	v_sub_f32_e32 v103, v74, v107
	v_pk_add_f32 v[98:99], v[98:99], v[102:103] neg_lo:[0,1] neg_hi:[0,1]
	v_add_f32_e32 v78, 1.0, v78
	v_cndmask_b32_e64 v104, 0, v203, s[4:5]
	v_mul_f32_e32 v74, 0x3fb8aa3b, v98
	v_rcp_f32_e32 v78, v78
	v_sub_f32_e32 v104, v101, v104
	v_exp_f32_e32 v101, v74
	v_mul_f32_e32 v95, 0x3fb8aa3b, v99
	v_exp_f32_e32 v95, v95
	v_min_f32_e32 v100, 0, v100
	v_mul_f32_e32 v79, 0x3fb8aa3b, v79
	v_exp_f32_e32 v79, v79
	v_sub_f32_e32 v102, 1.0, v86
	v_mul_f32_e32 v74, v78, v102
	v_fma_f32 v78, v101, v102, v86
	v_cmp_gt_f32_e64 s[4:5], s81, v78
	v_sub_f32_e32 v107, 1.0, v87
	v_fma_f32 v95, v95, v107, v87
	v_cndmask_b32_e64 v101, 0, 32, s[4:5]
	v_ldexp_f32 v78, v78, v101
	v_log_f32_e32 v78, v78
	v_cmp_gt_f32_e32 vcc, s81, v95
	v_cndmask_b32_e64 v101, 0, v203, s[4:5]
	v_sub_f32_e32 v103, 1.0, v82
	v_cndmask_b32_e64 v102, 0, 32, vcc
	v_ldexp_f32 v95, v95, v102
	v_mul_f32_e32 v102, 0x3f317217, v78
	v_fma_f32 v102, v78, s65, -v102
	v_fmac_f32_e32 v102, 0x3377d1cf, v78
	v_fmac_f32_e32 v102, 0x3f317217, v78
	v_cmp_lt_f32_e64 s[4:5], |v78|, s56
	v_log_f32_e32 v95, v95
	v_mul_f32_e32 v108, v106, v103
	v_cndmask_b32_e64 v78, v78, v102, s[4:5]
	v_cmp_gt_f32_e64 s[4:5], s81, v105
	v_sub_f32_e32 v109, v78, v101
	v_max_f32_e32 v101, v75, v75
	v_cndmask_b32_e64 v78, 0, 32, s[4:5]
	v_ldexp_f32 v78, v105, v78
	v_log_f32_e32 v78, v78
	v_min_f32_e32 v101, 0, v101
	v_mul_f32_e32 v106, 0x3f317217, v95
	v_fma_f32 v106, v95, s65, -v106
	v_mul_f32_e32 v102, 0x3f317217, v78
	v_fma_f32 v102, v78, s65, -v102
	v_fmac_f32_e32 v102, 0x3377d1cf, v78
	v_fmac_f32_e32 v102, 0x3f317217, v78
	v_cmp_lt_f32_e64 s[6:7], |v78|, s56
	v_fmac_f32_e32 v106, 0x3377d1cf, v95
	v_fmac_f32_e32 v106, 0x3f317217, v95
	v_cndmask_b32_e64 v78, v78, v102, s[6:7]
	v_cndmask_b32_e64 v102, 0, v203, s[4:5]
	v_sub_f32_e32 v105, v78, v102
	v_pk_add_f32 v[100:101], v[100:101], v[104:105] neg_lo:[0,1] neg_hi:[0,1]
	v_cmp_lt_f32_e64 s[4:5], |v95|, s56
	v_mul_f32_e32 v78, 0x3fb8aa3b, v100
	v_exp_f32_e32 v78, v78
	v_mul_f32_e32 v104, 0x3fb8aa3b, v101
	v_cndmask_b32_e64 v95, v95, v106, s[4:5]
	v_exp_f32_e32 v104, v104
	v_fma_f32 v78, v78, v103, v82
	v_cmp_gt_f32_e64 s[4:5], s81, v78
	v_mul_f32_e32 v75, 0x3fb8aa3b, v75
	v_exp_f32_e32 v75, v75
	v_cndmask_b32_e64 v102, 0, 32, s[4:5]
	v_ldexp_f32 v78, v78, v102
	v_cndmask_b32_e32 v102, 0, v203, vcc
	v_log_f32_e32 v78, v78
	v_sub_f32_e32 v95, v95, v102
	v_sub_f32_e32 v102, 1.0, v83
	v_fma_f32 v104, v104, v102, v83
	v_cmp_gt_f32_e32 vcc, s81, v104
	v_mul_f32_e32 v103, 0x3f317217, v78
	v_fma_f32 v103, v78, s65, -v103
	v_cndmask_b32_e64 v105, 0, 32, vcc
	v_ldexp_f32 v104, v104, v105
	v_log_f32_e32 v104, v104
	v_fmac_f32_e32 v103, 0x3377d1cf, v78
	v_fmac_f32_e32 v103, 0x3f317217, v78
	v_cmp_lt_f32_e64 s[6:7], |v78|, s56
	v_add_f32_e32 v75, 1.0, v75
	v_rcp_f32_e32 v75, v75
	v_cndmask_b32_e64 v78, v78, v103, s[6:7]
	v_cndmask_b32_e64 v103, 0, v203, s[4:5]
	v_sub_f32_e32 v110, v78, v103
	v_mul_f32_e32 v78, 0x3f317217, v104
	v_fma_f32 v78, v104, s65, -v78
	v_fmac_f32_e32 v78, 0x3377d1cf, v104
	v_fmac_f32_e32 v78, 0x3f317217, v104
	v_cmp_lt_f32_e64 s[4:5], |v104|, s56
	v_cndmask_b32_e32 v103, 0, v203, vcc
	v_mul_f32_e32 v113, v75, v102
	v_cndmask_b32_e64 v78, v104, v78, s[4:5]
	v_sub_f32_e32 v111, v78, v103
	v_add_f32_e32 v78, 1.0, v79
	v_mul_f32_e64 v79, |v80|, s82
	v_rcp_f32_e32 v78, v78
	v_exp_f32_e32 v79, v79
	v_max_f32_e32 v75, v80, v80
	v_mul_f32_e64 v102, |v76|, s82
	v_mul_f32_e32 v112, v78, v107
	v_add_f32_e32 v78, 1.0, v79
	v_cmp_gt_f32_e32 vcc, s81, v78
	v_exp_f32_e32 v103, v102
	v_sub_f32_e32 v105, 1.0, v88
	v_cndmask_b32_e64 v79, 0, 32, vcc
	v_ldexp_f32 v78, v78, v79
	v_log_f32_e32 v79, v78
	v_min_f32_e32 v78, 0, v75
	v_sub_f32_e32 v114, 1.0, v89
	v_mul_f32_e32 v75, 0x3f317217, v79
	v_fma_f32 v75, v79, s65, -v75
	v_fmac_f32_e32 v75, 0x3377d1cf, v79
	v_fmac_f32_e32 v75, 0x3f317217, v79
	v_cmp_lt_f32_e64 s[4:5], |v79|, s56
	s_nop 1
	v_cndmask_b32_e64 v75, v79, v75, s[4:5]
	v_cndmask_b32_e32 v79, 0, v203, vcc
	v_sub_f32_e32 v102, v75, v79
	v_add_f32_e32 v75, 1.0, v103
	v_cmp_gt_f32_e32 vcc, s81, v75
	s_nop 1
	v_cndmask_b32_e64 v79, 0, 32, vcc
	v_ldexp_f32 v75, v75, v79
	v_log_f32_e32 v75, v75
	v_max_f32_e32 v79, v76, v76
	v_min_f32_e32 v104, 0, v79
	v_mul_f32_e32 v76, 0x3fb8aa3b, v76
	v_mul_f32_e32 v79, 0x3f317217, v75
	v_fma_f32 v79, v75, s65, -v79
	v_fmac_f32_e32 v79, 0x3377d1cf, v75
	v_fmac_f32_e32 v79, 0x3f317217, v75
	v_cmp_lt_f32_e64 s[4:5], |v75|, s56
	v_exp_f32_e32 v76, v76
	s_nop 0
	v_cndmask_b32_e64 v75, v75, v79, s[4:5]
	v_cndmask_b32_e32 v79, 0, v203, vcc
	v_sub_f32_e32 v106, v75, v79
	v_mul_f32_e64 v79, |v81|, s82
	v_exp_f32_e32 v79, v79
	v_mul_f32_e32 v75, 0x3fb8aa3b, v80
	v_exp_f32_e32 v75, v75
	v_add_f32_e32 v76, 1.0, v76
	v_add_f32_e32 v79, 1.0, v79
	v_cmp_gt_f32_e32 vcc, s81, v79
	v_add_f32_e32 v75, 1.0, v75
	v_rcp_f32_e32 v75, v75
	v_cndmask_b32_e64 v103, 0, 32, vcc
	v_ldexp_f32 v79, v79, v103
	v_log_f32_e32 v103, v79
	v_max_f32_e32 v79, v81, v81
	v_min_f32_e32 v79, 0, v79
	v_mul_f32_e32 v75, v75, v105
	v_mul_f32_e32 v107, 0x3f317217, v103
	v_fma_f32 v107, v103, s65, -v107
	v_fmac_f32_e32 v107, 0x3377d1cf, v103
	v_fmac_f32_e32 v107, 0x3f317217, v103
	v_cmp_lt_f32_e64 s[4:5], |v103|, s56
	v_rcp_f32_e32 v76, v76
	v_sub_f32_e32 v80, 1.0, v84
	v_cndmask_b32_e64 v103, v103, v107, s[4:5]
	v_cndmask_b32_e32 v107, 0, v203, vcc
	v_sub_f32_e32 v103, v103, v107
	v_pk_add_f32 v[78:79], v[78:79], v[102:103] neg_lo:[0,1] neg_hi:[0,1]
	s_nop 0
	v_mul_f32_e32 v102, 0x3fb8aa3b, v78
	v_exp_f32_e32 v102, v102
	s_nop 0
	v_fma_f32 v102, v102, v105, v88
	v_mul_f32_e32 v105, 0x3fb8aa3b, v79
	v_cmp_gt_f32_e32 vcc, s81, v102
	v_exp_f32_e32 v105, v105
	s_nop 0
	v_cndmask_b32_e64 v103, 0, 32, vcc
	v_ldexp_f32 v102, v102, v103
	v_log_f32_e32 v102, v102
	v_fma_f32 v105, v105, v114, v89
	v_cmp_gt_f32_e64 s[4:5], s81, v105
	v_mul_f32_e32 v103, v76, v80
	v_mul_f32_e32 v76, 0x3f317217, v102
	v_cndmask_b32_e64 v107, 0, 32, s[4:5]
	v_ldexp_f32 v105, v105, v107
	v_fma_f32 v76, v102, s65, -v76
	v_log_f32_e32 v105, v105
	v_fmac_f32_e32 v76, 0x3377d1cf, v102
	v_fmac_f32_e32 v76, 0x3f317217, v102
	v_cmp_lt_f32_e64 s[6:7], |v102|, s56
	v_mul_f32_e64 v107, |v77|, s82
	v_exp_f32_e32 v107, v107
	v_cndmask_b32_e64 v76, v102, v76, s[6:7]
	v_cndmask_b32_e32 v102, 0, v203, vcc
	v_sub_f32_e32 v76, v76, v102
	v_mul_f32_e32 v102, 0x3f317217, v105
	v_fma_f32 v102, v105, s65, -v102
	v_fmac_f32_e32 v102, 0x3377d1cf, v105
	v_fmac_f32_e32 v102, 0x3f317217, v105
	v_cmp_lt_f32_e64 vcc, |v105|, s56
	s_nop 1
	v_cndmask_b32_e32 v102, v105, v102, vcc
	v_cmp_lt_f32_e32 vcc, 0, v87
	v_cndmask_b32_e64 v105, 0, v203, s[4:5]
	v_cmp_lt_f32_e64 s[4:5], 0, v86
	v_cndmask_b32_e32 v87, v99, v95, vcc
	v_add_f32_e32 v95, 1.0, v107
	v_cmp_gt_f32_e32 vcc, s81, v95
	v_cndmask_b32_e64 v86, v98, v109, s[4:5]
	v_max_f32_e32 v98, v77, v77
	v_cndmask_b32_e64 v99, 0, 32, vcc
	v_ldexp_f32 v95, v95, v99
	v_log_f32_e32 v95, v95
	v_sub_f32_e32 v102, v102, v105
	v_min_f32_e32 v105, 0, v98
	v_mul_f32_e32 v77, 0x3fb8aa3b, v77
	v_mul_f32_e32 v98, 0x3f317217, v95
	v_fma_f32 v98, v95, s65, -v98
	v_fmac_f32_e32 v98, 0x3377d1cf, v95
	v_fmac_f32_e32 v98, 0x3f317217, v95
	v_cmp_lt_f32_e64 s[4:5], |v95|, s56
	v_exp_f32_e32 v77, v77
	v_pk_mul_f32 v[86:87], v[86:87], s[68:69] op_sel_hi:[1,0]
	v_cndmask_b32_e64 v95, v95, v98, s[4:5]
	v_cndmask_b32_e32 v98, 0, v203, vcc
	v_sub_f32_e32 v107, v95, v98
	v_pk_add_f32 v[98:99], v[104:105], v[106:107] neg_lo:[0,1] neg_hi:[0,1]
	v_cmp_lt_f32_e32 vcc, 0, v89
	v_mul_f32_e32 v95, 0x3fb8aa3b, v98
	v_exp_f32_e32 v95, v95
	v_cndmask_b32_e32 v79, v79, v102, vcc
	v_cmp_lt_f32_e32 vcc, 0, v88
	s_nop 1
	v_cndmask_b32_e32 v78, v78, v76, vcc
	v_fma_f32 v76, v95, v80, v84
	v_pk_mul_f32 v[88:89], v[78:79], s[68:69] op_sel_hi:[1,0]
	v_mul_f32_e32 v79, 0x3fb8aa3b, v99
	v_cmp_gt_f32_e32 vcc, s81, v76
	v_exp_f32_e32 v79, v79
	s_nop 0
	v_cndmask_b32_e64 v80, 0, 32, vcc
	v_ldexp_f32 v76, v76, v80
	v_log_f32_e32 v76, v76
	v_sub_f32_e32 v80, 1.0, v85
	v_fma_f32 v79, v79, v80, v85
	v_cmp_gt_f32_e64 s[4:5], s81, v79
	v_mul_f32_e32 v78, 0x3f317217, v76
	v_fma_f32 v78, v76, s65, -v78
	v_cndmask_b32_e64 v95, 0, 32, s[4:5]
	v_ldexp_f32 v79, v79, v95
	v_log_f32_e32 v79, v79
	v_fmac_f32_e32 v78, 0x3377d1cf, v76
	v_fmac_f32_e32 v78, 0x3f317217, v76
	v_cmp_lt_f32_e64 s[6:7], |v76|, s56
	s_nop 1
	v_cndmask_b32_e64 v76, v76, v78, s[6:7]
	v_cndmask_b32_e32 v78, 0, v203, vcc
	v_sub_f32_e32 v76, v76, v78
	v_mul_f32_e32 v78, 0x3f317217, v79
	v_fma_f32 v78, v79, s65, -v78
	v_fmac_f32_e32 v78, 0x3377d1cf, v79
	v_fmac_f32_e32 v78, 0x3f317217, v79
	v_cmp_lt_f32_e64 vcc, |v79|, s56
	s_nop 1
	v_cndmask_b32_e32 v78, v79, v78, vcc
	v_cmp_lt_f32_e32 vcc, 0, v83
	v_cndmask_b32_e64 v79, 0, v203, s[4:5]
	v_sub_f32_e32 v78, v78, v79
	v_cndmask_b32_e32 v83, v101, v111, vcc
	v_cmp_lt_f32_e32 vcc, 0, v82
	s_nop 1
	v_cndmask_b32_e32 v82, v100, v110, vcc
	v_cmp_lt_f32_e32 vcc, 0, v85
	s_nop 1
	v_cndmask_b32_e32 v79, v99, v78, vcc
	v_mul_f32_e32 v78, 0x3fb8aa3b, v81
	v_exp_f32_e32 v81, v78
	v_cmp_lt_f32_e32 vcc, 0, v84
	s_nop 1
	v_cndmask_b32_e32 v78, v98, v76, vcc
	v_add_f32_e32 v76, 1.0, v81
	v_rcp_f32_e32 v81, v76
	v_add_f32_e32 v76, 1.0, v77
	v_rcp_f32_e32 v84, v76
	v_pk_mul_f32 v[78:79], v[78:79], s[68:69] op_sel_hi:[1,0]
	v_pk_mul_f32 v[76:77], v[82:83], s[68:69] op_sel_hi:[1,0]
	v_mul_f32_e32 v82, v81, v114
	v_mul_f32_e32 v83, v84, v80
	v_lshl_add_u64 v[80:81], v[92:93], 0, v[96:97]
	global_store_dwordx4 v[80:81], v[86:89], off
	global_store_dwordx4 v[80:81], v[76:79], off offset:16
	v_cvt_pk_bf16_f32 v74, v74, v112
	v_cvt_pk_bf16_f32 v75, v75, v82
	s_nop 1
	v_lshl_add_u64 v[78:79], v[148:149], 1, v[90:91]
	v_cvt_pk_bf16_f32 v76, v108, v113
	v_cvt_pk_bf16_f32 v77, v103, v83
	global_store_dwordx4 v[78:79], v[74:77], off

.LBB0_504:
	v_lshl_add_u64 v[82:83], v[148:149], 2, s[26:27]
	v_lshl_add_u64 v[74:75], s[14:15], 0, v[82:83]
	v_mov_b32_e32 v78, v214
	v_mov_b32_e32 v79, v215
	v_mov_b32_e32 v80, v216
	v_mov_b32_e32 v81, v217
	v_mov_b32_e32 v74, v218
	v_mov_b32_e32 v75, v219
	v_mov_b32_e32 v76, v220
	v_mov_b32_e32 v77, v221
	v_mul_f32_e64 v85, |v70|, s82
	v_mul_f32_e64 v87, |v66|, s82
	v_max_f32_e32 v88, v71, v71
	v_mul_f32_e64 v89, |v71|, s82
	v_exp_f32_e32 v95, v85
	v_max_f32_e32 v86, v66, v66
	v_mul_f32_e32 v66, 0x3fb8aa3b, v66
	v_mul_f32_e64 v94, |v67|, s82
	v_exp_f32_e32 v87, v87
	v_min_f32_e32 v85, 0, v88
	v_exp_f32_e32 v88, v89
	v_exp_f32_e32 v66, v66
	v_exp_f32_e32 v89, v94
	v_add_f32_e32 v94, 1.0, v95
	v_add_f32_e32 v87, 1.0, v87
	v_add_f32_e32 v88, 1.0, v88
	v_cmp_gt_f32_e32 vcc, s81, v94
	v_add_f32_e32 v66, 1.0, v66
	v_add_f32_e32 v95, 1.0, v89
	v_cndmask_b32_e64 v89, 0, 32, vcc
	v_cmp_gt_f32_e64 s[4:5], s81, v87
	v_cmp_gt_f32_e64 s[6:7], s81, v88
	v_rcp_f32_e32 v97, v66
	v_cndmask_b32_e64 v96, 0, 32, s[4:5]
	v_cndmask_b32_e64 v66, 0, 32, s[6:7]
	v_ldexp_f32 v89, v94, v89
	v_ldexp_f32 v87, v87, v96
	v_ldexp_f32 v66, v88, v66
	v_log_f32_e32 v88, v89
	v_log_f32_e32 v87, v87
	v_log_f32_e32 v66, v66
	v_cndmask_b32_e32 v94, 0, v203, vcc
	v_mul_f32_e32 v98, 0x3f317217, v88
	v_mul_f32_e32 v99, 0x3f317217, v87
	v_fma_f32 v98, v88, s65, -v98
	v_mul_f32_e32 v100, 0x3f317217, v66
	v_fma_f32 v99, v87, s65, -v99
	v_fmac_f32_e32 v98, 0x3377d1cf, v88
	v_fma_f32 v100, v66, s65, -v100
	v_fmac_f32_e32 v99, 0x3377d1cf, v87
	v_fmac_f32_e32 v98, 0x3f317217, v88
	v_cmp_lt_f32_e64 vcc, |v88|, s56
	v_max_f32_e32 v84, v70, v70
	v_mul_f32_e32 v70, 0x3fb8aa3b, v70
	v_fmac_f32_e32 v100, 0x3377d1cf, v66
	v_fmac_f32_e32 v99, 0x3f317217, v87
	v_cndmask_b32_e32 v88, v88, v98, vcc
	v_cmp_lt_f32_e64 vcc, |v87|, s56
	v_exp_f32_e32 v70, v70
	v_fmac_f32_e32 v100, 0x3f317217, v66
	v_cndmask_b32_e32 v87, v87, v99, vcc
	v_cmp_lt_f32_e64 vcc, |v66|, s56
	v_cndmask_b32_e64 v89, 0, v203, s[6:7]
	v_min_f32_e32 v84, 0, v84
	v_cndmask_b32_e32 v66, v66, v100, vcc
	v_sub_f32_e32 v88, v88, v94
	v_sub_f32_e32 v89, v66, v89
	v_pk_add_f32 v[84:85], v[84:85], v[88:89] neg_lo:[0,1] neg_hi:[0,1]
	v_add_f32_e32 v70, 1.0, v70
	v_mul_f32_e32 v66, 0x3fb8aa3b, v84
	v_rcp_f32_e32 v70, v70
	v_exp_f32_e32 v88, v66
	v_cndmask_b32_e64 v96, 0, v203, s[4:5]
	v_sub_f32_e32 v94, v87, v96
	v_mul_f32_e32 v87, 0x3fb8aa3b, v85
	v_exp_f32_e32 v87, v87
	v_min_f32_e32 v86, 0, v86
	v_mul_f32_e32 v71, 0x3fb8aa3b, v71
	v_exp_f32_e32 v71, v71
	v_sub_f32_e32 v89, 1.0, v78
	v_mul_f32_e32 v66, v70, v89
	v_fma_f32 v70, v88, v89, v78
	v_cmp_gt_f32_e64 s[4:5], s81, v70
	v_sub_f32_e32 v98, 1.0, v79
	v_fma_f32 v87, v87, v98, v79
	v_cndmask_b32_e64 v88, 0, 32, s[4:5]
	v_ldexp_f32 v70, v70, v88
	v_log_f32_e32 v70, v70
	v_cmp_gt_f32_e32 vcc, s81, v87
	v_sub_f32_e32 v96, 1.0, v74
	v_mul_f32_e32 v99, v97, v96
	v_cndmask_b32_e64 v89, 0, 32, vcc
	v_ldexp_f32 v87, v87, v89
	v_mul_f32_e32 v89, 0x3f317217, v70
	v_fma_f32 v89, v70, s65, -v89
	v_fmac_f32_e32 v89, 0x3377d1cf, v70
	v_log_f32_e32 v88, v87
	v_cndmask_b32_e64 v87, 0, v203, s[4:5]
	v_fmac_f32_e32 v89, 0x3f317217, v70
	v_cmp_lt_f32_e64 s[4:5], |v70|, s56
	v_mul_f32_e32 v97, 0x3f317217, v88
	v_fma_f32 v97, v88, s65, -v97
	v_cndmask_b32_e64 v70, v70, v89, s[4:5]
	v_cmp_gt_f32_e64 s[4:5], s81, v95
	v_sub_f32_e32 v100, v70, v87
	v_max_f32_e32 v87, v67, v67
	v_cndmask_b32_e64 v70, 0, 32, s[4:5]
	v_ldexp_f32 v70, v95, v70
	v_log_f32_e32 v70, v70
	v_min_f32_e32 v87, 0, v87
	v_fmac_f32_e32 v97, 0x3377d1cf, v88
	v_fmac_f32_e32 v97, 0x3f317217, v88
	v_mul_f32_e32 v89, 0x3f317217, v70
	v_fma_f32 v89, v70, s65, -v89
	v_fmac_f32_e32 v89, 0x3377d1cf, v70
	v_fmac_f32_e32 v89, 0x3f317217, v70
	v_cmp_lt_f32_e64 s[6:7], |v70|, s56
	v_mul_f32_e32 v67, 0x3fb8aa3b, v67
	v_exp_f32_e32 v67, v67
	v_cndmask_b32_e64 v70, v70, v89, s[6:7]
	v_cndmask_b32_e64 v89, 0, v203, s[4:5]
	v_sub_f32_e32 v95, v70, v89
	v_pk_add_f32 v[86:87], v[86:87], v[94:95] neg_lo:[0,1] neg_hi:[0,1]
	v_cmp_lt_f32_e64 s[4:5], |v88|, s56
	v_mul_f32_e32 v70, 0x3fb8aa3b, v86
	v_exp_f32_e32 v70, v70
	v_mul_f32_e32 v94, 0x3fb8aa3b, v87
	v_cndmask_b32_e64 v88, v88, v97, s[4:5]
	v_exp_f32_e32 v94, v94
	v_fma_f32 v70, v70, v96, v74
	v_cmp_gt_f32_e64 s[4:5], s81, v70
	v_add_f32_e32 v67, 1.0, v67
	v_rcp_f32_e32 v67, v67
	v_cndmask_b32_e64 v89, 0, 32, s[4:5]
	v_ldexp_f32 v70, v70, v89
	v_cndmask_b32_e32 v89, 0, v203, vcc
	v_log_f32_e32 v70, v70
	v_sub_f32_e32 v95, v88, v89
	v_sub_f32_e32 v88, 1.0, v75
	v_fma_f32 v94, v94, v88, v75
	v_cmp_gt_f32_e32 vcc, s81, v94
	v_mul_f32_e32 v89, 0x3f317217, v70
	v_fma_f32 v89, v70, s65, -v89
	v_cndmask_b32_e64 v96, 0, 32, vcc
	v_ldexp_f32 v94, v94, v96
	v_log_f32_e32 v94, v94
	v_fmac_f32_e32 v89, 0x3377d1cf, v70
	v_fmac_f32_e32 v89, 0x3f317217, v70
	v_cmp_lt_f32_e64 s[6:7], |v70|, s56
	v_mul_f32_e32 v103, v67, v88
	v_max_f32_e32 v67, v72, v72
	v_cndmask_b32_e64 v70, v70, v89, s[6:7]
	v_cndmask_b32_e64 v89, 0, v203, s[4:5]
	v_sub_f32_e32 v101, v70, v89
	v_mul_f32_e32 v70, 0x3f317217, v94
	v_fma_f32 v70, v94, s65, -v70
	v_fmac_f32_e32 v70, 0x3377d1cf, v94
	v_fmac_f32_e32 v70, 0x3f317217, v94
	v_cmp_lt_f32_e64 s[4:5], |v94|, s56
	v_cndmask_b32_e32 v89, 0, v203, vcc
	v_mul_f32_e64 v88, |v68|, s82
	v_cndmask_b32_e64 v70, v94, v70, s[4:5]
	v_sub_f32_e32 v102, v70, v89
	v_add_f32_e32 v70, 1.0, v71
	v_mul_f32_e64 v71, |v72|, s82
	v_rcp_f32_e32 v70, v70
	v_exp_f32_e32 v71, v71
	v_exp_f32_e32 v89, v88
	v_sub_f32_e32 v97, 1.0, v80
	v_mul_f32_e32 v98, v70, v98
	v_add_f32_e32 v70, 1.0, v71
	v_cmp_gt_f32_e32 vcc, s81, v70
	s_nop 1
	v_cndmask_b32_e64 v71, 0, 32, vcc
	v_ldexp_f32 v70, v70, v71
	v_log_f32_e32 v71, v70
	v_min_f32_e32 v70, 0, v67
	v_mul_f32_e32 v67, 0x3f317217, v71
	v_fma_f32 v67, v71, s65, -v67
	v_fmac_f32_e32 v67, 0x3377d1cf, v71
	v_fmac_f32_e32 v67, 0x3f317217, v71
	v_cmp_lt_f32_e64 s[4:5], |v71|, s56
	s_nop 1
	v_cndmask_b32_e64 v67, v71, v67, s[4:5]
	v_cndmask_b32_e32 v71, 0, v203, vcc
	v_sub_f32_e32 v88, v67, v71
	v_add_f32_e32 v67, 1.0, v89
	v_cmp_gt_f32_e32 vcc, s81, v67
	s_nop 1
	v_cndmask_b32_e64 v71, 0, 32, vcc
	v_ldexp_f32 v67, v67, v71
	v_log_f32_e32 v67, v67
	v_max_f32_e32 v71, v68, v68
	v_min_f32_e32 v94, 0, v71
	v_mul_f32_e32 v68, 0x3fb8aa3b, v68
	v_mul_f32_e32 v71, 0x3f317217, v67
	v_fma_f32 v71, v67, s65, -v71
	v_fmac_f32_e32 v71, 0x3377d1cf, v67
	v_fmac_f32_e32 v71, 0x3f317217, v67
	v_cmp_lt_f32_e64 s[4:5], |v67|, s56
	v_exp_f32_e32 v68, v68
	s_nop 0
	v_cndmask_b32_e64 v67, v67, v71, s[4:5]
	v_cndmask_b32_e32 v71, 0, v203, vcc
	v_sub_f32_e32 v96, v67, v71
	v_mul_f32_e64 v71, |v73|, s82
	v_exp_f32_e32 v71, v71
	v_mul_f32_e32 v67, 0x3fb8aa3b, v72
	v_exp_f32_e32 v67, v67
	v_add_f32_e32 v68, 1.0, v68
	v_add_f32_e32 v71, 1.0, v71
	v_cmp_gt_f32_e32 vcc, s81, v71
	v_add_f32_e32 v67, 1.0, v67
	v_rcp_f32_e32 v67, v67
	v_cndmask_b32_e64 v89, 0, 32, vcc
	v_ldexp_f32 v71, v71, v89
	v_log_f32_e32 v89, v71
	v_max_f32_e32 v71, v73, v73
	v_min_f32_e32 v71, 0, v71
	v_mul_f32_e32 v67, v67, v97
	v_mul_f32_e32 v104, 0x3f317217, v89
	v_fma_f32 v104, v89, s65, -v104
	v_fmac_f32_e32 v104, 0x3377d1cf, v89
	v_fmac_f32_e32 v104, 0x3f317217, v89
	v_cmp_lt_f32_e64 s[4:5], |v89|, s56
	v_rcp_f32_e32 v68, v68
	v_sub_f32_e32 v72, 1.0, v76
	v_cndmask_b32_e64 v89, v89, v104, s[4:5]
	v_cndmask_b32_e32 v104, 0, v203, vcc
	v_sub_f32_e32 v89, v89, v104
	v_pk_add_f32 v[70:71], v[70:71], v[88:89] neg_lo:[0,1] neg_hi:[0,1]
	v_sub_f32_e32 v104, 1.0, v81
	v_mul_f32_e32 v88, 0x3fb8aa3b, v70
	v_exp_f32_e32 v88, v88
	s_nop 0
	v_fma_f32 v88, v88, v97, v80
	v_mul_f32_e32 v97, 0x3fb8aa3b, v71
	v_cmp_gt_f32_e32 vcc, s81, v88
	v_exp_f32_e32 v97, v97
	s_nop 0
	v_cndmask_b32_e64 v89, 0, 32, vcc
	v_ldexp_f32 v88, v88, v89
	v_log_f32_e32 v88, v88
	v_fma_f32 v97, v97, v104, v81
	v_cmp_gt_f32_e64 s[4:5], s81, v97
	v_mul_f32_e32 v89, v68, v72
	v_mul_f32_e32 v68, 0x3f317217, v88
	v_cndmask_b32_e64 v105, 0, 32, s[4:5]
	v_ldexp_f32 v97, v97, v105
	v_fma_f32 v68, v88, s65, -v68
	v_log_f32_e32 v97, v97
	v_fmac_f32_e32 v68, 0x3377d1cf, v88
	v_fmac_f32_e32 v68, 0x3f317217, v88
	v_cmp_lt_f32_e64 s[6:7], |v88|, s56
	v_mul_f32_e64 v105, |v69|, s82
	v_exp_f32_e32 v105, v105
	v_cndmask_b32_e64 v68, v88, v68, s[6:7]
	v_cndmask_b32_e32 v88, 0, v203, vcc
	v_sub_f32_e32 v68, v68, v88
	v_mul_f32_e32 v88, 0x3f317217, v97
	v_fma_f32 v88, v97, s65, -v88
	v_fmac_f32_e32 v88, 0x3377d1cf, v97
	v_fmac_f32_e32 v88, 0x3f317217, v97
	v_cmp_lt_f32_e64 vcc, |v97|, s56
	s_nop 1
	v_cndmask_b32_e32 v88, v97, v88, vcc
	v_cmp_lt_f32_e32 vcc, 0, v79
	v_cndmask_b32_e64 v97, 0, v203, s[4:5]
	v_cmp_lt_f32_e64 s[4:5], 0, v78
	v_cndmask_b32_e32 v79, v85, v95, vcc
	v_add_f32_e32 v85, 1.0, v105
	v_cmp_gt_f32_e32 vcc, s81, v85
	v_cndmask_b32_e64 v78, v84, v100, s[4:5]
	v_max_f32_e32 v84, v69, v69
	v_cndmask_b32_e64 v95, 0, 32, vcc
	v_ldexp_f32 v85, v85, v95
	v_log_f32_e32 v85, v85
	v_min_f32_e32 v95, 0, v84
	v_sub_f32_e32 v88, v88, v97
	v_mul_f32_e32 v69, 0x3fb8aa3b, v69
	v_mul_f32_e32 v84, 0x3f317217, v85
	v_fma_f32 v84, v85, s65, -v84
	v_fmac_f32_e32 v84, 0x3377d1cf, v85
	v_fmac_f32_e32 v84, 0x3f317217, v85
	v_cmp_lt_f32_e64 s[4:5], |v85|, s56
	v_exp_f32_e32 v69, v69
	v_pk_mul_f32 v[78:79], v[78:79], s[68:69] op_sel_hi:[1,0]
	v_cndmask_b32_e64 v84, v85, v84, s[4:5]
	v_cndmask_b32_e32 v85, 0, v203, vcc
	v_sub_f32_e32 v97, v84, v85
	v_pk_add_f32 v[84:85], v[94:95], v[96:97] neg_lo:[0,1] neg_hi:[0,1]
	v_cmp_lt_f32_e32 vcc, 0, v81
	v_mul_f32_e32 v94, 0x3fb8aa3b, v84
	v_exp_f32_e32 v94, v94
	v_cndmask_b32_e32 v71, v71, v88, vcc
	v_cmp_lt_f32_e32 vcc, 0, v80
	s_nop 1
	v_cndmask_b32_e32 v70, v70, v68, vcc
	v_fma_f32 v68, v94, v72, v76
	v_pk_mul_f32 v[80:81], v[70:71], s[68:69] op_sel_hi:[1,0]
	v_mul_f32_e32 v71, 0x3fb8aa3b, v85
	v_cmp_gt_f32_e32 vcc, s81, v68
	v_exp_f32_e32 v71, v71
	s_nop 0
	v_cndmask_b32_e64 v72, 0, 32, vcc
	v_ldexp_f32 v68, v68, v72
	v_log_f32_e32 v68, v68
	v_sub_f32_e32 v72, 1.0, v77
	v_fma_f32 v71, v71, v72, v77
	v_cmp_gt_f32_e64 s[4:5], s81, v71
	v_mul_f32_e32 v70, 0x3f317217, v68
	v_fma_f32 v70, v68, s65, -v70
	v_cndmask_b32_e64 v88, 0, 32, s[4:5]
	v_ldexp_f32 v71, v71, v88
	v_log_f32_e32 v71, v71
	v_fmac_f32_e32 v70, 0x3377d1cf, v68
	v_fmac_f32_e32 v70, 0x3f317217, v68
	v_cmp_lt_f32_e64 s[6:7], |v68|, s56
	s_nop 1
	v_cndmask_b32_e64 v68, v68, v70, s[6:7]
	v_cndmask_b32_e32 v70, 0, v203, vcc
	v_sub_f32_e32 v68, v68, v70
	v_mul_f32_e32 v70, 0x3f317217, v71
	v_fma_f32 v70, v71, s65, -v70
	v_fmac_f32_e32 v70, 0x3377d1cf, v71
	v_fmac_f32_e32 v70, 0x3f317217, v71
	v_cmp_lt_f32_e64 vcc, |v71|, s56
	s_nop 1
	v_cndmask_b32_e32 v70, v71, v70, vcc
	v_cmp_lt_f32_e32 vcc, 0, v75
	v_cndmask_b32_e64 v71, 0, v203, s[4:5]
	v_sub_f32_e32 v70, v70, v71
	v_cndmask_b32_e32 v75, v87, v102, vcc
	v_cmp_lt_f32_e32 vcc, 0, v74
	s_nop 1
	v_cndmask_b32_e32 v74, v86, v101, vcc
	v_cmp_lt_f32_e32 vcc, 0, v77
	s_nop 1
	v_cndmask_b32_e32 v71, v85, v70, vcc
	v_mul_f32_e32 v70, 0x3fb8aa3b, v73
	v_exp_f32_e32 v73, v70
	v_cmp_lt_f32_e32 vcc, 0, v76
	s_nop 1
	v_cndmask_b32_e32 v70, v84, v68, vcc
	v_add_f32_e32 v68, 1.0, v73
	v_rcp_f32_e32 v73, v68
	v_add_f32_e32 v68, 1.0, v69
	v_rcp_f32_e32 v76, v68
	v_pk_mul_f32 v[70:71], v[70:71], s[68:69] op_sel_hi:[1,0]
	v_pk_mul_f32 v[68:69], v[74:75], s[68:69] op_sel_hi:[1,0]
	v_mul_f32_e32 v74, v73, v104
	v_mul_f32_e32 v75, v76, v72
	v_lshl_add_u64 v[72:73], v[92:93], 0, v[82:83]
	global_store_dwordx4 v[72:73], v[78:81], off
	global_store_dwordx4 v[72:73], v[68:71], off offset:16
	v_cvt_pk_bf16_f32 v66, v66, v98
	v_cvt_pk_bf16_f32 v67, v67, v74
	s_nop 1
	v_lshl_add_u64 v[70:71], v[148:149], 1, v[90:91]
	v_cvt_pk_bf16_f32 v68, v99, v103
	v_cvt_pk_bf16_f32 v69, v89, v75
	global_store_dwordx4 v[70:71], v[66:69], off offset:256
	s_and_b64 vcc, exec, s[90:91]
	s_cbranch_vccz .LBB0_496

.LBB0_514:
	v_ashrrev_i32_e32 v77, 31, v76
	s_nop 0
	v_lshlrev_b64 v[66:67], 11, v[76:77]
	s_and_b64 vcc, exec, s[0:1]
	v_lshl_add_u64 v[74:75], s[10:11], 0, v[74:75]
	v_lshl_add_u64 v[76:77], v[66:67], 2, s[12:13]
	s_cbranch_vccz .LBB0_516
	v_lshl_add_u64 v[80:81], v[148:149], 2, s[2:3]
	v_lshl_add_u64 v[66:67], s[14:15], 0, v[80:81]
	v_mov_b32_e32 v70, v206
	v_mov_b32_e32 v71, v207
	v_mov_b32_e32 v72, v208
	v_mov_b32_e32 v73, v209
	v_mov_b32_e32 v66, v210
	v_mov_b32_e32 v67, v211
	v_mov_b32_e32 v68, v212
	v_mov_b32_e32 v69, v213
	v_max_f32_e32 v79, v62, v62
	v_mul_f32_e64 v83, |v62|, s82
	v_mul_f32_e64 v85, |v58|, s82
	v_min_f32_e32 v82, 0, v79
	v_exp_f32_e32 v79, v83
	v_max_f32_e32 v86, v63, v63
	v_mul_f32_e64 v87, |v63|, s82
	v_mul_f32_e64 v88, |v59|, s82
	v_exp_f32_e32 v85, v85
	v_max_f32_e32 v84, v58, v58
	v_mul_f32_e32 v58, 0x3fb8aa3b, v58
	v_min_f32_e32 v83, 0, v86
	v_exp_f32_e32 v86, v87
	v_exp_f32_e32 v87, v88
	v_exp_f32_e32 v58, v58
	v_add_f32_e32 v79, 1.0, v79
	v_add_f32_e32 v85, 1.0, v85
	v_cmp_gt_f32_e32 vcc, s81, v79
	v_add_f32_e32 v86, 1.0, v86
	v_add_f32_e32 v89, 1.0, v87
	v_cndmask_b32_e64 v87, 0, 32, vcc
	v_cmp_gt_f32_e64 s[4:5], s81, v85
	v_add_f32_e32 v58, 1.0, v58
	v_cmp_gt_f32_e64 s[6:7], s81, v86
	v_cndmask_b32_e64 v88, 0, 32, s[4:5]
	v_ldexp_f32 v79, v79, v87
	v_rcp_f32_e32 v90, v58
	v_cndmask_b32_e64 v58, 0, 32, s[6:7]
	v_ldexp_f32 v85, v85, v88
	v_log_f32_e32 v79, v79
	v_ldexp_f32 v58, v86, v58
	v_log_f32_e32 v85, v85
	v_log_f32_e32 v58, v58
	v_mul_f32_e32 v86, 0x3f317217, v79
	v_fma_f32 v86, v79, s65, -v86
	v_mul_f32_e32 v92, 0x3f317217, v85
	v_mul_f32_e32 v93, 0x3f317217, v58
	v_fma_f32 v92, v85, s65, -v92
	v_fmac_f32_e32 v86, 0x3377d1cf, v79
	v_cndmask_b32_e32 v87, 0, v203, vcc
	v_fma_f32 v93, v58, s65, -v93
	v_fmac_f32_e32 v92, 0x3377d1cf, v85
	v_fmac_f32_e32 v86, 0x3f317217, v79
	v_cmp_lt_f32_e64 vcc, |v79|, s56
	v_mul_f32_e32 v62, 0x3fb8aa3b, v62
	v_fmac_f32_e32 v93, 0x3377d1cf, v58
	v_fmac_f32_e32 v92, 0x3f317217, v85
	v_cndmask_b32_e32 v79, v79, v86, vcc
	v_cmp_lt_f32_e64 vcc, |v85|, s56
	v_exp_f32_e32 v62, v62
	v_fmac_f32_e32 v93, 0x3f317217, v58
	v_cndmask_b32_e32 v85, v85, v92, vcc
	v_cmp_lt_f32_e64 vcc, |v58|, s56
	v_cndmask_b32_e64 v91, 0, v203, s[6:7]
	v_sub_f32_e32 v86, v79, v87
	v_cndmask_b32_e32 v58, v58, v93, vcc
	v_sub_f32_e32 v87, v58, v91
	v_pk_add_f32 v[82:83], v[82:83], v[86:87] neg_lo:[0,1] neg_hi:[0,1]
	v_add_f32_e32 v62, 1.0, v62
	v_cndmask_b32_e64 v88, 0, v203, s[4:5]
	v_mul_f32_e32 v58, 0x3fb8aa3b, v82
	v_rcp_f32_e32 v62, v62
	v_sub_f32_e32 v88, v85, v88
	v_exp_f32_e32 v85, v58
	v_mul_f32_e32 v79, 0x3fb8aa3b, v83
	v_exp_f32_e32 v79, v79
	v_min_f32_e32 v84, 0, v84
	v_mul_f32_e32 v63, 0x3fb8aa3b, v63
	v_exp_f32_e32 v63, v63
	v_sub_f32_e32 v86, 1.0, v70
	v_mul_f32_e32 v58, v62, v86
	v_fma_f32 v62, v85, v86, v70
	v_cmp_gt_f32_e64 s[4:5], s81, v62
	v_sub_f32_e32 v91, 1.0, v71
	v_fma_f32 v79, v79, v91, v71
	v_cndmask_b32_e64 v85, 0, 32, s[4:5]
	v_ldexp_f32 v62, v62, v85
	v_log_f32_e32 v62, v62
	v_cmp_gt_f32_e32 vcc, s81, v79
	v_cndmask_b32_e64 v85, 0, v203, s[4:5]
	v_sub_f32_e32 v87, 1.0, v66
	v_cndmask_b32_e64 v86, 0, 32, vcc
	v_ldexp_f32 v79, v79, v86
	v_mul_f32_e32 v86, 0x3f317217, v62
	v_fma_f32 v86, v62, s65, -v86
	v_fmac_f32_e32 v86, 0x3377d1cf, v62
	v_fmac_f32_e32 v86, 0x3f317217, v62
	v_cmp_lt_f32_e64 s[4:5], |v62|, s56
	v_log_f32_e32 v79, v79
	v_mul_f32_e32 v92, v90, v87
	v_cndmask_b32_e64 v62, v62, v86, s[4:5]
	v_cmp_gt_f32_e64 s[4:5], s81, v89
	v_sub_f32_e32 v93, v62, v85
	v_max_f32_e32 v85, v59, v59
	v_cndmask_b32_e64 v62, 0, 32, s[4:5]
	v_ldexp_f32 v62, v89, v62
	v_log_f32_e32 v62, v62
	v_min_f32_e32 v85, 0, v85
	v_mul_f32_e32 v90, 0x3f317217, v79
	v_fma_f32 v90, v79, s65, -v90
	v_mul_f32_e32 v86, 0x3f317217, v62
	v_fma_f32 v86, v62, s65, -v86
	v_fmac_f32_e32 v86, 0x3377d1cf, v62
	v_fmac_f32_e32 v86, 0x3f317217, v62
	v_cmp_lt_f32_e64 s[6:7], |v62|, s56
	v_fmac_f32_e32 v90, 0x3377d1cf, v79
	v_fmac_f32_e32 v90, 0x3f317217, v79
	v_cndmask_b32_e64 v62, v62, v86, s[6:7]
	v_cndmask_b32_e64 v86, 0, v203, s[4:5]
	v_sub_f32_e32 v89, v62, v86
	v_pk_add_f32 v[84:85], v[84:85], v[88:89] neg_lo:[0,1] neg_hi:[0,1]
	v_cmp_lt_f32_e64 s[4:5], |v79|, s56
	v_mul_f32_e32 v62, 0x3fb8aa3b, v84
	v_exp_f32_e32 v62, v62
	v_mul_f32_e32 v88, 0x3fb8aa3b, v85
	v_cndmask_b32_e64 v79, v79, v90, s[4:5]
	v_exp_f32_e32 v88, v88
	v_fma_f32 v62, v62, v87, v66
	v_cmp_gt_f32_e64 s[4:5], s81, v62
	v_mul_f32_e32 v59, 0x3fb8aa3b, v59
	v_exp_f32_e32 v59, v59
	v_cndmask_b32_e64 v86, 0, 32, s[4:5]
	v_ldexp_f32 v62, v62, v86
	v_cndmask_b32_e32 v86, 0, v203, vcc
	v_log_f32_e32 v62, v62
	v_sub_f32_e32 v79, v79, v86
	v_sub_f32_e32 v86, 1.0, v67
	v_fma_f32 v88, v88, v86, v67
	v_cmp_gt_f32_e32 vcc, s81, v88
	v_mul_f32_e32 v87, 0x3f317217, v62
	v_fma_f32 v87, v62, s65, -v87
	v_cndmask_b32_e64 v89, 0, 32, vcc
	v_ldexp_f32 v88, v88, v89
	v_log_f32_e32 v88, v88
	v_fmac_f32_e32 v87, 0x3377d1cf, v62
	v_fmac_f32_e32 v87, 0x3f317217, v62
	v_cmp_lt_f32_e64 s[6:7], |v62|, s56
	v_add_f32_e32 v59, 1.0, v59
	v_rcp_f32_e32 v59, v59
	v_cndmask_b32_e64 v62, v62, v87, s[6:7]
	v_cndmask_b32_e64 v87, 0, v203, s[4:5]
	v_sub_f32_e32 v94, v62, v87
	v_mul_f32_e32 v62, 0x3f317217, v88
	v_fma_f32 v62, v88, s65, -v62
	v_fmac_f32_e32 v62, 0x3377d1cf, v88
	v_fmac_f32_e32 v62, 0x3f317217, v88
	v_cmp_lt_f32_e64 s[4:5], |v88|, s56
	v_cndmask_b32_e32 v87, 0, v203, vcc
	v_mul_f32_e32 v97, v59, v86
	v_cndmask_b32_e64 v62, v88, v62, s[4:5]
	v_sub_f32_e32 v95, v62, v87
	v_add_f32_e32 v62, 1.0, v63
	v_mul_f32_e64 v63, |v64|, s82
	v_rcp_f32_e32 v62, v62
	v_exp_f32_e32 v63, v63
	v_max_f32_e32 v59, v64, v64
	v_mul_f32_e64 v86, |v60|, s82
	v_mul_f32_e32 v96, v62, v91
	v_add_f32_e32 v62, 1.0, v63
	v_cmp_gt_f32_e32 vcc, s81, v62
	v_exp_f32_e32 v87, v86
	v_sub_f32_e32 v89, 1.0, v72
	v_cndmask_b32_e64 v63, 0, 32, vcc
	v_ldexp_f32 v62, v62, v63
	v_log_f32_e32 v63, v62
	v_min_f32_e32 v62, 0, v59
	v_sub_f32_e32 v98, 1.0, v73
	v_mul_f32_e32 v59, 0x3f317217, v63
	v_fma_f32 v59, v63, s65, -v59
	v_fmac_f32_e32 v59, 0x3377d1cf, v63
	v_fmac_f32_e32 v59, 0x3f317217, v63
	v_cmp_lt_f32_e64 s[4:5], |v63|, s56
	s_nop 1
	v_cndmask_b32_e64 v59, v63, v59, s[4:5]
	v_cndmask_b32_e32 v63, 0, v203, vcc
	v_sub_f32_e32 v86, v59, v63
	v_add_f32_e32 v59, 1.0, v87
	v_cmp_gt_f32_e32 vcc, s81, v59
	s_nop 1
	v_cndmask_b32_e64 v63, 0, 32, vcc
	v_ldexp_f32 v59, v59, v63
	v_log_f32_e32 v59, v59
	v_max_f32_e32 v63, v60, v60
	v_min_f32_e32 v88, 0, v63
	v_mul_f32_e32 v60, 0x3fb8aa3b, v60
	v_mul_f32_e32 v63, 0x3f317217, v59
	v_fma_f32 v63, v59, s65, -v63
	v_fmac_f32_e32 v63, 0x3377d1cf, v59
	v_fmac_f32_e32 v63, 0x3f317217, v59
	v_cmp_lt_f32_e64 s[4:5], |v59|, s56
	v_exp_f32_e32 v60, v60
	s_nop 0
	v_cndmask_b32_e64 v59, v59, v63, s[4:5]
	v_cndmask_b32_e32 v63, 0, v203, vcc
	v_sub_f32_e32 v90, v59, v63
	v_mul_f32_e64 v63, |v65|, s82
	v_exp_f32_e32 v63, v63
	v_mul_f32_e32 v59, 0x3fb8aa3b, v64
	v_exp_f32_e32 v59, v59
	v_add_f32_e32 v60, 1.0, v60
	v_add_f32_e32 v63, 1.0, v63
	v_cmp_gt_f32_e32 vcc, s81, v63
	v_add_f32_e32 v59, 1.0, v59
	v_rcp_f32_e32 v59, v59
	v_cndmask_b32_e64 v87, 0, 32, vcc
	v_ldexp_f32 v63, v63, v87
	v_log_f32_e32 v87, v63
	v_max_f32_e32 v63, v65, v65
	v_min_f32_e32 v63, 0, v63
	v_mul_f32_e32 v59, v59, v89
	v_mul_f32_e32 v91, 0x3f317217, v87
	v_fma_f32 v91, v87, s65, -v91
	v_fmac_f32_e32 v91, 0x3377d1cf, v87
	v_fmac_f32_e32 v91, 0x3f317217, v87
	v_cmp_lt_f32_e64 s[4:5], |v87|, s56
	v_rcp_f32_e32 v60, v60
	v_sub_f32_e32 v64, 1.0, v68
	v_cndmask_b32_e64 v87, v87, v91, s[4:5]
	v_cndmask_b32_e32 v91, 0, v203, vcc
	v_sub_f32_e32 v87, v87, v91
	v_pk_add_f32 v[62:63], v[62:63], v[86:87] neg_lo:[0,1] neg_hi:[0,1]
	s_nop 0
	v_mul_f32_e32 v86, 0x3fb8aa3b, v62
	v_exp_f32_e32 v86, v86
	s_nop 0
	v_fma_f32 v86, v86, v89, v72
	v_mul_f32_e32 v89, 0x3fb8aa3b, v63
	v_cmp_gt_f32_e32 vcc, s81, v86
	v_exp_f32_e32 v89, v89
	s_nop 0
	v_cndmask_b32_e64 v87, 0, 32, vcc
	v_ldexp_f32 v86, v86, v87
	v_log_f32_e32 v86, v86
	v_fma_f32 v89, v89, v98, v73
	v_cmp_gt_f32_e64 s[4:5], s81, v89
	v_mul_f32_e32 v87, v60, v64
	v_mul_f32_e32 v60, 0x3f317217, v86
	v_cndmask_b32_e64 v91, 0, 32, s[4:5]
	v_ldexp_f32 v89, v89, v91
	v_fma_f32 v60, v86, s65, -v60
	v_log_f32_e32 v89, v89
	v_fmac_f32_e32 v60, 0x3377d1cf, v86
	v_fmac_f32_e32 v60, 0x3f317217, v86
	v_cmp_lt_f32_e64 s[6:7], |v86|, s56
	v_mul_f32_e64 v91, |v61|, s82
	v_exp_f32_e32 v91, v91
	v_cndmask_b32_e64 v60, v86, v60, s[6:7]
	v_cndmask_b32_e32 v86, 0, v203, vcc
	v_sub_f32_e32 v60, v60, v86
	v_mul_f32_e32 v86, 0x3f317217, v89
	v_fma_f32 v86, v89, s65, -v86
	v_fmac_f32_e32 v86, 0x3377d1cf, v89
	v_fmac_f32_e32 v86, 0x3f317217, v89
	v_cmp_lt_f32_e64 vcc, |v89|, s56
	s_nop 1
	v_cndmask_b32_e32 v86, v89, v86, vcc
	v_cmp_lt_f32_e32 vcc, 0, v71
	v_cndmask_b32_e64 v89, 0, v203, s[4:5]
	v_cmp_lt_f32_e64 s[4:5], 0, v70
	v_cndmask_b32_e32 v71, v83, v79, vcc
	v_add_f32_e32 v79, 1.0, v91
	v_cmp_gt_f32_e32 vcc, s81, v79
	v_cndmask_b32_e64 v70, v82, v93, s[4:5]
	v_max_f32_e32 v82, v61, v61
	v_cndmask_b32_e64 v83, 0, 32, vcc
	v_ldexp_f32 v79, v79, v83
	v_log_f32_e32 v79, v79
	v_sub_f32_e32 v86, v86, v89
	v_min_f32_e32 v89, 0, v82
	v_mul_f32_e32 v61, 0x3fb8aa3b, v61
	v_mul_f32_e32 v82, 0x3f317217, v79
	v_fma_f32 v82, v79, s65, -v82
	v_fmac_f32_e32 v82, 0x3377d1cf, v79
	v_fmac_f32_e32 v82, 0x3f317217, v79
	v_cmp_lt_f32_e64 s[4:5], |v79|, s56
	v_exp_f32_e32 v61, v61
	v_pk_mul_f32 v[70:71], v[70:71], s[68:69] op_sel_hi:[1,0]
	v_cndmask_b32_e64 v79, v79, v82, s[4:5]
	v_cndmask_b32_e32 v82, 0, v203, vcc
	v_sub_f32_e32 v91, v79, v82
	v_pk_add_f32 v[82:83], v[88:89], v[90:91] neg_lo:[0,1] neg_hi:[0,1]
	v_cmp_lt_f32_e32 vcc, 0, v73
	v_mul_f32_e32 v79, 0x3fb8aa3b, v82
	v_exp_f32_e32 v79, v79
	v_cndmask_b32_e32 v63, v63, v86, vcc
	v_cmp_lt_f32_e32 vcc, 0, v72
	s_nop 1
	v_cndmask_b32_e32 v62, v62, v60, vcc
	v_fma_f32 v60, v79, v64, v68
	v_pk_mul_f32 v[72:73], v[62:63], s[68:69] op_sel_hi:[1,0]
	v_mul_f32_e32 v63, 0x3fb8aa3b, v83
	v_cmp_gt_f32_e32 vcc, s81, v60
	v_exp_f32_e32 v63, v63
	s_nop 0
	v_cndmask_b32_e64 v64, 0, 32, vcc
	v_ldexp_f32 v60, v60, v64
	v_log_f32_e32 v60, v60
	v_sub_f32_e32 v64, 1.0, v69
	v_fma_f32 v63, v63, v64, v69
	v_cmp_gt_f32_e64 s[4:5], s81, v63
	v_mul_f32_e32 v62, 0x3f317217, v60
	v_fma_f32 v62, v60, s65, -v62
	v_cndmask_b32_e64 v79, 0, 32, s[4:5]
	v_ldexp_f32 v63, v63, v79
	v_log_f32_e32 v63, v63
	v_fmac_f32_e32 v62, 0x3377d1cf, v60
	v_fmac_f32_e32 v62, 0x3f317217, v60
	v_cmp_lt_f32_e64 s[6:7], |v60|, s56
	s_nop 1
	v_cndmask_b32_e64 v60, v60, v62, s[6:7]
	v_cndmask_b32_e32 v62, 0, v203, vcc
	v_sub_f32_e32 v60, v60, v62
	v_mul_f32_e32 v62, 0x3f317217, v63
	v_fma_f32 v62, v63, s65, -v62
	v_fmac_f32_e32 v62, 0x3377d1cf, v63
	v_fmac_f32_e32 v62, 0x3f317217, v63
	v_cmp_lt_f32_e64 vcc, |v63|, s56
	s_nop 1
	v_cndmask_b32_e32 v62, v63, v62, vcc
	v_cmp_lt_f32_e32 vcc, 0, v67
	v_cndmask_b32_e64 v63, 0, v203, s[4:5]
	v_sub_f32_e32 v62, v62, v63
	v_cndmask_b32_e32 v67, v85, v95, vcc
	v_cmp_lt_f32_e32 vcc, 0, v66
	s_nop 1
	v_cndmask_b32_e32 v66, v84, v94, vcc
	v_cmp_lt_f32_e32 vcc, 0, v69
	s_nop 1
	v_cndmask_b32_e32 v63, v83, v62, vcc
	v_mul_f32_e32 v62, 0x3fb8aa3b, v65
	v_exp_f32_e32 v65, v62
	v_cmp_lt_f32_e32 vcc, 0, v68
	s_nop 1
	v_cndmask_b32_e32 v62, v82, v60, vcc
	v_add_f32_e32 v60, 1.0, v65
	v_rcp_f32_e32 v65, v60
	v_add_f32_e32 v60, 1.0, v61
	v_rcp_f32_e32 v68, v60
	v_pk_mul_f32 v[62:63], v[62:63], s[68:69] op_sel_hi:[1,0]
	v_pk_mul_f32 v[60:61], v[66:67], s[68:69] op_sel_hi:[1,0]
	v_mul_f32_e32 v66, v65, v98
	v_mul_f32_e32 v67, v68, v64
	v_lshl_add_u64 v[64:65], v[76:77], 0, v[80:81]
	global_store_dwordx4 v[64:65], v[70:73], off
	global_store_dwordx4 v[64:65], v[60:63], off offset:16
	v_cvt_pk_bf16_f32 v58, v58, v96
	v_cvt_pk_bf16_f32 v59, v59, v66
	s_nop 1
	v_lshl_add_u64 v[62:63], v[148:149], 1, v[74:75]
	v_cvt_pk_bf16_f32 v60, v92, v97
	v_cvt_pk_bf16_f32 v61, v87, v67
	global_store_dwordx4 v[62:63], v[58:61], off

.LBB0_527:
	v_lshl_add_u64 v[66:67], v[148:149], 2, s[26:27]
	v_lshl_add_u64 v[58:59], s[14:15], 0, v[66:67]
	v_mov_b32_e32 v62, v214
	v_mov_b32_e32 v63, v215
	v_mov_b32_e32 v64, v216
	v_mov_b32_e32 v65, v217
	v_mov_b32_e32 v58, v218
	v_mov_b32_e32 v59, v219
	v_mov_b32_e32 v60, v220
	v_mov_b32_e32 v61, v221
	v_mul_f32_e64 v69, |v54|, s82
	v_mul_f32_e64 v71, |v50|, s82
	v_max_f32_e32 v72, v55, v55
	v_mul_f32_e64 v73, |v55|, s82
	v_exp_f32_e32 v79, v69
	v_max_f32_e32 v70, v50, v50
	v_mul_f32_e32 v50, 0x3fb8aa3b, v50
	v_mul_f32_e64 v78, |v51|, s82
	v_exp_f32_e32 v71, v71
	v_min_f32_e32 v69, 0, v72
	v_exp_f32_e32 v72, v73
	v_exp_f32_e32 v50, v50
	v_exp_f32_e32 v73, v78
	v_add_f32_e32 v78, 1.0, v79
	v_add_f32_e32 v71, 1.0, v71
	v_add_f32_e32 v72, 1.0, v72
	v_cmp_gt_f32_e32 vcc, s81, v78
	v_add_f32_e32 v50, 1.0, v50
	v_add_f32_e32 v79, 1.0, v73
	v_cndmask_b32_e64 v73, 0, 32, vcc
	v_cmp_gt_f32_e64 s[4:5], s81, v71
	v_cmp_gt_f32_e64 s[6:7], s81, v72
	v_rcp_f32_e32 v81, v50
	v_cndmask_b32_e64 v80, 0, 32, s[4:5]
	v_cndmask_b32_e64 v50, 0, 32, s[6:7]
	v_ldexp_f32 v73, v78, v73
	v_ldexp_f32 v71, v71, v80
	v_ldexp_f32 v50, v72, v50
	v_log_f32_e32 v72, v73
	v_log_f32_e32 v71, v71
	v_log_f32_e32 v50, v50
	v_cndmask_b32_e32 v78, 0, v203, vcc
	v_mul_f32_e32 v82, 0x3f317217, v72
	v_mul_f32_e32 v83, 0x3f317217, v71
	v_fma_f32 v82, v72, s65, -v82
	v_mul_f32_e32 v84, 0x3f317217, v50
	v_fma_f32 v83, v71, s65, -v83
	v_fmac_f32_e32 v82, 0x3377d1cf, v72
	v_fma_f32 v84, v50, s65, -v84
	v_fmac_f32_e32 v83, 0x3377d1cf, v71
	v_fmac_f32_e32 v82, 0x3f317217, v72
	v_cmp_lt_f32_e64 vcc, |v72|, s56
	v_max_f32_e32 v68, v54, v54
	v_mul_f32_e32 v54, 0x3fb8aa3b, v54
	v_fmac_f32_e32 v84, 0x3377d1cf, v50
	v_fmac_f32_e32 v83, 0x3f317217, v71
	v_cndmask_b32_e32 v72, v72, v82, vcc
	v_cmp_lt_f32_e64 vcc, |v71|, s56
	v_exp_f32_e32 v54, v54
	v_fmac_f32_e32 v84, 0x3f317217, v50
	v_cndmask_b32_e32 v71, v71, v83, vcc
	v_cmp_lt_f32_e64 vcc, |v50|, s56
	v_cndmask_b32_e64 v73, 0, v203, s[6:7]
	v_min_f32_e32 v68, 0, v68
	v_cndmask_b32_e32 v50, v50, v84, vcc
	v_sub_f32_e32 v72, v72, v78
	v_sub_f32_e32 v73, v50, v73
	v_pk_add_f32 v[68:69], v[68:69], v[72:73] neg_lo:[0,1] neg_hi:[0,1]
	v_add_f32_e32 v54, 1.0, v54
	v_mul_f32_e32 v50, 0x3fb8aa3b, v68
	v_rcp_f32_e32 v54, v54
	v_exp_f32_e32 v72, v50
	v_cndmask_b32_e64 v80, 0, v203, s[4:5]
	v_sub_f32_e32 v78, v71, v80
	v_mul_f32_e32 v71, 0x3fb8aa3b, v69
	v_exp_f32_e32 v71, v71
	v_min_f32_e32 v70, 0, v70
	v_mul_f32_e32 v55, 0x3fb8aa3b, v55
	v_exp_f32_e32 v55, v55
	v_sub_f32_e32 v73, 1.0, v62
	v_mul_f32_e32 v50, v54, v73
	v_fma_f32 v54, v72, v73, v62
	v_cmp_gt_f32_e64 s[4:5], s81, v54
	v_sub_f32_e32 v82, 1.0, v63
	v_fma_f32 v71, v71, v82, v63
	v_cndmask_b32_e64 v72, 0, 32, s[4:5]
	v_ldexp_f32 v54, v54, v72
	v_log_f32_e32 v54, v54
	v_cmp_gt_f32_e32 vcc, s81, v71
	v_sub_f32_e32 v80, 1.0, v58
	v_mul_f32_e32 v83, v81, v80
	v_cndmask_b32_e64 v73, 0, 32, vcc
	v_ldexp_f32 v71, v71, v73
	v_mul_f32_e32 v73, 0x3f317217, v54
	v_fma_f32 v73, v54, s65, -v73
	v_fmac_f32_e32 v73, 0x3377d1cf, v54
	v_log_f32_e32 v72, v71
	v_cndmask_b32_e64 v71, 0, v203, s[4:5]
	v_fmac_f32_e32 v73, 0x3f317217, v54
	v_cmp_lt_f32_e64 s[4:5], |v54|, s56
	v_mul_f32_e32 v81, 0x3f317217, v72
	v_fma_f32 v81, v72, s65, -v81
	v_cndmask_b32_e64 v54, v54, v73, s[4:5]
	v_cmp_gt_f32_e64 s[4:5], s81, v79
	v_sub_f32_e32 v84, v54, v71
	v_max_f32_e32 v71, v51, v51
	v_cndmask_b32_e64 v54, 0, 32, s[4:5]
	v_ldexp_f32 v54, v79, v54
	v_log_f32_e32 v54, v54
	v_min_f32_e32 v71, 0, v71
	v_fmac_f32_e32 v81, 0x3377d1cf, v72
	v_fmac_f32_e32 v81, 0x3f317217, v72
	v_mul_f32_e32 v73, 0x3f317217, v54
	v_fma_f32 v73, v54, s65, -v73
	v_fmac_f32_e32 v73, 0x3377d1cf, v54
	v_fmac_f32_e32 v73, 0x3f317217, v54
	v_cmp_lt_f32_e64 s[6:7], |v54|, s56
	v_mul_f32_e32 v51, 0x3fb8aa3b, v51
	v_exp_f32_e32 v51, v51
	v_cndmask_b32_e64 v54, v54, v73, s[6:7]
	v_cndmask_b32_e64 v73, 0, v203, s[4:5]
	v_sub_f32_e32 v79, v54, v73
	v_pk_add_f32 v[70:71], v[70:71], v[78:79] neg_lo:[0,1] neg_hi:[0,1]
	v_cmp_lt_f32_e64 s[4:5], |v72|, s56
	v_mul_f32_e32 v54, 0x3fb8aa3b, v70
	v_exp_f32_e32 v54, v54
	v_mul_f32_e32 v78, 0x3fb8aa3b, v71
	v_cndmask_b32_e64 v72, v72, v81, s[4:5]
	v_exp_f32_e32 v78, v78
	v_fma_f32 v54, v54, v80, v58
	v_cmp_gt_f32_e64 s[4:5], s81, v54
	v_add_f32_e32 v51, 1.0, v51
	v_rcp_f32_e32 v51, v51
	v_cndmask_b32_e64 v73, 0, 32, s[4:5]
	v_ldexp_f32 v54, v54, v73
	v_cndmask_b32_e32 v73, 0, v203, vcc
	v_log_f32_e32 v54, v54
	v_sub_f32_e32 v79, v72, v73
	v_sub_f32_e32 v72, 1.0, v59
	v_fma_f32 v78, v78, v72, v59
	v_cmp_gt_f32_e32 vcc, s81, v78
	v_mul_f32_e32 v73, 0x3f317217, v54
	v_fma_f32 v73, v54, s65, -v73
	v_cndmask_b32_e64 v80, 0, 32, vcc
	v_ldexp_f32 v78, v78, v80
	v_log_f32_e32 v78, v78
	v_fmac_f32_e32 v73, 0x3377d1cf, v54
	v_fmac_f32_e32 v73, 0x3f317217, v54
	v_cmp_lt_f32_e64 s[6:7], |v54|, s56
	v_mul_f32_e32 v87, v51, v72
	v_max_f32_e32 v51, v56, v56
	v_cndmask_b32_e64 v54, v54, v73, s[6:7]
	v_cndmask_b32_e64 v73, 0, v203, s[4:5]
	v_sub_f32_e32 v85, v54, v73
	v_mul_f32_e32 v54, 0x3f317217, v78
	v_fma_f32 v54, v78, s65, -v54
	v_fmac_f32_e32 v54, 0x3377d1cf, v78
	v_fmac_f32_e32 v54, 0x3f317217, v78
	v_cmp_lt_f32_e64 s[4:5], |v78|, s56
	v_cndmask_b32_e32 v73, 0, v203, vcc
	v_mul_f32_e64 v72, |v52|, s82
	v_cndmask_b32_e64 v54, v78, v54, s[4:5]
	v_sub_f32_e32 v86, v54, v73
	v_add_f32_e32 v54, 1.0, v55
	v_mul_f32_e64 v55, |v56|, s82
	v_rcp_f32_e32 v54, v54
	v_exp_f32_e32 v55, v55
	v_exp_f32_e32 v73, v72
	v_sub_f32_e32 v81, 1.0, v64
	v_mul_f32_e32 v82, v54, v82
	v_add_f32_e32 v54, 1.0, v55
	v_cmp_gt_f32_e32 vcc, s81, v54
	s_nop 1
	v_cndmask_b32_e64 v55, 0, 32, vcc
	v_ldexp_f32 v54, v54, v55
	v_log_f32_e32 v55, v54
	v_min_f32_e32 v54, 0, v51
	v_mul_f32_e32 v51, 0x3f317217, v55
	v_fma_f32 v51, v55, s65, -v51
	v_fmac_f32_e32 v51, 0x3377d1cf, v55
	v_fmac_f32_e32 v51, 0x3f317217, v55
	v_cmp_lt_f32_e64 s[4:5], |v55|, s56
	s_nop 1
	v_cndmask_b32_e64 v51, v55, v51, s[4:5]
	v_cndmask_b32_e32 v55, 0, v203, vcc
	v_sub_f32_e32 v72, v51, v55
	v_add_f32_e32 v51, 1.0, v73
	v_cmp_gt_f32_e32 vcc, s81, v51
	s_nop 1
	v_cndmask_b32_e64 v55, 0, 32, vcc
	v_ldexp_f32 v51, v51, v55
	v_log_f32_e32 v51, v51
	v_max_f32_e32 v55, v52, v52
	v_min_f32_e32 v78, 0, v55
	v_mul_f32_e32 v52, 0x3fb8aa3b, v52
	v_mul_f32_e32 v55, 0x3f317217, v51
	v_fma_f32 v55, v51, s65, -v55
	v_fmac_f32_e32 v55, 0x3377d1cf, v51
	v_fmac_f32_e32 v55, 0x3f317217, v51
	v_cmp_lt_f32_e64 s[4:5], |v51|, s56
	v_exp_f32_e32 v52, v52
	s_nop 0
	v_cndmask_b32_e64 v51, v51, v55, s[4:5]
	v_cndmask_b32_e32 v55, 0, v203, vcc
	v_sub_f32_e32 v80, v51, v55
	v_mul_f32_e64 v55, |v57|, s82
	v_exp_f32_e32 v55, v55
	v_mul_f32_e32 v51, 0x3fb8aa3b, v56
	v_exp_f32_e32 v51, v51
	v_add_f32_e32 v52, 1.0, v52
	v_add_f32_e32 v55, 1.0, v55
	v_cmp_gt_f32_e32 vcc, s81, v55
	v_add_f32_e32 v51, 1.0, v51
	v_rcp_f32_e32 v51, v51
	v_cndmask_b32_e64 v73, 0, 32, vcc
	v_ldexp_f32 v55, v55, v73
	v_log_f32_e32 v73, v55
	v_max_f32_e32 v55, v57, v57
	v_min_f32_e32 v55, 0, v55
	v_mul_f32_e32 v51, v51, v81
	v_mul_f32_e32 v88, 0x3f317217, v73
	v_fma_f32 v88, v73, s65, -v88
	v_fmac_f32_e32 v88, 0x3377d1cf, v73
	v_fmac_f32_e32 v88, 0x3f317217, v73
	v_cmp_lt_f32_e64 s[4:5], |v73|, s56
	v_rcp_f32_e32 v52, v52
	v_sub_f32_e32 v56, 1.0, v60
	v_cndmask_b32_e64 v73, v73, v88, s[4:5]
	v_cndmask_b32_e32 v88, 0, v203, vcc
	v_sub_f32_e32 v73, v73, v88
	v_pk_add_f32 v[54:55], v[54:55], v[72:73] neg_lo:[0,1] neg_hi:[0,1]
	v_sub_f32_e32 v88, 1.0, v65
	v_mul_f32_e32 v72, 0x3fb8aa3b, v54
	v_exp_f32_e32 v72, v72
	s_nop 0
	v_fma_f32 v72, v72, v81, v64
	v_mul_f32_e32 v81, 0x3fb8aa3b, v55
	v_cmp_gt_f32_e32 vcc, s81, v72
	v_exp_f32_e32 v81, v81
	s_nop 0
	v_cndmask_b32_e64 v73, 0, 32, vcc
	v_ldexp_f32 v72, v72, v73
	v_log_f32_e32 v72, v72
	v_fma_f32 v81, v81, v88, v65
	v_cmp_gt_f32_e64 s[4:5], s81, v81
	v_mul_f32_e32 v73, v52, v56
	v_mul_f32_e32 v52, 0x3f317217, v72
	v_cndmask_b32_e64 v89, 0, 32, s[4:5]
	v_ldexp_f32 v81, v81, v89
	v_fma_f32 v52, v72, s65, -v52
	v_log_f32_e32 v81, v81
	v_fmac_f32_e32 v52, 0x3377d1cf, v72
	v_fmac_f32_e32 v52, 0x3f317217, v72
	v_cmp_lt_f32_e64 s[6:7], |v72|, s56
	v_mul_f32_e64 v89, |v53|, s82
	v_exp_f32_e32 v89, v89
	v_cndmask_b32_e64 v52, v72, v52, s[6:7]
	v_cndmask_b32_e32 v72, 0, v203, vcc
	v_sub_f32_e32 v52, v52, v72
	v_mul_f32_e32 v72, 0x3f317217, v81
	v_fma_f32 v72, v81, s65, -v72
	v_fmac_f32_e32 v72, 0x3377d1cf, v81
	v_fmac_f32_e32 v72, 0x3f317217, v81
	v_cmp_lt_f32_e64 vcc, |v81|, s56
	s_nop 1
	v_cndmask_b32_e32 v72, v81, v72, vcc
	v_cmp_lt_f32_e32 vcc, 0, v63
	v_cndmask_b32_e64 v81, 0, v203, s[4:5]
	v_cmp_lt_f32_e64 s[4:5], 0, v62
	v_cndmask_b32_e32 v63, v69, v79, vcc
	v_add_f32_e32 v69, 1.0, v89
	v_cmp_gt_f32_e32 vcc, s81, v69
	v_cndmask_b32_e64 v62, v68, v84, s[4:5]
	v_max_f32_e32 v68, v53, v53
	v_cndmask_b32_e64 v79, 0, 32, vcc
	v_ldexp_f32 v69, v69, v79
	v_log_f32_e32 v69, v69
	v_min_f32_e32 v79, 0, v68
	v_sub_f32_e32 v72, v72, v81
	v_mul_f32_e32 v53, 0x3fb8aa3b, v53
	v_mul_f32_e32 v68, 0x3f317217, v69
	v_fma_f32 v68, v69, s65, -v68
	v_fmac_f32_e32 v68, 0x3377d1cf, v69
	v_fmac_f32_e32 v68, 0x3f317217, v69
	v_cmp_lt_f32_e64 s[4:5], |v69|, s56
	v_exp_f32_e32 v53, v53
	v_pk_mul_f32 v[62:63], v[62:63], s[68:69] op_sel_hi:[1,0]
	v_cndmask_b32_e64 v68, v69, v68, s[4:5]
	v_cndmask_b32_e32 v69, 0, v203, vcc
	v_sub_f32_e32 v81, v68, v69
	v_pk_add_f32 v[68:69], v[78:79], v[80:81] neg_lo:[0,1] neg_hi:[0,1]
	v_cmp_lt_f32_e32 vcc, 0, v65
	v_mul_f32_e32 v78, 0x3fb8aa3b, v68
	v_exp_f32_e32 v78, v78
	v_cndmask_b32_e32 v55, v55, v72, vcc
	v_cmp_lt_f32_e32 vcc, 0, v64
	s_nop 1
	v_cndmask_b32_e32 v54, v54, v52, vcc
	v_fma_f32 v52, v78, v56, v60
	v_pk_mul_f32 v[64:65], v[54:55], s[68:69] op_sel_hi:[1,0]
	v_mul_f32_e32 v55, 0x3fb8aa3b, v69
	v_cmp_gt_f32_e32 vcc, s81, v52
	v_exp_f32_e32 v55, v55
	s_nop 0
	v_cndmask_b32_e64 v56, 0, 32, vcc
	v_ldexp_f32 v52, v52, v56
	v_log_f32_e32 v52, v52
	v_sub_f32_e32 v56, 1.0, v61
	v_fma_f32 v55, v55, v56, v61
	v_cmp_gt_f32_e64 s[4:5], s81, v55
	v_mul_f32_e32 v54, 0x3f317217, v52
	v_fma_f32 v54, v52, s65, -v54
	v_cndmask_b32_e64 v72, 0, 32, s[4:5]
	v_ldexp_f32 v55, v55, v72
	v_log_f32_e32 v55, v55
	v_fmac_f32_e32 v54, 0x3377d1cf, v52
	v_fmac_f32_e32 v54, 0x3f317217, v52
	v_cmp_lt_f32_e64 s[6:7], |v52|, s56
	s_nop 1
	v_cndmask_b32_e64 v52, v52, v54, s[6:7]
	v_cndmask_b32_e32 v54, 0, v203, vcc
	v_sub_f32_e32 v52, v52, v54
	v_mul_f32_e32 v54, 0x3f317217, v55
	v_fma_f32 v54, v55, s65, -v54
	v_fmac_f32_e32 v54, 0x3377d1cf, v55
	v_fmac_f32_e32 v54, 0x3f317217, v55
	v_cmp_lt_f32_e64 vcc, |v55|, s56
	s_nop 1
	v_cndmask_b32_e32 v54, v55, v54, vcc
	v_cmp_lt_f32_e32 vcc, 0, v59
	v_cndmask_b32_e64 v55, 0, v203, s[4:5]
	v_sub_f32_e32 v54, v54, v55
	v_cndmask_b32_e32 v59, v71, v86, vcc
	v_cmp_lt_f32_e32 vcc, 0, v58
	s_nop 1
	v_cndmask_b32_e32 v58, v70, v85, vcc
	v_cmp_lt_f32_e32 vcc, 0, v61
	s_nop 1
	v_cndmask_b32_e32 v55, v69, v54, vcc
	v_mul_f32_e32 v54, 0x3fb8aa3b, v57
	v_exp_f32_e32 v57, v54
	v_cmp_lt_f32_e32 vcc, 0, v60
	s_nop 1
	v_cndmask_b32_e32 v54, v68, v52, vcc
	v_add_f32_e32 v52, 1.0, v57
	v_rcp_f32_e32 v57, v52
	v_add_f32_e32 v52, 1.0, v53
	v_rcp_f32_e32 v60, v52
	v_pk_mul_f32 v[54:55], v[54:55], s[68:69] op_sel_hi:[1,0]
	v_pk_mul_f32 v[52:53], v[58:59], s[68:69] op_sel_hi:[1,0]
	v_mul_f32_e32 v58, v57, v88
	v_mul_f32_e32 v59, v60, v56
	v_lshl_add_u64 v[56:57], v[76:77], 0, v[66:67]
	global_store_dwordx4 v[56:57], v[62:65], off
	global_store_dwordx4 v[56:57], v[52:55], off offset:16
	v_cvt_pk_bf16_f32 v50, v50, v82
	v_cvt_pk_bf16_f32 v51, v51, v58
	s_nop 1
	v_lshl_add_u64 v[54:55], v[148:149], 1, v[74:75]
	v_cvt_pk_bf16_f32 v52, v83, v87
	v_cvt_pk_bf16_f32 v53, v73, v59
	global_store_dwordx4 v[54:55], v[50:53], off offset:256
	s_and_b64 vcc, exec, s[90:91]
	s_cbranch_vccz .LBB0_519

.LBB0_537:
	v_ashrrev_i32_e32 v61, 31, v60
	s_nop 0
	v_lshlrev_b64 v[50:51], 11, v[60:61]
	s_and_b64 vcc, exec, s[0:1]
	v_lshl_add_u64 v[58:59], s[10:11], 0, v[58:59]
	v_lshl_add_u64 v[60:61], v[50:51], 2, s[12:13]
	s_cbranch_vccz .LBB0_539
	v_lshl_add_u64 v[64:65], v[148:149], 2, s[2:3]
	v_lshl_add_u64 v[50:51], s[14:15], 0, v[64:65]
	v_mov_b32_e32 v54, v206
	v_mov_b32_e32 v55, v207
	v_mov_b32_e32 v56, v208
	v_mov_b32_e32 v57, v209
	v_mov_b32_e32 v50, v210
	v_mov_b32_e32 v51, v211
	v_mov_b32_e32 v52, v212
	v_mov_b32_e32 v53, v213
	v_max_f32_e32 v63, v46, v46
	v_mul_f32_e64 v67, |v46|, s82
	v_mul_f32_e64 v69, |v42|, s82
	v_min_f32_e32 v66, 0, v63
	v_exp_f32_e32 v63, v67
	v_max_f32_e32 v70, v47, v47
	v_mul_f32_e64 v71, |v47|, s82
	v_mul_f32_e64 v72, |v43|, s82
	v_exp_f32_e32 v69, v69
	v_max_f32_e32 v68, v42, v42
	v_mul_f32_e32 v42, 0x3fb8aa3b, v42
	v_min_f32_e32 v67, 0, v70
	v_exp_f32_e32 v70, v71
	v_exp_f32_e32 v71, v72
	v_exp_f32_e32 v42, v42
	v_add_f32_e32 v63, 1.0, v63
	v_add_f32_e32 v69, 1.0, v69
	v_cmp_gt_f32_e32 vcc, s81, v63
	v_add_f32_e32 v70, 1.0, v70
	v_add_f32_e32 v73, 1.0, v71
	v_cndmask_b32_e64 v71, 0, 32, vcc
	v_cmp_gt_f32_e64 s[4:5], s81, v69
	v_add_f32_e32 v42, 1.0, v42
	v_cmp_gt_f32_e64 s[6:7], s81, v70
	v_cndmask_b32_e64 v72, 0, 32, s[4:5]
	v_ldexp_f32 v63, v63, v71
	v_rcp_f32_e32 v74, v42
	v_cndmask_b32_e64 v42, 0, 32, s[6:7]
	v_ldexp_f32 v69, v69, v72
	v_log_f32_e32 v63, v63
	v_ldexp_f32 v42, v70, v42
	v_log_f32_e32 v69, v69
	v_log_f32_e32 v42, v42
	v_mul_f32_e32 v70, 0x3f317217, v63
	v_fma_f32 v70, v63, s65, -v70
	v_mul_f32_e32 v76, 0x3f317217, v69
	v_mul_f32_e32 v77, 0x3f317217, v42
	v_fma_f32 v76, v69, s65, -v76
	v_fmac_f32_e32 v70, 0x3377d1cf, v63
	v_cndmask_b32_e32 v71, 0, v203, vcc
	v_fma_f32 v77, v42, s65, -v77
	v_fmac_f32_e32 v76, 0x3377d1cf, v69
	v_fmac_f32_e32 v70, 0x3f317217, v63
	v_cmp_lt_f32_e64 vcc, |v63|, s56
	v_mul_f32_e32 v46, 0x3fb8aa3b, v46
	v_fmac_f32_e32 v77, 0x3377d1cf, v42
	v_fmac_f32_e32 v76, 0x3f317217, v69
	v_cndmask_b32_e32 v63, v63, v70, vcc
	v_cmp_lt_f32_e64 vcc, |v69|, s56
	v_exp_f32_e32 v46, v46
	v_fmac_f32_e32 v77, 0x3f317217, v42
	v_cndmask_b32_e32 v69, v69, v76, vcc
	v_cmp_lt_f32_e64 vcc, |v42|, s56
	v_cndmask_b32_e64 v75, 0, v203, s[6:7]
	v_sub_f32_e32 v70, v63, v71
	v_cndmask_b32_e32 v42, v42, v77, vcc
	v_sub_f32_e32 v71, v42, v75
	v_pk_add_f32 v[66:67], v[66:67], v[70:71] neg_lo:[0,1] neg_hi:[0,1]
	v_add_f32_e32 v46, 1.0, v46
	v_cndmask_b32_e64 v72, 0, v203, s[4:5]
	v_mul_f32_e32 v42, 0x3fb8aa3b, v66
	v_rcp_f32_e32 v46, v46
	v_sub_f32_e32 v72, v69, v72
	v_exp_f32_e32 v69, v42
	v_mul_f32_e32 v63, 0x3fb8aa3b, v67
	v_exp_f32_e32 v63, v63
	v_min_f32_e32 v68, 0, v68
	v_mul_f32_e32 v47, 0x3fb8aa3b, v47
	v_exp_f32_e32 v47, v47
	v_sub_f32_e32 v70, 1.0, v54
	v_mul_f32_e32 v42, v46, v70
	v_fma_f32 v46, v69, v70, v54
	v_cmp_gt_f32_e64 s[4:5], s81, v46
	v_sub_f32_e32 v75, 1.0, v55
	v_fma_f32 v63, v63, v75, v55
	v_cndmask_b32_e64 v69, 0, 32, s[4:5]
	v_ldexp_f32 v46, v46, v69
	v_log_f32_e32 v46, v46
	v_cmp_gt_f32_e32 vcc, s81, v63
	v_cndmask_b32_e64 v69, 0, v203, s[4:5]
	v_sub_f32_e32 v71, 1.0, v50
	v_cndmask_b32_e64 v70, 0, 32, vcc
	v_ldexp_f32 v63, v63, v70
	v_mul_f32_e32 v70, 0x3f317217, v46
	v_fma_f32 v70, v46, s65, -v70
	v_fmac_f32_e32 v70, 0x3377d1cf, v46
	v_fmac_f32_e32 v70, 0x3f317217, v46
	v_cmp_lt_f32_e64 s[4:5], |v46|, s56
	v_log_f32_e32 v63, v63
	v_mul_f32_e32 v76, v74, v71
	v_cndmask_b32_e64 v46, v46, v70, s[4:5]
	v_cmp_gt_f32_e64 s[4:5], s81, v73
	v_sub_f32_e32 v77, v46, v69
	v_max_f32_e32 v69, v43, v43
	v_cndmask_b32_e64 v46, 0, 32, s[4:5]
	v_ldexp_f32 v46, v73, v46
	v_log_f32_e32 v46, v46
	v_min_f32_e32 v69, 0, v69
	v_mul_f32_e32 v74, 0x3f317217, v63
	v_fma_f32 v74, v63, s65, -v74
	v_mul_f32_e32 v70, 0x3f317217, v46
	v_fma_f32 v70, v46, s65, -v70
	v_fmac_f32_e32 v70, 0x3377d1cf, v46
	v_fmac_f32_e32 v70, 0x3f317217, v46
	v_cmp_lt_f32_e64 s[6:7], |v46|, s56
	v_fmac_f32_e32 v74, 0x3377d1cf, v63
	v_fmac_f32_e32 v74, 0x3f317217, v63
	v_cndmask_b32_e64 v46, v46, v70, s[6:7]
	v_cndmask_b32_e64 v70, 0, v203, s[4:5]
	v_sub_f32_e32 v73, v46, v70
	v_pk_add_f32 v[68:69], v[68:69], v[72:73] neg_lo:[0,1] neg_hi:[0,1]
	v_cmp_lt_f32_e64 s[4:5], |v63|, s56
	v_mul_f32_e32 v46, 0x3fb8aa3b, v68
	v_exp_f32_e32 v46, v46
	v_mul_f32_e32 v72, 0x3fb8aa3b, v69
	v_cndmask_b32_e64 v63, v63, v74, s[4:5]
	v_exp_f32_e32 v72, v72
	v_fma_f32 v46, v46, v71, v50
	v_cmp_gt_f32_e64 s[4:5], s81, v46
	v_mul_f32_e32 v43, 0x3fb8aa3b, v43
	v_exp_f32_e32 v43, v43
	v_cndmask_b32_e64 v70, 0, 32, s[4:5]
	v_ldexp_f32 v46, v46, v70
	v_cndmask_b32_e32 v70, 0, v203, vcc
	v_log_f32_e32 v46, v46
	v_sub_f32_e32 v63, v63, v70
	v_sub_f32_e32 v70, 1.0, v51
	v_fma_f32 v72, v72, v70, v51
	v_cmp_gt_f32_e32 vcc, s81, v72
	v_mul_f32_e32 v71, 0x3f317217, v46
	v_fma_f32 v71, v46, s65, -v71
	v_cndmask_b32_e64 v73, 0, 32, vcc
	v_ldexp_f32 v72, v72, v73
	v_log_f32_e32 v72, v72
	v_fmac_f32_e32 v71, 0x3377d1cf, v46
	v_fmac_f32_e32 v71, 0x3f317217, v46
	v_cmp_lt_f32_e64 s[6:7], |v46|, s56
	v_add_f32_e32 v43, 1.0, v43
	v_rcp_f32_e32 v43, v43
	v_cndmask_b32_e64 v46, v46, v71, s[6:7]
	v_cndmask_b32_e64 v71, 0, v203, s[4:5]
	v_sub_f32_e32 v78, v46, v71
	v_mul_f32_e32 v46, 0x3f317217, v72
	v_fma_f32 v46, v72, s65, -v46
	v_fmac_f32_e32 v46, 0x3377d1cf, v72
	v_fmac_f32_e32 v46, 0x3f317217, v72
	v_cmp_lt_f32_e64 s[4:5], |v72|, s56
	v_cndmask_b32_e32 v71, 0, v203, vcc
	v_mul_f32_e32 v81, v43, v70
	v_cndmask_b32_e64 v46, v72, v46, s[4:5]
	v_sub_f32_e32 v79, v46, v71
	v_add_f32_e32 v46, 1.0, v47
	v_mul_f32_e64 v47, |v48|, s82
	v_rcp_f32_e32 v46, v46
	v_exp_f32_e32 v47, v47
	v_max_f32_e32 v43, v48, v48
	v_mul_f32_e64 v70, |v44|, s82
	v_mul_f32_e32 v80, v46, v75
	v_add_f32_e32 v46, 1.0, v47
	v_cmp_gt_f32_e32 vcc, s81, v46
	v_exp_f32_e32 v71, v70
	v_sub_f32_e32 v73, 1.0, v56
	v_cndmask_b32_e64 v47, 0, 32, vcc
	v_ldexp_f32 v46, v46, v47
	v_log_f32_e32 v47, v46
	v_min_f32_e32 v46, 0, v43
	v_sub_f32_e32 v82, 1.0, v57
	v_mul_f32_e32 v43, 0x3f317217, v47
	v_fma_f32 v43, v47, s65, -v43
	v_fmac_f32_e32 v43, 0x3377d1cf, v47
	v_fmac_f32_e32 v43, 0x3f317217, v47
	v_cmp_lt_f32_e64 s[4:5], |v47|, s56
	s_nop 1
	v_cndmask_b32_e64 v43, v47, v43, s[4:5]
	v_cndmask_b32_e32 v47, 0, v203, vcc
	v_sub_f32_e32 v70, v43, v47
	v_add_f32_e32 v43, 1.0, v71
	v_cmp_gt_f32_e32 vcc, s81, v43
	s_nop 1
	v_cndmask_b32_e64 v47, 0, 32, vcc
	v_ldexp_f32 v43, v43, v47
	v_log_f32_e32 v43, v43
	v_max_f32_e32 v47, v44, v44
	v_min_f32_e32 v72, 0, v47
	v_mul_f32_e32 v44, 0x3fb8aa3b, v44
	v_mul_f32_e32 v47, 0x3f317217, v43
	v_fma_f32 v47, v43, s65, -v47
	v_fmac_f32_e32 v47, 0x3377d1cf, v43
	v_fmac_f32_e32 v47, 0x3f317217, v43
	v_cmp_lt_f32_e64 s[4:5], |v43|, s56
	v_exp_f32_e32 v44, v44
	s_nop 0
	v_cndmask_b32_e64 v43, v43, v47, s[4:5]
	v_cndmask_b32_e32 v47, 0, v203, vcc
	v_sub_f32_e32 v74, v43, v47
	v_mul_f32_e64 v47, |v49|, s82
	v_exp_f32_e32 v47, v47
	v_mul_f32_e32 v43, 0x3fb8aa3b, v48
	v_exp_f32_e32 v43, v43
	v_add_f32_e32 v44, 1.0, v44
	v_add_f32_e32 v47, 1.0, v47
	v_cmp_gt_f32_e32 vcc, s81, v47
	v_add_f32_e32 v43, 1.0, v43
	v_rcp_f32_e32 v43, v43
	v_cndmask_b32_e64 v71, 0, 32, vcc
	v_ldexp_f32 v47, v47, v71
	v_log_f32_e32 v71, v47
	v_max_f32_e32 v47, v49, v49
	v_min_f32_e32 v47, 0, v47
	v_mul_f32_e32 v43, v43, v73
	v_mul_f32_e32 v75, 0x3f317217, v71
	v_fma_f32 v75, v71, s65, -v75
	v_fmac_f32_e32 v75, 0x3377d1cf, v71
	v_fmac_f32_e32 v75, 0x3f317217, v71
	v_cmp_lt_f32_e64 s[4:5], |v71|, s56
	v_rcp_f32_e32 v44, v44
	v_sub_f32_e32 v48, 1.0, v52
	v_cndmask_b32_e64 v71, v71, v75, s[4:5]
	v_cndmask_b32_e32 v75, 0, v203, vcc
	v_sub_f32_e32 v71, v71, v75
	v_pk_add_f32 v[46:47], v[46:47], v[70:71] neg_lo:[0,1] neg_hi:[0,1]
	s_nop 0
	v_mul_f32_e32 v70, 0x3fb8aa3b, v46
	v_exp_f32_e32 v70, v70
	s_nop 0
	v_fma_f32 v70, v70, v73, v56
	v_mul_f32_e32 v73, 0x3fb8aa3b, v47
	v_cmp_gt_f32_e32 vcc, s81, v70
	v_exp_f32_e32 v73, v73
	s_nop 0
	v_cndmask_b32_e64 v71, 0, 32, vcc
	v_ldexp_f32 v70, v70, v71
	v_log_f32_e32 v70, v70
	v_fma_f32 v73, v73, v82, v57
	v_cmp_gt_f32_e64 s[4:5], s81, v73
	v_mul_f32_e32 v71, v44, v48
	v_mul_f32_e32 v44, 0x3f317217, v70
	v_cndmask_b32_e64 v75, 0, 32, s[4:5]
	v_ldexp_f32 v73, v73, v75
	v_fma_f32 v44, v70, s65, -v44
	v_log_f32_e32 v73, v73
	v_fmac_f32_e32 v44, 0x3377d1cf, v70
	v_fmac_f32_e32 v44, 0x3f317217, v70
	v_cmp_lt_f32_e64 s[6:7], |v70|, s56
	v_mul_f32_e64 v75, |v45|, s82
	v_exp_f32_e32 v75, v75
	v_cndmask_b32_e64 v44, v70, v44, s[6:7]
	v_cndmask_b32_e32 v70, 0, v203, vcc
	v_sub_f32_e32 v44, v44, v70
	v_mul_f32_e32 v70, 0x3f317217, v73
	v_fma_f32 v70, v73, s65, -v70
	v_fmac_f32_e32 v70, 0x3377d1cf, v73
	v_fmac_f32_e32 v70, 0x3f317217, v73
	v_cmp_lt_f32_e64 vcc, |v73|, s56
	s_nop 1
	v_cndmask_b32_e32 v70, v73, v70, vcc
	v_cmp_lt_f32_e32 vcc, 0, v55
	v_cndmask_b32_e64 v73, 0, v203, s[4:5]
	v_cmp_lt_f32_e64 s[4:5], 0, v54
	v_cndmask_b32_e32 v55, v67, v63, vcc
	v_add_f32_e32 v63, 1.0, v75
	v_cmp_gt_f32_e32 vcc, s81, v63
	v_cndmask_b32_e64 v54, v66, v77, s[4:5]
	v_max_f32_e32 v66, v45, v45
	v_cndmask_b32_e64 v67, 0, 32, vcc
	v_ldexp_f32 v63, v63, v67
	v_log_f32_e32 v63, v63
	v_sub_f32_e32 v70, v70, v73
	v_min_f32_e32 v73, 0, v66
	v_mul_f32_e32 v45, 0x3fb8aa3b, v45
	v_mul_f32_e32 v66, 0x3f317217, v63
	v_fma_f32 v66, v63, s65, -v66
	v_fmac_f32_e32 v66, 0x3377d1cf, v63
	v_fmac_f32_e32 v66, 0x3f317217, v63
	v_cmp_lt_f32_e64 s[4:5], |v63|, s56
	v_exp_f32_e32 v45, v45
	v_pk_mul_f32 v[54:55], v[54:55], s[68:69] op_sel_hi:[1,0]
	v_cndmask_b32_e64 v63, v63, v66, s[4:5]
	v_cndmask_b32_e32 v66, 0, v203, vcc
	v_sub_f32_e32 v75, v63, v66
	v_pk_add_f32 v[66:67], v[72:73], v[74:75] neg_lo:[0,1] neg_hi:[0,1]
	v_cmp_lt_f32_e32 vcc, 0, v57
	v_mul_f32_e32 v63, 0x3fb8aa3b, v66
	v_exp_f32_e32 v63, v63
	v_cndmask_b32_e32 v47, v47, v70, vcc
	v_cmp_lt_f32_e32 vcc, 0, v56
	s_nop 1
	v_cndmask_b32_e32 v46, v46, v44, vcc
	v_fma_f32 v44, v63, v48, v52
	v_pk_mul_f32 v[56:57], v[46:47], s[68:69] op_sel_hi:[1,0]
	v_mul_f32_e32 v47, 0x3fb8aa3b, v67
	v_cmp_gt_f32_e32 vcc, s81, v44
	v_exp_f32_e32 v47, v47
	s_nop 0
	v_cndmask_b32_e64 v48, 0, 32, vcc
	v_ldexp_f32 v44, v44, v48
	v_log_f32_e32 v44, v44
	v_sub_f32_e32 v48, 1.0, v53
	v_fma_f32 v47, v47, v48, v53
	v_cmp_gt_f32_e64 s[4:5], s81, v47
	v_mul_f32_e32 v46, 0x3f317217, v44
	v_fma_f32 v46, v44, s65, -v46
	v_cndmask_b32_e64 v63, 0, 32, s[4:5]
	v_ldexp_f32 v47, v47, v63
	v_log_f32_e32 v47, v47
	v_fmac_f32_e32 v46, 0x3377d1cf, v44
	v_fmac_f32_e32 v46, 0x3f317217, v44
	v_cmp_lt_f32_e64 s[6:7], |v44|, s56
	s_nop 1
	v_cndmask_b32_e64 v44, v44, v46, s[6:7]
	v_cndmask_b32_e32 v46, 0, v203, vcc
	v_sub_f32_e32 v44, v44, v46
	v_mul_f32_e32 v46, 0x3f317217, v47
	v_fma_f32 v46, v47, s65, -v46
	v_fmac_f32_e32 v46, 0x3377d1cf, v47
	v_fmac_f32_e32 v46, 0x3f317217, v47
	v_cmp_lt_f32_e64 vcc, |v47|, s56
	s_nop 1
	v_cndmask_b32_e32 v46, v47, v46, vcc
	v_cmp_lt_f32_e32 vcc, 0, v51
	v_cndmask_b32_e64 v47, 0, v203, s[4:5]
	v_sub_f32_e32 v46, v46, v47
	v_cndmask_b32_e32 v51, v69, v79, vcc
	v_cmp_lt_f32_e32 vcc, 0, v50
	s_nop 1
	v_cndmask_b32_e32 v50, v68, v78, vcc
	v_cmp_lt_f32_e32 vcc, 0, v53
	s_nop 1
	v_cndmask_b32_e32 v47, v67, v46, vcc
	v_mul_f32_e32 v46, 0x3fb8aa3b, v49
	v_exp_f32_e32 v49, v46
	v_cmp_lt_f32_e32 vcc, 0, v52
	s_nop 1
	v_cndmask_b32_e32 v46, v66, v44, vcc
	v_add_f32_e32 v44, 1.0, v49
	v_rcp_f32_e32 v49, v44
	v_add_f32_e32 v44, 1.0, v45
	v_rcp_f32_e32 v52, v44
	v_pk_mul_f32 v[46:47], v[46:47], s[68:69] op_sel_hi:[1,0]
	v_pk_mul_f32 v[44:45], v[50:51], s[68:69] op_sel_hi:[1,0]
	v_mul_f32_e32 v50, v49, v82
	v_mul_f32_e32 v51, v52, v48
	v_lshl_add_u64 v[48:49], v[60:61], 0, v[64:65]
	global_store_dwordx4 v[48:49], v[54:57], off
	global_store_dwordx4 v[48:49], v[44:47], off offset:16
	v_cvt_pk_bf16_f32 v42, v42, v80
	v_cvt_pk_bf16_f32 v43, v43, v50
	s_nop 1
	v_lshl_add_u64 v[46:47], v[148:149], 1, v[58:59]
	v_cvt_pk_bf16_f32 v44, v76, v81
	v_cvt_pk_bf16_f32 v45, v71, v51
	global_store_dwordx4 v[46:47], v[42:45], off

.LBB0_550:
	v_lshl_add_u64 v[50:51], v[148:149], 2, s[26:27]
	v_lshl_add_u64 v[42:43], s[14:15], 0, v[50:51]
	v_mov_b32_e32 v46, v214
	v_mov_b32_e32 v47, v215
	v_mov_b32_e32 v48, v216
	v_mov_b32_e32 v49, v217
	v_mov_b32_e32 v42, v218
	v_mov_b32_e32 v43, v219
	v_mov_b32_e32 v44, v220
	v_mov_b32_e32 v45, v221
	v_mul_f32_e64 v53, |v38|, s82
	v_mul_f32_e64 v55, |v34|, s82
	v_max_f32_e32 v56, v39, v39
	v_mul_f32_e64 v57, |v39|, s82
	v_exp_f32_e32 v63, v53
	v_max_f32_e32 v54, v34, v34
	v_mul_f32_e32 v34, 0x3fb8aa3b, v34
	v_mul_f32_e64 v62, |v35|, s82
	v_exp_f32_e32 v55, v55
	v_min_f32_e32 v53, 0, v56
	v_exp_f32_e32 v56, v57
	v_exp_f32_e32 v34, v34
	v_exp_f32_e32 v57, v62
	v_add_f32_e32 v62, 1.0, v63
	v_add_f32_e32 v55, 1.0, v55
	v_add_f32_e32 v56, 1.0, v56
	v_cmp_gt_f32_e32 vcc, s81, v62
	v_add_f32_e32 v34, 1.0, v34
	v_add_f32_e32 v63, 1.0, v57
	v_cndmask_b32_e64 v57, 0, 32, vcc
	v_cmp_gt_f32_e64 s[4:5], s81, v55
	v_cmp_gt_f32_e64 s[6:7], s81, v56
	v_rcp_f32_e32 v65, v34
	v_cndmask_b32_e64 v64, 0, 32, s[4:5]
	v_cndmask_b32_e64 v34, 0, 32, s[6:7]
	v_ldexp_f32 v57, v62, v57
	v_ldexp_f32 v55, v55, v64
	v_ldexp_f32 v34, v56, v34
	v_log_f32_e32 v56, v57
	v_log_f32_e32 v55, v55
	v_log_f32_e32 v34, v34
	v_cndmask_b32_e32 v62, 0, v203, vcc
	v_mul_f32_e32 v66, 0x3f317217, v56
	v_mul_f32_e32 v67, 0x3f317217, v55
	v_fma_f32 v66, v56, s65, -v66
	v_mul_f32_e32 v68, 0x3f317217, v34
	v_fma_f32 v67, v55, s65, -v67
	v_fmac_f32_e32 v66, 0x3377d1cf, v56
	v_fma_f32 v68, v34, s65, -v68
	v_fmac_f32_e32 v67, 0x3377d1cf, v55
	v_fmac_f32_e32 v66, 0x3f317217, v56
	v_cmp_lt_f32_e64 vcc, |v56|, s56
	v_max_f32_e32 v52, v38, v38
	v_mul_f32_e32 v38, 0x3fb8aa3b, v38
	v_fmac_f32_e32 v68, 0x3377d1cf, v34
	v_fmac_f32_e32 v67, 0x3f317217, v55
	v_cndmask_b32_e32 v56, v56, v66, vcc
	v_cmp_lt_f32_e64 vcc, |v55|, s56
	v_exp_f32_e32 v38, v38
	v_fmac_f32_e32 v68, 0x3f317217, v34
	v_cndmask_b32_e32 v55, v55, v67, vcc
	v_cmp_lt_f32_e64 vcc, |v34|, s56
	v_cndmask_b32_e64 v57, 0, v203, s[6:7]
	v_min_f32_e32 v52, 0, v52
	v_cndmask_b32_e32 v34, v34, v68, vcc
	v_sub_f32_e32 v56, v56, v62
	v_sub_f32_e32 v57, v34, v57
	v_pk_add_f32 v[52:53], v[52:53], v[56:57] neg_lo:[0,1] neg_hi:[0,1]
	v_add_f32_e32 v38, 1.0, v38
	v_mul_f32_e32 v34, 0x3fb8aa3b, v52
	v_rcp_f32_e32 v38, v38
	v_exp_f32_e32 v56, v34
	v_cndmask_b32_e64 v64, 0, v203, s[4:5]
	v_sub_f32_e32 v62, v55, v64
	v_mul_f32_e32 v55, 0x3fb8aa3b, v53
	v_exp_f32_e32 v55, v55
	v_min_f32_e32 v54, 0, v54
	v_mul_f32_e32 v39, 0x3fb8aa3b, v39
	v_exp_f32_e32 v39, v39
	v_sub_f32_e32 v57, 1.0, v46
	v_mul_f32_e32 v34, v38, v57
	v_fma_f32 v38, v56, v57, v46
	v_cmp_gt_f32_e64 s[4:5], s81, v38
	v_sub_f32_e32 v66, 1.0, v47
	v_fma_f32 v55, v55, v66, v47
	v_cndmask_b32_e64 v56, 0, 32, s[4:5]
	v_ldexp_f32 v38, v38, v56
	v_log_f32_e32 v38, v38
	v_cmp_gt_f32_e32 vcc, s81, v55
	v_sub_f32_e32 v64, 1.0, v42
	v_mul_f32_e32 v67, v65, v64
	v_cndmask_b32_e64 v57, 0, 32, vcc
	v_ldexp_f32 v55, v55, v57
	v_mul_f32_e32 v57, 0x3f317217, v38
	v_fma_f32 v57, v38, s65, -v57
	v_fmac_f32_e32 v57, 0x3377d1cf, v38
	v_log_f32_e32 v56, v55
	v_cndmask_b32_e64 v55, 0, v203, s[4:5]
	v_fmac_f32_e32 v57, 0x3f317217, v38
	v_cmp_lt_f32_e64 s[4:5], |v38|, s56
	v_mul_f32_e32 v65, 0x3f317217, v56
	v_fma_f32 v65, v56, s65, -v65
	v_cndmask_b32_e64 v38, v38, v57, s[4:5]
	v_cmp_gt_f32_e64 s[4:5], s81, v63
	v_sub_f32_e32 v68, v38, v55
	v_max_f32_e32 v55, v35, v35
	v_cndmask_b32_e64 v38, 0, 32, s[4:5]
	v_ldexp_f32 v38, v63, v38
	v_log_f32_e32 v38, v38
	v_min_f32_e32 v55, 0, v55
	v_fmac_f32_e32 v65, 0x3377d1cf, v56
	v_fmac_f32_e32 v65, 0x3f317217, v56
	v_mul_f32_e32 v57, 0x3f317217, v38
	v_fma_f32 v57, v38, s65, -v57
	v_fmac_f32_e32 v57, 0x3377d1cf, v38
	v_fmac_f32_e32 v57, 0x3f317217, v38
	v_cmp_lt_f32_e64 s[6:7], |v38|, s56
	v_mul_f32_e32 v35, 0x3fb8aa3b, v35
	v_exp_f32_e32 v35, v35
	v_cndmask_b32_e64 v38, v38, v57, s[6:7]
	v_cndmask_b32_e64 v57, 0, v203, s[4:5]
	v_sub_f32_e32 v63, v38, v57
	v_pk_add_f32 v[54:55], v[54:55], v[62:63] neg_lo:[0,1] neg_hi:[0,1]
	v_cmp_lt_f32_e64 s[4:5], |v56|, s56
	v_mul_f32_e32 v38, 0x3fb8aa3b, v54
	v_exp_f32_e32 v38, v38
	v_mul_f32_e32 v62, 0x3fb8aa3b, v55
	v_cndmask_b32_e64 v56, v56, v65, s[4:5]
	v_exp_f32_e32 v62, v62
	v_fma_f32 v38, v38, v64, v42
	v_cmp_gt_f32_e64 s[4:5], s81, v38
	v_add_f32_e32 v35, 1.0, v35
	v_rcp_f32_e32 v35, v35
	v_cndmask_b32_e64 v57, 0, 32, s[4:5]
	v_ldexp_f32 v38, v38, v57
	v_cndmask_b32_e32 v57, 0, v203, vcc
	v_log_f32_e32 v38, v38
	v_sub_f32_e32 v63, v56, v57
	v_sub_f32_e32 v56, 1.0, v43
	v_fma_f32 v62, v62, v56, v43
	v_cmp_gt_f32_e32 vcc, s81, v62
	v_mul_f32_e32 v57, 0x3f317217, v38
	v_fma_f32 v57, v38, s65, -v57
	v_cndmask_b32_e64 v64, 0, 32, vcc
	v_ldexp_f32 v62, v62, v64
	v_log_f32_e32 v62, v62
	v_fmac_f32_e32 v57, 0x3377d1cf, v38
	v_fmac_f32_e32 v57, 0x3f317217, v38
	v_cmp_lt_f32_e64 s[6:7], |v38|, s56
	v_mul_f32_e32 v71, v35, v56
	v_max_f32_e32 v35, v40, v40
	v_cndmask_b32_e64 v38, v38, v57, s[6:7]
	v_cndmask_b32_e64 v57, 0, v203, s[4:5]
	v_sub_f32_e32 v69, v38, v57
	v_mul_f32_e32 v38, 0x3f317217, v62
	v_fma_f32 v38, v62, s65, -v38
	v_fmac_f32_e32 v38, 0x3377d1cf, v62
	v_fmac_f32_e32 v38, 0x3f317217, v62
	v_cmp_lt_f32_e64 s[4:5], |v62|, s56
	v_cndmask_b32_e32 v57, 0, v203, vcc
	v_mul_f32_e64 v56, |v36|, s82
	v_cndmask_b32_e64 v38, v62, v38, s[4:5]
	v_sub_f32_e32 v70, v38, v57
	v_add_f32_e32 v38, 1.0, v39
	v_mul_f32_e64 v39, |v40|, s82
	v_rcp_f32_e32 v38, v38
	v_exp_f32_e32 v39, v39
	v_exp_f32_e32 v57, v56
	v_sub_f32_e32 v65, 1.0, v48
	v_mul_f32_e32 v66, v38, v66
	v_add_f32_e32 v38, 1.0, v39
	v_cmp_gt_f32_e32 vcc, s81, v38
	s_nop 1
	v_cndmask_b32_e64 v39, 0, 32, vcc
	v_ldexp_f32 v38, v38, v39
	v_log_f32_e32 v39, v38
	v_min_f32_e32 v38, 0, v35
	v_mul_f32_e32 v35, 0x3f317217, v39
	v_fma_f32 v35, v39, s65, -v35
	v_fmac_f32_e32 v35, 0x3377d1cf, v39
	v_fmac_f32_e32 v35, 0x3f317217, v39
	v_cmp_lt_f32_e64 s[4:5], |v39|, s56
	s_nop 1
	v_cndmask_b32_e64 v35, v39, v35, s[4:5]
	v_cndmask_b32_e32 v39, 0, v203, vcc
	v_sub_f32_e32 v56, v35, v39
	v_add_f32_e32 v35, 1.0, v57
	v_cmp_gt_f32_e32 vcc, s81, v35
	s_nop 1
	v_cndmask_b32_e64 v39, 0, 32, vcc
	v_ldexp_f32 v35, v35, v39
	v_log_f32_e32 v35, v35
	v_max_f32_e32 v39, v36, v36
	v_min_f32_e32 v62, 0, v39
	v_mul_f32_e32 v36, 0x3fb8aa3b, v36
	v_mul_f32_e32 v39, 0x3f317217, v35
	v_fma_f32 v39, v35, s65, -v39
	v_fmac_f32_e32 v39, 0x3377d1cf, v35
	v_fmac_f32_e32 v39, 0x3f317217, v35
	v_cmp_lt_f32_e64 s[4:5], |v35|, s56
	v_exp_f32_e32 v36, v36
	s_nop 0
	v_cndmask_b32_e64 v35, v35, v39, s[4:5]
	v_cndmask_b32_e32 v39, 0, v203, vcc
	v_sub_f32_e32 v64, v35, v39
	v_mul_f32_e64 v39, |v41|, s82
	v_exp_f32_e32 v39, v39
	v_mul_f32_e32 v35, 0x3fb8aa3b, v40
	v_exp_f32_e32 v35, v35
	v_add_f32_e32 v36, 1.0, v36
	v_add_f32_e32 v39, 1.0, v39
	v_cmp_gt_f32_e32 vcc, s81, v39
	v_add_f32_e32 v35, 1.0, v35
	v_rcp_f32_e32 v35, v35
	v_cndmask_b32_e64 v57, 0, 32, vcc
	v_ldexp_f32 v39, v39, v57
	v_log_f32_e32 v57, v39
	v_max_f32_e32 v39, v41, v41
	v_min_f32_e32 v39, 0, v39
	v_mul_f32_e32 v35, v35, v65
	v_mul_f32_e32 v72, 0x3f317217, v57
	v_fma_f32 v72, v57, s65, -v72
	v_fmac_f32_e32 v72, 0x3377d1cf, v57
	v_fmac_f32_e32 v72, 0x3f317217, v57
	v_cmp_lt_f32_e64 s[4:5], |v57|, s56
	v_rcp_f32_e32 v36, v36
	v_sub_f32_e32 v40, 1.0, v44
	v_cndmask_b32_e64 v57, v57, v72, s[4:5]
	v_cndmask_b32_e32 v72, 0, v203, vcc
	v_sub_f32_e32 v57, v57, v72
	v_pk_add_f32 v[38:39], v[38:39], v[56:57] neg_lo:[0,1] neg_hi:[0,1]
	v_sub_f32_e32 v72, 1.0, v49
	v_mul_f32_e32 v56, 0x3fb8aa3b, v38
	v_exp_f32_e32 v56, v56
	s_nop 0
	v_fma_f32 v56, v56, v65, v48
	v_mul_f32_e32 v65, 0x3fb8aa3b, v39
	v_cmp_gt_f32_e32 vcc, s81, v56
	v_exp_f32_e32 v65, v65
	s_nop 0
	v_cndmask_b32_e64 v57, 0, 32, vcc
	v_ldexp_f32 v56, v56, v57
	v_log_f32_e32 v56, v56
	v_fma_f32 v65, v65, v72, v49
	v_cmp_gt_f32_e64 s[4:5], s81, v65
	v_mul_f32_e32 v57, v36, v40
	v_mul_f32_e32 v36, 0x3f317217, v56
	v_cndmask_b32_e64 v73, 0, 32, s[4:5]
	v_ldexp_f32 v65, v65, v73
	v_fma_f32 v36, v56, s65, -v36
	v_log_f32_e32 v65, v65
	v_fmac_f32_e32 v36, 0x3377d1cf, v56
	v_fmac_f32_e32 v36, 0x3f317217, v56
	v_cmp_lt_f32_e64 s[6:7], |v56|, s56
	v_mul_f32_e64 v73, |v37|, s82
	v_exp_f32_e32 v73, v73
	v_cndmask_b32_e64 v36, v56, v36, s[6:7]
	v_cndmask_b32_e32 v56, 0, v203, vcc
	v_sub_f32_e32 v36, v36, v56
	v_mul_f32_e32 v56, 0x3f317217, v65
	v_fma_f32 v56, v65, s65, -v56
	v_fmac_f32_e32 v56, 0x3377d1cf, v65
	v_fmac_f32_e32 v56, 0x3f317217, v65
	v_cmp_lt_f32_e64 vcc, |v65|, s56
	s_nop 1
	v_cndmask_b32_e32 v56, v65, v56, vcc
	v_cmp_lt_f32_e32 vcc, 0, v47
	v_cndmask_b32_e64 v65, 0, v203, s[4:5]
	v_cmp_lt_f32_e64 s[4:5], 0, v46
	v_cndmask_b32_e32 v47, v53, v63, vcc
	v_add_f32_e32 v53, 1.0, v73
	v_cmp_gt_f32_e32 vcc, s81, v53
	v_cndmask_b32_e64 v46, v52, v68, s[4:5]
	v_max_f32_e32 v52, v37, v37
	v_cndmask_b32_e64 v63, 0, 32, vcc
	v_ldexp_f32 v53, v53, v63
	v_log_f32_e32 v53, v53
	v_min_f32_e32 v63, 0, v52
	v_sub_f32_e32 v56, v56, v65
	v_mul_f32_e32 v37, 0x3fb8aa3b, v37
	v_mul_f32_e32 v52, 0x3f317217, v53
	v_fma_f32 v52, v53, s65, -v52
	v_fmac_f32_e32 v52, 0x3377d1cf, v53
	v_fmac_f32_e32 v52, 0x3f317217, v53
	v_cmp_lt_f32_e64 s[4:5], |v53|, s56
	v_exp_f32_e32 v37, v37
	v_pk_mul_f32 v[46:47], v[46:47], s[68:69] op_sel_hi:[1,0]
	v_cndmask_b32_e64 v52, v53, v52, s[4:5]
	v_cndmask_b32_e32 v53, 0, v203, vcc
	v_sub_f32_e32 v65, v52, v53
	v_pk_add_f32 v[52:53], v[62:63], v[64:65] neg_lo:[0,1] neg_hi:[0,1]
	v_cmp_lt_f32_e32 vcc, 0, v49
	v_mul_f32_e32 v62, 0x3fb8aa3b, v52
	v_exp_f32_e32 v62, v62
	v_cndmask_b32_e32 v39, v39, v56, vcc
	v_cmp_lt_f32_e32 vcc, 0, v48
	s_nop 1
	v_cndmask_b32_e32 v38, v38, v36, vcc
	v_fma_f32 v36, v62, v40, v44
	v_pk_mul_f32 v[48:49], v[38:39], s[68:69] op_sel_hi:[1,0]
	v_mul_f32_e32 v39, 0x3fb8aa3b, v53
	v_cmp_gt_f32_e32 vcc, s81, v36
	v_exp_f32_e32 v39, v39
	s_nop 0
	v_cndmask_b32_e64 v40, 0, 32, vcc
	v_ldexp_f32 v36, v36, v40
	v_log_f32_e32 v36, v36
	v_sub_f32_e32 v40, 1.0, v45
	v_fma_f32 v39, v39, v40, v45
	v_cmp_gt_f32_e64 s[4:5], s81, v39
	v_mul_f32_e32 v38, 0x3f317217, v36
	v_fma_f32 v38, v36, s65, -v38
	v_cndmask_b32_e64 v56, 0, 32, s[4:5]
	v_ldexp_f32 v39, v39, v56
	v_log_f32_e32 v39, v39
	v_fmac_f32_e32 v38, 0x3377d1cf, v36
	v_fmac_f32_e32 v38, 0x3f317217, v36
	v_cmp_lt_f32_e64 s[6:7], |v36|, s56
	s_nop 1
	v_cndmask_b32_e64 v36, v36, v38, s[6:7]
	v_cndmask_b32_e32 v38, 0, v203, vcc
	v_sub_f32_e32 v36, v36, v38
	v_mul_f32_e32 v38, 0x3f317217, v39
	v_fma_f32 v38, v39, s65, -v38
	v_fmac_f32_e32 v38, 0x3377d1cf, v39
	v_fmac_f32_e32 v38, 0x3f317217, v39
	v_cmp_lt_f32_e64 vcc, |v39|, s56
	s_nop 1
	v_cndmask_b32_e32 v38, v39, v38, vcc
	v_cmp_lt_f32_e32 vcc, 0, v43
	v_cndmask_b32_e64 v39, 0, v203, s[4:5]
	v_sub_f32_e32 v38, v38, v39
	v_cndmask_b32_e32 v43, v55, v70, vcc
	v_cmp_lt_f32_e32 vcc, 0, v42
	s_nop 1
	v_cndmask_b32_e32 v42, v54, v69, vcc
	v_cmp_lt_f32_e32 vcc, 0, v45
	s_nop 1
	v_cndmask_b32_e32 v39, v53, v38, vcc
	v_mul_f32_e32 v38, 0x3fb8aa3b, v41
	v_exp_f32_e32 v41, v38
	v_cmp_lt_f32_e32 vcc, 0, v44
	s_nop 1
	v_cndmask_b32_e32 v38, v52, v36, vcc
	v_add_f32_e32 v36, 1.0, v41
	v_rcp_f32_e32 v41, v36
	v_add_f32_e32 v36, 1.0, v37
	v_rcp_f32_e32 v44, v36
	v_pk_mul_f32 v[38:39], v[38:39], s[68:69] op_sel_hi:[1,0]
	v_pk_mul_f32 v[36:37], v[42:43], s[68:69] op_sel_hi:[1,0]
	v_mul_f32_e32 v42, v41, v72
	v_mul_f32_e32 v43, v44, v40
	v_lshl_add_u64 v[40:41], v[60:61], 0, v[50:51]
	global_store_dwordx4 v[40:41], v[46:49], off
	global_store_dwordx4 v[40:41], v[36:39], off offset:16
	v_cvt_pk_bf16_f32 v34, v34, v66
	v_cvt_pk_bf16_f32 v35, v35, v42
	s_nop 1
	v_lshl_add_u64 v[38:39], v[148:149], 1, v[58:59]
	v_cvt_pk_bf16_f32 v36, v67, v71
	v_cvt_pk_bf16_f32 v37, v57, v43
	global_store_dwordx4 v[38:39], v[34:37], off offset:256
	s_and_b64 vcc, exec, s[90:91]
	s_cbranch_vccz .LBB0_542

.LBB0_560:
	v_ashrrev_i32_e32 v45, 31, v44
	s_nop 0
	v_lshlrev_b64 v[34:35], 11, v[44:45]
	s_and_b64 vcc, exec, s[0:1]
	v_lshl_add_u64 v[42:43], s[10:11], 0, v[42:43]
	v_lshl_add_u64 v[44:45], v[34:35], 2, s[12:13]
	s_cbranch_vccz .LBB0_562
	v_lshl_add_u64 v[48:49], v[148:149], 2, s[2:3]
	v_lshl_add_u64 v[34:35], s[14:15], 0, v[48:49]
	v_mov_b32_e32 v38, v206
	v_mov_b32_e32 v39, v207
	v_mov_b32_e32 v40, v208
	v_mov_b32_e32 v41, v209
	v_mov_b32_e32 v34, v210
	v_mov_b32_e32 v35, v211
	v_mov_b32_e32 v36, v212
	v_mov_b32_e32 v37, v213
	v_max_f32_e32 v47, v30, v30
	v_mul_f32_e64 v51, |v30|, s82
	v_mul_f32_e64 v53, |v26|, s82
	v_min_f32_e32 v50, 0, v47
	v_exp_f32_e32 v47, v51
	v_max_f32_e32 v54, v31, v31
	v_mul_f32_e64 v55, |v31|, s82
	v_mul_f32_e64 v56, |v27|, s82
	v_exp_f32_e32 v53, v53
	v_max_f32_e32 v52, v26, v26
	v_mul_f32_e32 v26, 0x3fb8aa3b, v26
	v_min_f32_e32 v51, 0, v54
	v_exp_f32_e32 v54, v55
	v_exp_f32_e32 v55, v56
	v_exp_f32_e32 v26, v26
	v_add_f32_e32 v47, 1.0, v47
	v_add_f32_e32 v53, 1.0, v53
	v_cmp_gt_f32_e32 vcc, s81, v47
	v_add_f32_e32 v54, 1.0, v54
	v_add_f32_e32 v57, 1.0, v55
	v_cndmask_b32_e64 v55, 0, 32, vcc
	v_cmp_gt_f32_e64 s[4:5], s81, v53
	v_add_f32_e32 v26, 1.0, v26
	v_cmp_gt_f32_e64 s[6:7], s81, v54
	v_cndmask_b32_e64 v56, 0, 32, s[4:5]
	v_ldexp_f32 v47, v47, v55
	v_rcp_f32_e32 v58, v26
	v_cndmask_b32_e64 v26, 0, 32, s[6:7]
	v_ldexp_f32 v53, v53, v56
	v_log_f32_e32 v47, v47
	v_ldexp_f32 v26, v54, v26
	v_log_f32_e32 v53, v53
	v_log_f32_e32 v26, v26
	v_mul_f32_e32 v54, 0x3f317217, v47
	v_fma_f32 v54, v47, s65, -v54
	v_mul_f32_e32 v60, 0x3f317217, v53
	v_mul_f32_e32 v61, 0x3f317217, v26
	v_fma_f32 v60, v53, s65, -v60
	v_fmac_f32_e32 v54, 0x3377d1cf, v47
	v_cndmask_b32_e32 v55, 0, v203, vcc
	v_fma_f32 v61, v26, s65, -v61
	v_fmac_f32_e32 v60, 0x3377d1cf, v53
	v_fmac_f32_e32 v54, 0x3f317217, v47
	v_cmp_lt_f32_e64 vcc, |v47|, s56
	v_mul_f32_e32 v30, 0x3fb8aa3b, v30
	v_fmac_f32_e32 v61, 0x3377d1cf, v26
	v_fmac_f32_e32 v60, 0x3f317217, v53
	v_cndmask_b32_e32 v47, v47, v54, vcc
	v_cmp_lt_f32_e64 vcc, |v53|, s56
	v_exp_f32_e32 v30, v30
	v_fmac_f32_e32 v61, 0x3f317217, v26
	v_cndmask_b32_e32 v53, v53, v60, vcc
	v_cmp_lt_f32_e64 vcc, |v26|, s56
	v_cndmask_b32_e64 v59, 0, v203, s[6:7]
	v_sub_f32_e32 v54, v47, v55
	v_cndmask_b32_e32 v26, v26, v61, vcc
	v_sub_f32_e32 v55, v26, v59
	v_pk_add_f32 v[50:51], v[50:51], v[54:55] neg_lo:[0,1] neg_hi:[0,1]
	v_add_f32_e32 v30, 1.0, v30
	v_cndmask_b32_e64 v56, 0, v203, s[4:5]
	v_mul_f32_e32 v26, 0x3fb8aa3b, v50
	v_rcp_f32_e32 v30, v30
	v_sub_f32_e32 v56, v53, v56
	v_exp_f32_e32 v53, v26
	v_mul_f32_e32 v47, 0x3fb8aa3b, v51
	v_exp_f32_e32 v47, v47
	v_min_f32_e32 v52, 0, v52
	v_mul_f32_e32 v31, 0x3fb8aa3b, v31
	v_exp_f32_e32 v31, v31
	v_sub_f32_e32 v54, 1.0, v38
	v_mul_f32_e32 v26, v30, v54
	v_fma_f32 v30, v53, v54, v38
	v_cmp_gt_f32_e64 s[4:5], s81, v30
	v_sub_f32_e32 v59, 1.0, v39
	v_fma_f32 v47, v47, v59, v39
	v_cndmask_b32_e64 v53, 0, 32, s[4:5]
	v_ldexp_f32 v30, v30, v53
	v_log_f32_e32 v30, v30
	v_cmp_gt_f32_e32 vcc, s81, v47
	v_cndmask_b32_e64 v53, 0, v203, s[4:5]
	v_sub_f32_e32 v55, 1.0, v34
	v_cndmask_b32_e64 v54, 0, 32, vcc
	v_ldexp_f32 v47, v47, v54
	v_mul_f32_e32 v54, 0x3f317217, v30
	v_fma_f32 v54, v30, s65, -v54
	v_fmac_f32_e32 v54, 0x3377d1cf, v30
	v_fmac_f32_e32 v54, 0x3f317217, v30
	v_cmp_lt_f32_e64 s[4:5], |v30|, s56
	v_log_f32_e32 v47, v47
	v_mul_f32_e32 v60, v58, v55
	v_cndmask_b32_e64 v30, v30, v54, s[4:5]
	v_cmp_gt_f32_e64 s[4:5], s81, v57
	v_sub_f32_e32 v61, v30, v53
	v_max_f32_e32 v53, v27, v27
	v_cndmask_b32_e64 v30, 0, 32, s[4:5]
	v_ldexp_f32 v30, v57, v30
	v_log_f32_e32 v30, v30
	v_min_f32_e32 v53, 0, v53
	v_mul_f32_e32 v58, 0x3f317217, v47
	v_fma_f32 v58, v47, s65, -v58
	v_mul_f32_e32 v54, 0x3f317217, v30
	v_fma_f32 v54, v30, s65, -v54
	v_fmac_f32_e32 v54, 0x3377d1cf, v30
	v_fmac_f32_e32 v54, 0x3f317217, v30
	v_cmp_lt_f32_e64 s[6:7], |v30|, s56
	v_fmac_f32_e32 v58, 0x3377d1cf, v47
	v_fmac_f32_e32 v58, 0x3f317217, v47
	v_cndmask_b32_e64 v30, v30, v54, s[6:7]
	v_cndmask_b32_e64 v54, 0, v203, s[4:5]
	v_sub_f32_e32 v57, v30, v54
	v_pk_add_f32 v[52:53], v[52:53], v[56:57] neg_lo:[0,1] neg_hi:[0,1]
	v_cmp_lt_f32_e64 s[4:5], |v47|, s56
	v_mul_f32_e32 v30, 0x3fb8aa3b, v52
	v_exp_f32_e32 v30, v30
	v_mul_f32_e32 v56, 0x3fb8aa3b, v53
	v_cndmask_b32_e64 v47, v47, v58, s[4:5]
	v_exp_f32_e32 v56, v56
	v_fma_f32 v30, v30, v55, v34
	v_cmp_gt_f32_e64 s[4:5], s81, v30
	v_mul_f32_e32 v27, 0x3fb8aa3b, v27
	v_exp_f32_e32 v27, v27
	v_cndmask_b32_e64 v54, 0, 32, s[4:5]
	v_ldexp_f32 v30, v30, v54
	v_cndmask_b32_e32 v54, 0, v203, vcc
	v_log_f32_e32 v30, v30
	v_sub_f32_e32 v47, v47, v54
	v_sub_f32_e32 v54, 1.0, v35
	v_fma_f32 v56, v56, v54, v35
	v_cmp_gt_f32_e32 vcc, s81, v56
	v_mul_f32_e32 v55, 0x3f317217, v30
	v_fma_f32 v55, v30, s65, -v55
	v_cndmask_b32_e64 v57, 0, 32, vcc
	v_ldexp_f32 v56, v56, v57
	v_log_f32_e32 v56, v56
	v_fmac_f32_e32 v55, 0x3377d1cf, v30
	v_fmac_f32_e32 v55, 0x3f317217, v30
	v_cmp_lt_f32_e64 s[6:7], |v30|, s56
	v_add_f32_e32 v27, 1.0, v27
	v_rcp_f32_e32 v27, v27
	v_cndmask_b32_e64 v30, v30, v55, s[6:7]
	v_cndmask_b32_e64 v55, 0, v203, s[4:5]
	v_sub_f32_e32 v62, v30, v55
	v_mul_f32_e32 v30, 0x3f317217, v56
	v_fma_f32 v30, v56, s65, -v30
	v_fmac_f32_e32 v30, 0x3377d1cf, v56
	v_fmac_f32_e32 v30, 0x3f317217, v56
	v_cmp_lt_f32_e64 s[4:5], |v56|, s56
	v_cndmask_b32_e32 v55, 0, v203, vcc
	v_mul_f32_e32 v65, v27, v54
	v_cndmask_b32_e64 v30, v56, v30, s[4:5]
	v_sub_f32_e32 v63, v30, v55
	v_add_f32_e32 v30, 1.0, v31
	v_mul_f32_e64 v31, |v32|, s82
	v_rcp_f32_e32 v30, v30
	v_exp_f32_e32 v31, v31
	v_max_f32_e32 v27, v32, v32
	v_mul_f32_e64 v54, |v28|, s82
	v_mul_f32_e32 v64, v30, v59
	v_add_f32_e32 v30, 1.0, v31
	v_cmp_gt_f32_e32 vcc, s81, v30
	v_exp_f32_e32 v55, v54
	v_sub_f32_e32 v57, 1.0, v40
	v_cndmask_b32_e64 v31, 0, 32, vcc
	v_ldexp_f32 v30, v30, v31
	v_log_f32_e32 v31, v30
	v_min_f32_e32 v30, 0, v27
	v_sub_f32_e32 v66, 1.0, v41
	v_mul_f32_e32 v27, 0x3f317217, v31
	v_fma_f32 v27, v31, s65, -v27
	v_fmac_f32_e32 v27, 0x3377d1cf, v31
	v_fmac_f32_e32 v27, 0x3f317217, v31
	v_cmp_lt_f32_e64 s[4:5], |v31|, s56
	s_nop 1
	v_cndmask_b32_e64 v27, v31, v27, s[4:5]
	v_cndmask_b32_e32 v31, 0, v203, vcc
	v_sub_f32_e32 v54, v27, v31
	v_add_f32_e32 v27, 1.0, v55
	v_cmp_gt_f32_e32 vcc, s81, v27
	s_nop 1
	v_cndmask_b32_e64 v31, 0, 32, vcc
	v_ldexp_f32 v27, v27, v31
	v_log_f32_e32 v27, v27
	v_max_f32_e32 v31, v28, v28
	v_min_f32_e32 v56, 0, v31
	v_mul_f32_e32 v28, 0x3fb8aa3b, v28
	v_mul_f32_e32 v31, 0x3f317217, v27
	v_fma_f32 v31, v27, s65, -v31
	v_fmac_f32_e32 v31, 0x3377d1cf, v27
	v_fmac_f32_e32 v31, 0x3f317217, v27
	v_cmp_lt_f32_e64 s[4:5], |v27|, s56
	v_exp_f32_e32 v28, v28
	s_nop 0
	v_cndmask_b32_e64 v27, v27, v31, s[4:5]
	v_cndmask_b32_e32 v31, 0, v203, vcc
	v_sub_f32_e32 v58, v27, v31
	v_mul_f32_e64 v31, |v33|, s82
	v_exp_f32_e32 v31, v31
	v_mul_f32_e32 v27, 0x3fb8aa3b, v32
	v_exp_f32_e32 v27, v27
	v_add_f32_e32 v28, 1.0, v28
	v_add_f32_e32 v31, 1.0, v31
	v_cmp_gt_f32_e32 vcc, s81, v31
	v_add_f32_e32 v27, 1.0, v27
	v_rcp_f32_e32 v27, v27
	v_cndmask_b32_e64 v55, 0, 32, vcc
	v_ldexp_f32 v31, v31, v55
	v_log_f32_e32 v55, v31
	v_max_f32_e32 v31, v33, v33
	v_min_f32_e32 v31, 0, v31
	v_mul_f32_e32 v27, v27, v57
	v_mul_f32_e32 v59, 0x3f317217, v55
	v_fma_f32 v59, v55, s65, -v59
	v_fmac_f32_e32 v59, 0x3377d1cf, v55
	v_fmac_f32_e32 v59, 0x3f317217, v55
	v_cmp_lt_f32_e64 s[4:5], |v55|, s56
	v_rcp_f32_e32 v28, v28
	v_sub_f32_e32 v32, 1.0, v36
	v_cndmask_b32_e64 v55, v55, v59, s[4:5]
	v_cndmask_b32_e32 v59, 0, v203, vcc
	v_sub_f32_e32 v55, v55, v59
	v_pk_add_f32 v[30:31], v[30:31], v[54:55] neg_lo:[0,1] neg_hi:[0,1]
	s_nop 0
	v_mul_f32_e32 v54, 0x3fb8aa3b, v30
	v_exp_f32_e32 v54, v54
	s_nop 0
	v_fma_f32 v54, v54, v57, v40
	v_mul_f32_e32 v57, 0x3fb8aa3b, v31
	v_cmp_gt_f32_e32 vcc, s81, v54
	v_exp_f32_e32 v57, v57
	s_nop 0
	v_cndmask_b32_e64 v55, 0, 32, vcc
	v_ldexp_f32 v54, v54, v55
	v_log_f32_e32 v54, v54
	v_fma_f32 v57, v57, v66, v41
	v_cmp_gt_f32_e64 s[4:5], s81, v57
	v_mul_f32_e32 v55, v28, v32
	v_mul_f32_e32 v28, 0x3f317217, v54
	v_cndmask_b32_e64 v59, 0, 32, s[4:5]
	v_ldexp_f32 v57, v57, v59
	v_fma_f32 v28, v54, s65, -v28
	v_log_f32_e32 v57, v57
	v_fmac_f32_e32 v28, 0x3377d1cf, v54
	v_fmac_f32_e32 v28, 0x3f317217, v54
	v_cmp_lt_f32_e64 s[6:7], |v54|, s56
	v_mul_f32_e64 v59, |v29|, s82
	v_exp_f32_e32 v59, v59
	v_cndmask_b32_e64 v28, v54, v28, s[6:7]
	v_cndmask_b32_e32 v54, 0, v203, vcc
	v_sub_f32_e32 v28, v28, v54
	v_mul_f32_e32 v54, 0x3f317217, v57
	v_fma_f32 v54, v57, s65, -v54
	v_fmac_f32_e32 v54, 0x3377d1cf, v57
	v_fmac_f32_e32 v54, 0x3f317217, v57
	v_cmp_lt_f32_e64 vcc, |v57|, s56
	s_nop 1
	v_cndmask_b32_e32 v54, v57, v54, vcc
	v_cmp_lt_f32_e32 vcc, 0, v39
	v_cndmask_b32_e64 v57, 0, v203, s[4:5]
	v_cmp_lt_f32_e64 s[4:5], 0, v38
	v_cndmask_b32_e32 v39, v51, v47, vcc
	v_add_f32_e32 v47, 1.0, v59
	v_cmp_gt_f32_e32 vcc, s81, v47
	v_cndmask_b32_e64 v38, v50, v61, s[4:5]
	v_max_f32_e32 v50, v29, v29
	v_cndmask_b32_e64 v51, 0, 32, vcc
	v_ldexp_f32 v47, v47, v51
	v_log_f32_e32 v47, v47
	v_sub_f32_e32 v54, v54, v57
	v_min_f32_e32 v57, 0, v50
	v_mul_f32_e32 v29, 0x3fb8aa3b, v29
	v_mul_f32_e32 v50, 0x3f317217, v47
	v_fma_f32 v50, v47, s65, -v50
	v_fmac_f32_e32 v50, 0x3377d1cf, v47
	v_fmac_f32_e32 v50, 0x3f317217, v47
	v_cmp_lt_f32_e64 s[4:5], |v47|, s56
	v_exp_f32_e32 v29, v29
	v_pk_mul_f32 v[38:39], v[38:39], s[68:69] op_sel_hi:[1,0]
	v_cndmask_b32_e64 v47, v47, v50, s[4:5]
	v_cndmask_b32_e32 v50, 0, v203, vcc
	v_sub_f32_e32 v59, v47, v50
	v_pk_add_f32 v[50:51], v[56:57], v[58:59] neg_lo:[0,1] neg_hi:[0,1]
	v_cmp_lt_f32_e32 vcc, 0, v41
	v_mul_f32_e32 v47, 0x3fb8aa3b, v50
	v_exp_f32_e32 v47, v47
	v_cndmask_b32_e32 v31, v31, v54, vcc
	v_cmp_lt_f32_e32 vcc, 0, v40
	s_nop 1
	v_cndmask_b32_e32 v30, v30, v28, vcc
	v_fma_f32 v28, v47, v32, v36
	v_pk_mul_f32 v[40:41], v[30:31], s[68:69] op_sel_hi:[1,0]
	v_mul_f32_e32 v31, 0x3fb8aa3b, v51
	v_cmp_gt_f32_e32 vcc, s81, v28
	v_exp_f32_e32 v31, v31
	s_nop 0
	v_cndmask_b32_e64 v32, 0, 32, vcc
	v_ldexp_f32 v28, v28, v32
	v_log_f32_e32 v28, v28
	v_sub_f32_e32 v32, 1.0, v37
	v_fma_f32 v31, v31, v32, v37
	v_cmp_gt_f32_e64 s[4:5], s81, v31
	v_mul_f32_e32 v30, 0x3f317217, v28
	v_fma_f32 v30, v28, s65, -v30
	v_cndmask_b32_e64 v47, 0, 32, s[4:5]
	v_ldexp_f32 v31, v31, v47
	v_log_f32_e32 v31, v31
	v_fmac_f32_e32 v30, 0x3377d1cf, v28
	v_fmac_f32_e32 v30, 0x3f317217, v28
	v_cmp_lt_f32_e64 s[6:7], |v28|, s56
	s_nop 1
	v_cndmask_b32_e64 v28, v28, v30, s[6:7]
	v_cndmask_b32_e32 v30, 0, v203, vcc
	v_sub_f32_e32 v28, v28, v30
	v_mul_f32_e32 v30, 0x3f317217, v31
	v_fma_f32 v30, v31, s65, -v30
	v_fmac_f32_e32 v30, 0x3377d1cf, v31
	v_fmac_f32_e32 v30, 0x3f317217, v31
	v_cmp_lt_f32_e64 vcc, |v31|, s56
	s_nop 1
	v_cndmask_b32_e32 v30, v31, v30, vcc
	v_cmp_lt_f32_e32 vcc, 0, v35
	v_cndmask_b32_e64 v31, 0, v203, s[4:5]
	v_sub_f32_e32 v30, v30, v31
	v_cndmask_b32_e32 v35, v53, v63, vcc
	v_cmp_lt_f32_e32 vcc, 0, v34
	s_nop 1
	v_cndmask_b32_e32 v34, v52, v62, vcc
	v_cmp_lt_f32_e32 vcc, 0, v37
	s_nop 1
	v_cndmask_b32_e32 v31, v51, v30, vcc
	v_mul_f32_e32 v30, 0x3fb8aa3b, v33
	v_exp_f32_e32 v33, v30
	v_cmp_lt_f32_e32 vcc, 0, v36
	s_nop 1
	v_cndmask_b32_e32 v30, v50, v28, vcc
	v_add_f32_e32 v28, 1.0, v33
	v_rcp_f32_e32 v33, v28
	v_add_f32_e32 v28, 1.0, v29
	v_rcp_f32_e32 v36, v28
	v_pk_mul_f32 v[30:31], v[30:31], s[68:69] op_sel_hi:[1,0]
	v_pk_mul_f32 v[28:29], v[34:35], s[68:69] op_sel_hi:[1,0]
	v_mul_f32_e32 v34, v33, v66
	v_mul_f32_e32 v35, v36, v32
	v_lshl_add_u64 v[32:33], v[44:45], 0, v[48:49]
	global_store_dwordx4 v[32:33], v[38:41], off
	global_store_dwordx4 v[32:33], v[28:31], off offset:16
	v_cvt_pk_bf16_f32 v26, v26, v64
	v_cvt_pk_bf16_f32 v27, v27, v34
	s_nop 1
	v_lshl_add_u64 v[30:31], v[148:149], 1, v[42:43]
	v_cvt_pk_bf16_f32 v28, v60, v65
	v_cvt_pk_bf16_f32 v29, v55, v35
	global_store_dwordx4 v[30:31], v[26:29], off

.LBB0_573:
	v_lshl_add_u64 v[34:35], v[148:149], 2, s[26:27]
	v_lshl_add_u64 v[26:27], s[14:15], 0, v[34:35]
	v_mov_b32_e32 v30, v214
	v_mov_b32_e32 v31, v215
	v_mov_b32_e32 v32, v216
	v_mov_b32_e32 v33, v217
	v_mov_b32_e32 v26, v218
	v_mov_b32_e32 v27, v219
	v_mov_b32_e32 v28, v220
	v_mov_b32_e32 v29, v221
	v_mul_f32_e64 v37, |v22|, s82
	v_mul_f32_e64 v39, |v18|, s82
	v_max_f32_e32 v40, v23, v23
	v_mul_f32_e64 v41, |v23|, s82
	v_exp_f32_e32 v47, v37
	v_max_f32_e32 v38, v18, v18
	v_mul_f32_e32 v18, 0x3fb8aa3b, v18
	v_mul_f32_e64 v46, |v19|, s82
	v_exp_f32_e32 v39, v39
	v_min_f32_e32 v37, 0, v40
	v_exp_f32_e32 v40, v41
	v_exp_f32_e32 v18, v18
	v_exp_f32_e32 v41, v46
	v_add_f32_e32 v46, 1.0, v47
	v_add_f32_e32 v39, 1.0, v39
	v_add_f32_e32 v40, 1.0, v40
	v_cmp_gt_f32_e32 vcc, s81, v46
	v_add_f32_e32 v18, 1.0, v18
	v_add_f32_e32 v47, 1.0, v41
	v_cndmask_b32_e64 v41, 0, 32, vcc
	v_cmp_gt_f32_e64 s[4:5], s81, v39
	v_cmp_gt_f32_e64 s[6:7], s81, v40
	v_rcp_f32_e32 v49, v18
	v_cndmask_b32_e64 v48, 0, 32, s[4:5]
	v_cndmask_b32_e64 v18, 0, 32, s[6:7]
	v_ldexp_f32 v41, v46, v41
	v_ldexp_f32 v39, v39, v48
	v_ldexp_f32 v18, v40, v18
	v_log_f32_e32 v40, v41
	v_log_f32_e32 v39, v39
	v_log_f32_e32 v18, v18
	v_cndmask_b32_e32 v46, 0, v203, vcc
	v_mul_f32_e32 v50, 0x3f317217, v40
	v_mul_f32_e32 v51, 0x3f317217, v39
	v_fma_f32 v50, v40, s65, -v50
	v_mul_f32_e32 v52, 0x3f317217, v18
	v_fma_f32 v51, v39, s65, -v51
	v_fmac_f32_e32 v50, 0x3377d1cf, v40
	v_fma_f32 v52, v18, s65, -v52
	v_fmac_f32_e32 v51, 0x3377d1cf, v39
	v_fmac_f32_e32 v50, 0x3f317217, v40
	v_cmp_lt_f32_e64 vcc, |v40|, s56
	v_max_f32_e32 v36, v22, v22
	v_mul_f32_e32 v22, 0x3fb8aa3b, v22
	v_fmac_f32_e32 v52, 0x3377d1cf, v18
	v_fmac_f32_e32 v51, 0x3f317217, v39
	v_cndmask_b32_e32 v40, v40, v50, vcc
	v_cmp_lt_f32_e64 vcc, |v39|, s56
	v_exp_f32_e32 v22, v22
	v_fmac_f32_e32 v52, 0x3f317217, v18
	v_cndmask_b32_e32 v39, v39, v51, vcc
	v_cmp_lt_f32_e64 vcc, |v18|, s56
	v_cndmask_b32_e64 v41, 0, v203, s[6:7]
	v_min_f32_e32 v36, 0, v36
	v_cndmask_b32_e32 v18, v18, v52, vcc
	v_sub_f32_e32 v40, v40, v46
	v_sub_f32_e32 v41, v18, v41
	v_pk_add_f32 v[36:37], v[36:37], v[40:41] neg_lo:[0,1] neg_hi:[0,1]
	v_add_f32_e32 v22, 1.0, v22
	v_mul_f32_e32 v18, 0x3fb8aa3b, v36
	v_rcp_f32_e32 v22, v22
	v_exp_f32_e32 v40, v18
	v_cndmask_b32_e64 v48, 0, v203, s[4:5]
	v_sub_f32_e32 v46, v39, v48
	v_mul_f32_e32 v39, 0x3fb8aa3b, v37
	v_exp_f32_e32 v39, v39
	v_min_f32_e32 v38, 0, v38
	v_mul_f32_e32 v23, 0x3fb8aa3b, v23
	v_exp_f32_e32 v23, v23
	v_sub_f32_e32 v41, 1.0, v30
	v_mul_f32_e32 v18, v22, v41
	v_fma_f32 v22, v40, v41, v30
	v_cmp_gt_f32_e64 s[4:5], s81, v22
	v_sub_f32_e32 v50, 1.0, v31
	v_fma_f32 v39, v39, v50, v31
	v_cndmask_b32_e64 v40, 0, 32, s[4:5]
	v_ldexp_f32 v22, v22, v40
	v_log_f32_e32 v22, v22
	v_cmp_gt_f32_e32 vcc, s81, v39
	v_sub_f32_e32 v48, 1.0, v26
	v_mul_f32_e32 v51, v49, v48
	v_cndmask_b32_e64 v41, 0, 32, vcc
	v_ldexp_f32 v39, v39, v41
	v_mul_f32_e32 v41, 0x3f317217, v22
	v_fma_f32 v41, v22, s65, -v41
	v_fmac_f32_e32 v41, 0x3377d1cf, v22
	v_log_f32_e32 v40, v39
	v_cndmask_b32_e64 v39, 0, v203, s[4:5]
	v_fmac_f32_e32 v41, 0x3f317217, v22
	v_cmp_lt_f32_e64 s[4:5], |v22|, s56
	v_mul_f32_e32 v49, 0x3f317217, v40
	v_fma_f32 v49, v40, s65, -v49
	v_cndmask_b32_e64 v22, v22, v41, s[4:5]
	v_cmp_gt_f32_e64 s[4:5], s81, v47
	v_sub_f32_e32 v52, v22, v39
	v_max_f32_e32 v39, v19, v19
	v_cndmask_b32_e64 v22, 0, 32, s[4:5]
	v_ldexp_f32 v22, v47, v22
	v_log_f32_e32 v22, v22
	v_min_f32_e32 v39, 0, v39
	v_fmac_f32_e32 v49, 0x3377d1cf, v40
	v_fmac_f32_e32 v49, 0x3f317217, v40
	v_mul_f32_e32 v41, 0x3f317217, v22
	v_fma_f32 v41, v22, s65, -v41
	v_fmac_f32_e32 v41, 0x3377d1cf, v22
	v_fmac_f32_e32 v41, 0x3f317217, v22
	v_cmp_lt_f32_e64 s[6:7], |v22|, s56
	v_mul_f32_e32 v19, 0x3fb8aa3b, v19
	v_exp_f32_e32 v19, v19
	v_cndmask_b32_e64 v22, v22, v41, s[6:7]
	v_cndmask_b32_e64 v41, 0, v203, s[4:5]
	v_sub_f32_e32 v47, v22, v41
	v_pk_add_f32 v[38:39], v[38:39], v[46:47] neg_lo:[0,1] neg_hi:[0,1]
	v_cmp_lt_f32_e64 s[4:5], |v40|, s56
	v_mul_f32_e32 v22, 0x3fb8aa3b, v38
	v_exp_f32_e32 v22, v22
	v_mul_f32_e32 v46, 0x3fb8aa3b, v39
	v_cndmask_b32_e64 v40, v40, v49, s[4:5]
	v_exp_f32_e32 v46, v46
	v_fma_f32 v22, v22, v48, v26
	v_cmp_gt_f32_e64 s[4:5], s81, v22
	v_add_f32_e32 v19, 1.0, v19
	v_rcp_f32_e32 v19, v19
	v_cndmask_b32_e64 v41, 0, 32, s[4:5]
	v_ldexp_f32 v22, v22, v41
	v_cndmask_b32_e32 v41, 0, v203, vcc
	v_log_f32_e32 v22, v22
	v_sub_f32_e32 v47, v40, v41
	v_sub_f32_e32 v40, 1.0, v27
	v_fma_f32 v46, v46, v40, v27
	v_cmp_gt_f32_e32 vcc, s81, v46
	v_mul_f32_e32 v41, 0x3f317217, v22
	v_fma_f32 v41, v22, s65, -v41
	v_cndmask_b32_e64 v48, 0, 32, vcc
	v_ldexp_f32 v46, v46, v48
	v_log_f32_e32 v46, v46
	v_fmac_f32_e32 v41, 0x3377d1cf, v22
	v_fmac_f32_e32 v41, 0x3f317217, v22
	v_cmp_lt_f32_e64 s[6:7], |v22|, s56
	v_mul_f32_e32 v55, v19, v40
	v_max_f32_e32 v19, v24, v24
	v_cndmask_b32_e64 v22, v22, v41, s[6:7]
	v_cndmask_b32_e64 v41, 0, v203, s[4:5]
	v_sub_f32_e32 v53, v22, v41
	v_mul_f32_e32 v22, 0x3f317217, v46
	v_fma_f32 v22, v46, s65, -v22
	v_fmac_f32_e32 v22, 0x3377d1cf, v46
	v_fmac_f32_e32 v22, 0x3f317217, v46
	v_cmp_lt_f32_e64 s[4:5], |v46|, s56
	v_cndmask_b32_e32 v41, 0, v203, vcc
	v_mul_f32_e64 v40, |v20|, s82
	v_cndmask_b32_e64 v22, v46, v22, s[4:5]
	v_sub_f32_e32 v54, v22, v41
	v_add_f32_e32 v22, 1.0, v23
	v_mul_f32_e64 v23, |v24|, s82
	v_rcp_f32_e32 v22, v22
	v_exp_f32_e32 v23, v23
	v_exp_f32_e32 v41, v40
	v_sub_f32_e32 v49, 1.0, v32
	v_mul_f32_e32 v50, v22, v50
	v_add_f32_e32 v22, 1.0, v23
	v_cmp_gt_f32_e32 vcc, s81, v22
	s_nop 1
	v_cndmask_b32_e64 v23, 0, 32, vcc
	v_ldexp_f32 v22, v22, v23
	v_log_f32_e32 v23, v22
	v_min_f32_e32 v22, 0, v19
	v_mul_f32_e32 v19, 0x3f317217, v23
	v_fma_f32 v19, v23, s65, -v19
	v_fmac_f32_e32 v19, 0x3377d1cf, v23
	v_fmac_f32_e32 v19, 0x3f317217, v23
	v_cmp_lt_f32_e64 s[4:5], |v23|, s56
	s_nop 1
	v_cndmask_b32_e64 v19, v23, v19, s[4:5]
	v_cndmask_b32_e32 v23, 0, v203, vcc
	v_sub_f32_e32 v40, v19, v23
	v_add_f32_e32 v19, 1.0, v41
	v_cmp_gt_f32_e32 vcc, s81, v19
	s_nop 1
	v_cndmask_b32_e64 v23, 0, 32, vcc
	v_ldexp_f32 v19, v19, v23
	v_log_f32_e32 v19, v19
	v_max_f32_e32 v23, v20, v20
	v_min_f32_e32 v46, 0, v23
	v_mul_f32_e32 v20, 0x3fb8aa3b, v20
	v_mul_f32_e32 v23, 0x3f317217, v19
	v_fma_f32 v23, v19, s65, -v23
	v_fmac_f32_e32 v23, 0x3377d1cf, v19
	v_fmac_f32_e32 v23, 0x3f317217, v19
	v_cmp_lt_f32_e64 s[4:5], |v19|, s56
	v_exp_f32_e32 v20, v20
	s_nop 0
	v_cndmask_b32_e64 v19, v19, v23, s[4:5]
	v_cndmask_b32_e32 v23, 0, v203, vcc
	v_sub_f32_e32 v48, v19, v23
	v_mul_f32_e64 v23, |v25|, s82
	v_exp_f32_e32 v23, v23
	v_mul_f32_e32 v19, 0x3fb8aa3b, v24
	v_exp_f32_e32 v19, v19
	v_add_f32_e32 v20, 1.0, v20
	v_add_f32_e32 v23, 1.0, v23
	v_cmp_gt_f32_e32 vcc, s81, v23
	v_add_f32_e32 v19, 1.0, v19
	v_rcp_f32_e32 v19, v19
	v_cndmask_b32_e64 v41, 0, 32, vcc
	v_ldexp_f32 v23, v23, v41
	v_log_f32_e32 v41, v23
	v_max_f32_e32 v23, v25, v25
	v_min_f32_e32 v23, 0, v23
	v_mul_f32_e32 v19, v19, v49
	v_mul_f32_e32 v56, 0x3f317217, v41
	v_fma_f32 v56, v41, s65, -v56
	v_fmac_f32_e32 v56, 0x3377d1cf, v41
	v_fmac_f32_e32 v56, 0x3f317217, v41
	v_cmp_lt_f32_e64 s[4:5], |v41|, s56
	v_rcp_f32_e32 v20, v20
	v_sub_f32_e32 v24, 1.0, v28
	v_cndmask_b32_e64 v41, v41, v56, s[4:5]
	v_cndmask_b32_e32 v56, 0, v203, vcc
	v_sub_f32_e32 v41, v41, v56
	v_pk_add_f32 v[22:23], v[22:23], v[40:41] neg_lo:[0,1] neg_hi:[0,1]
	v_sub_f32_e32 v56, 1.0, v33
	v_mul_f32_e32 v40, 0x3fb8aa3b, v22
	v_exp_f32_e32 v40, v40
	s_nop 0
	v_fma_f32 v40, v40, v49, v32
	v_mul_f32_e32 v49, 0x3fb8aa3b, v23
	v_cmp_gt_f32_e32 vcc, s81, v40
	v_exp_f32_e32 v49, v49
	s_nop 0
	v_cndmask_b32_e64 v41, 0, 32, vcc
	v_ldexp_f32 v40, v40, v41
	v_log_f32_e32 v40, v40
	v_fma_f32 v49, v49, v56, v33
	v_cmp_gt_f32_e64 s[4:5], s81, v49
	v_mul_f32_e32 v41, v20, v24
	v_mul_f32_e32 v20, 0x3f317217, v40
	v_cndmask_b32_e64 v57, 0, 32, s[4:5]
	v_ldexp_f32 v49, v49, v57
	v_fma_f32 v20, v40, s65, -v20
	v_log_f32_e32 v49, v49
	v_fmac_f32_e32 v20, 0x3377d1cf, v40
	v_fmac_f32_e32 v20, 0x3f317217, v40
	v_cmp_lt_f32_e64 s[6:7], |v40|, s56
	v_mul_f32_e64 v57, |v21|, s82
	v_exp_f32_e32 v57, v57
	v_cndmask_b32_e64 v20, v40, v20, s[6:7]
	v_cndmask_b32_e32 v40, 0, v203, vcc
	v_sub_f32_e32 v20, v20, v40
	v_mul_f32_e32 v40, 0x3f317217, v49
	v_fma_f32 v40, v49, s65, -v40
	v_fmac_f32_e32 v40, 0x3377d1cf, v49
	v_fmac_f32_e32 v40, 0x3f317217, v49
	v_cmp_lt_f32_e64 vcc, |v49|, s56
	s_nop 1
	v_cndmask_b32_e32 v40, v49, v40, vcc
	v_cmp_lt_f32_e32 vcc, 0, v31
	v_cndmask_b32_e64 v49, 0, v203, s[4:5]
	v_cmp_lt_f32_e64 s[4:5], 0, v30
	v_cndmask_b32_e32 v31, v37, v47, vcc
	v_add_f32_e32 v37, 1.0, v57
	v_cmp_gt_f32_e32 vcc, s81, v37
	v_cndmask_b32_e64 v30, v36, v52, s[4:5]
	v_max_f32_e32 v36, v21, v21
	v_cndmask_b32_e64 v47, 0, 32, vcc
	v_ldexp_f32 v37, v37, v47
	v_log_f32_e32 v37, v37
	v_min_f32_e32 v47, 0, v36
	v_sub_f32_e32 v40, v40, v49
	v_mul_f32_e32 v21, 0x3fb8aa3b, v21
	v_mul_f32_e32 v36, 0x3f317217, v37
	v_fma_f32 v36, v37, s65, -v36
	v_fmac_f32_e32 v36, 0x3377d1cf, v37
	v_fmac_f32_e32 v36, 0x3f317217, v37
	v_cmp_lt_f32_e64 s[4:5], |v37|, s56
	v_exp_f32_e32 v21, v21
	v_pk_mul_f32 v[30:31], v[30:31], s[68:69] op_sel_hi:[1,0]
	v_cndmask_b32_e64 v36, v37, v36, s[4:5]
	v_cndmask_b32_e32 v37, 0, v203, vcc
	v_sub_f32_e32 v49, v36, v37
	v_pk_add_f32 v[36:37], v[46:47], v[48:49] neg_lo:[0,1] neg_hi:[0,1]
	v_cmp_lt_f32_e32 vcc, 0, v33
	v_mul_f32_e32 v46, 0x3fb8aa3b, v36
	v_exp_f32_e32 v46, v46
	v_cndmask_b32_e32 v23, v23, v40, vcc
	v_cmp_lt_f32_e32 vcc, 0, v32
	s_nop 1
	v_cndmask_b32_e32 v22, v22, v20, vcc
	v_fma_f32 v20, v46, v24, v28
	v_pk_mul_f32 v[32:33], v[22:23], s[68:69] op_sel_hi:[1,0]
	v_mul_f32_e32 v23, 0x3fb8aa3b, v37
	v_cmp_gt_f32_e32 vcc, s81, v20
	v_exp_f32_e32 v23, v23
	s_nop 0
	v_cndmask_b32_e64 v24, 0, 32, vcc
	v_ldexp_f32 v20, v20, v24
	v_log_f32_e32 v20, v20
	v_sub_f32_e32 v24, 1.0, v29
	v_fma_f32 v23, v23, v24, v29
	v_cmp_gt_f32_e64 s[4:5], s81, v23
	v_mul_f32_e32 v22, 0x3f317217, v20
	v_fma_f32 v22, v20, s65, -v22
	v_cndmask_b32_e64 v40, 0, 32, s[4:5]
	v_ldexp_f32 v23, v23, v40
	v_log_f32_e32 v23, v23
	v_fmac_f32_e32 v22, 0x3377d1cf, v20
	v_fmac_f32_e32 v22, 0x3f317217, v20
	v_cmp_lt_f32_e64 s[6:7], |v20|, s56
	s_nop 1
	v_cndmask_b32_e64 v20, v20, v22, s[6:7]
	v_cndmask_b32_e32 v22, 0, v203, vcc
	v_sub_f32_e32 v20, v20, v22
	v_mul_f32_e32 v22, 0x3f317217, v23
	v_fma_f32 v22, v23, s65, -v22
	v_fmac_f32_e32 v22, 0x3377d1cf, v23
	v_fmac_f32_e32 v22, 0x3f317217, v23
	v_cmp_lt_f32_e64 vcc, |v23|, s56
	s_nop 1
	v_cndmask_b32_e32 v22, v23, v22, vcc
	v_cmp_lt_f32_e32 vcc, 0, v27
	v_cndmask_b32_e64 v23, 0, v203, s[4:5]
	v_sub_f32_e32 v22, v22, v23
	v_cndmask_b32_e32 v27, v39, v54, vcc
	v_cmp_lt_f32_e32 vcc, 0, v26
	s_nop 1
	v_cndmask_b32_e32 v26, v38, v53, vcc
	v_cmp_lt_f32_e32 vcc, 0, v29
	s_nop 1
	v_cndmask_b32_e32 v23, v37, v22, vcc
	v_mul_f32_e32 v22, 0x3fb8aa3b, v25
	v_exp_f32_e32 v25, v22
	v_cmp_lt_f32_e32 vcc, 0, v28
	s_nop 1
	v_cndmask_b32_e32 v22, v36, v20, vcc
	v_add_f32_e32 v20, 1.0, v25
	v_rcp_f32_e32 v25, v20
	v_add_f32_e32 v20, 1.0, v21
	v_rcp_f32_e32 v28, v20
	v_pk_mul_f32 v[22:23], v[22:23], s[68:69] op_sel_hi:[1,0]
	v_pk_mul_f32 v[20:21], v[26:27], s[68:69] op_sel_hi:[1,0]
	v_mul_f32_e32 v26, v25, v56
	v_mul_f32_e32 v27, v28, v24
	v_lshl_add_u64 v[24:25], v[44:45], 0, v[34:35]
	global_store_dwordx4 v[24:25], v[30:33], off
	global_store_dwordx4 v[24:25], v[20:23], off offset:16
	v_cvt_pk_bf16_f32 v18, v18, v50
	v_cvt_pk_bf16_f32 v19, v19, v26
	s_nop 1
	v_lshl_add_u64 v[22:23], v[148:149], 1, v[42:43]
	v_cvt_pk_bf16_f32 v20, v51, v55
	v_cvt_pk_bf16_f32 v21, v41, v27
	global_store_dwordx4 v[22:23], v[18:21], off offset:256
	s_and_b64 vcc, exec, s[90:91]
	s_cbranch_vccz .LBB0_565

.LBB0_583:
	v_ashrrev_i32_e32 v29, 31, v28
	s_nop 0
	v_lshlrev_b64 v[18:19], 11, v[28:29]
	s_and_b64 vcc, exec, s[0:1]
	v_lshl_add_u64 v[26:27], s[10:11], 0, v[26:27]
	v_lshl_add_u64 v[28:29], v[18:19], 2, s[12:13]
	s_cbranch_vccz .LBB0_585
	v_lshl_add_u64 v[32:33], v[148:149], 2, s[2:3]
	v_lshl_add_u64 v[18:19], s[14:15], 0, v[32:33]
	v_mov_b32_e32 v22, v206
	v_mov_b32_e32 v23, v207
	v_mov_b32_e32 v24, v208
	v_mov_b32_e32 v25, v209
	v_mov_b32_e32 v18, v210
	v_mov_b32_e32 v19, v211
	v_mov_b32_e32 v20, v212
	v_mov_b32_e32 v21, v213
	v_max_f32_e32 v31, v14, v14
	v_mul_f32_e64 v35, |v14|, s82
	v_mul_f32_e64 v37, |v10|, s82
	v_min_f32_e32 v34, 0, v31
	v_exp_f32_e32 v31, v35
	v_max_f32_e32 v38, v15, v15
	v_mul_f32_e64 v39, |v15|, s82
	v_mul_f32_e64 v40, |v11|, s82
	v_exp_f32_e32 v37, v37
	v_max_f32_e32 v36, v10, v10
	v_mul_f32_e32 v10, 0x3fb8aa3b, v10
	v_min_f32_e32 v35, 0, v38
	v_exp_f32_e32 v38, v39
	v_exp_f32_e32 v39, v40
	v_exp_f32_e32 v10, v10
	v_add_f32_e32 v31, 1.0, v31
	v_add_f32_e32 v37, 1.0, v37
	v_cmp_gt_f32_e32 vcc, s81, v31
	v_add_f32_e32 v38, 1.0, v38
	v_add_f32_e32 v41, 1.0, v39
	v_cndmask_b32_e64 v39, 0, 32, vcc
	v_cmp_gt_f32_e64 s[4:5], s81, v37
	v_add_f32_e32 v10, 1.0, v10
	v_cmp_gt_f32_e64 s[6:7], s81, v38
	v_cndmask_b32_e64 v40, 0, 32, s[4:5]
	v_ldexp_f32 v31, v31, v39
	v_rcp_f32_e32 v42, v10
	v_cndmask_b32_e64 v10, 0, 32, s[6:7]
	v_ldexp_f32 v37, v37, v40
	v_log_f32_e32 v31, v31
	v_ldexp_f32 v10, v38, v10
	v_log_f32_e32 v37, v37
	v_log_f32_e32 v10, v10
	v_mul_f32_e32 v38, 0x3f317217, v31
	v_fma_f32 v38, v31, s65, -v38
	v_mul_f32_e32 v44, 0x3f317217, v37
	v_mul_f32_e32 v45, 0x3f317217, v10
	v_fma_f32 v44, v37, s65, -v44
	v_fmac_f32_e32 v38, 0x3377d1cf, v31
	v_cndmask_b32_e32 v39, 0, v203, vcc
	v_fma_f32 v45, v10, s65, -v45
	v_fmac_f32_e32 v44, 0x3377d1cf, v37
	v_fmac_f32_e32 v38, 0x3f317217, v31
	v_cmp_lt_f32_e64 vcc, |v31|, s56
	v_mul_f32_e32 v14, 0x3fb8aa3b, v14
	v_fmac_f32_e32 v45, 0x3377d1cf, v10
	v_fmac_f32_e32 v44, 0x3f317217, v37
	v_cndmask_b32_e32 v31, v31, v38, vcc
	v_cmp_lt_f32_e64 vcc, |v37|, s56
	v_exp_f32_e32 v14, v14
	v_fmac_f32_e32 v45, 0x3f317217, v10
	v_cndmask_b32_e32 v37, v37, v44, vcc
	v_cmp_lt_f32_e64 vcc, |v10|, s56
	v_cndmask_b32_e64 v43, 0, v203, s[6:7]
	v_sub_f32_e32 v38, v31, v39
	v_cndmask_b32_e32 v10, v10, v45, vcc
	v_sub_f32_e32 v39, v10, v43
	v_pk_add_f32 v[34:35], v[34:35], v[38:39] neg_lo:[0,1] neg_hi:[0,1]
	v_add_f32_e32 v14, 1.0, v14
	v_cndmask_b32_e64 v40, 0, v203, s[4:5]
	v_mul_f32_e32 v10, 0x3fb8aa3b, v34
	v_rcp_f32_e32 v14, v14
	v_sub_f32_e32 v40, v37, v40
	v_exp_f32_e32 v37, v10
	v_mul_f32_e32 v31, 0x3fb8aa3b, v35
	v_exp_f32_e32 v31, v31
	v_min_f32_e32 v36, 0, v36
	v_mul_f32_e32 v15, 0x3fb8aa3b, v15
	v_exp_f32_e32 v15, v15
	v_sub_f32_e32 v38, 1.0, v22
	v_mul_f32_e32 v10, v14, v38
	v_fma_f32 v14, v37, v38, v22
	v_cmp_gt_f32_e64 s[4:5], s81, v14
	v_sub_f32_e32 v43, 1.0, v23
	v_fma_f32 v31, v31, v43, v23
	v_cndmask_b32_e64 v37, 0, 32, s[4:5]
	v_ldexp_f32 v14, v14, v37
	v_log_f32_e32 v14, v14
	v_cmp_gt_f32_e32 vcc, s81, v31
	v_cndmask_b32_e64 v37, 0, v203, s[4:5]
	v_sub_f32_e32 v39, 1.0, v18
	v_cndmask_b32_e64 v38, 0, 32, vcc
	v_ldexp_f32 v31, v31, v38
	v_mul_f32_e32 v38, 0x3f317217, v14
	v_fma_f32 v38, v14, s65, -v38
	v_fmac_f32_e32 v38, 0x3377d1cf, v14
	v_fmac_f32_e32 v38, 0x3f317217, v14
	v_cmp_lt_f32_e64 s[4:5], |v14|, s56
	v_log_f32_e32 v31, v31
	v_mul_f32_e32 v44, v42, v39
	v_cndmask_b32_e64 v14, v14, v38, s[4:5]
	v_cmp_gt_f32_e64 s[4:5], s81, v41
	v_sub_f32_e32 v45, v14, v37
	v_max_f32_e32 v37, v11, v11
	v_cndmask_b32_e64 v14, 0, 32, s[4:5]
	v_ldexp_f32 v14, v41, v14
	v_log_f32_e32 v14, v14
	v_min_f32_e32 v37, 0, v37
	v_mul_f32_e32 v42, 0x3f317217, v31
	v_fma_f32 v42, v31, s65, -v42
	v_mul_f32_e32 v38, 0x3f317217, v14
	v_fma_f32 v38, v14, s65, -v38
	v_fmac_f32_e32 v38, 0x3377d1cf, v14
	v_fmac_f32_e32 v38, 0x3f317217, v14
	v_cmp_lt_f32_e64 s[6:7], |v14|, s56
	v_fmac_f32_e32 v42, 0x3377d1cf, v31
	v_fmac_f32_e32 v42, 0x3f317217, v31
	v_cndmask_b32_e64 v14, v14, v38, s[6:7]
	v_cndmask_b32_e64 v38, 0, v203, s[4:5]
	v_sub_f32_e32 v41, v14, v38
	v_pk_add_f32 v[36:37], v[36:37], v[40:41] neg_lo:[0,1] neg_hi:[0,1]
	v_cmp_lt_f32_e64 s[4:5], |v31|, s56
	v_mul_f32_e32 v14, 0x3fb8aa3b, v36
	v_exp_f32_e32 v14, v14
	v_mul_f32_e32 v40, 0x3fb8aa3b, v37
	v_cndmask_b32_e64 v31, v31, v42, s[4:5]
	v_exp_f32_e32 v40, v40
	v_fma_f32 v14, v14, v39, v18
	v_cmp_gt_f32_e64 s[4:5], s81, v14
	v_mul_f32_e32 v11, 0x3fb8aa3b, v11
	v_exp_f32_e32 v11, v11
	v_cndmask_b32_e64 v38, 0, 32, s[4:5]
	v_ldexp_f32 v14, v14, v38
	v_cndmask_b32_e32 v38, 0, v203, vcc
	v_log_f32_e32 v14, v14
	v_sub_f32_e32 v31, v31, v38
	v_sub_f32_e32 v38, 1.0, v19
	v_fma_f32 v40, v40, v38, v19
	v_cmp_gt_f32_e32 vcc, s81, v40
	v_mul_f32_e32 v39, 0x3f317217, v14
	v_fma_f32 v39, v14, s65, -v39
	v_cndmask_b32_e64 v41, 0, 32, vcc
	v_ldexp_f32 v40, v40, v41
	v_log_f32_e32 v40, v40
	v_fmac_f32_e32 v39, 0x3377d1cf, v14
	v_fmac_f32_e32 v39, 0x3f317217, v14
	v_cmp_lt_f32_e64 s[6:7], |v14|, s56
	v_add_f32_e32 v11, 1.0, v11
	v_rcp_f32_e32 v11, v11
	v_cndmask_b32_e64 v14, v14, v39, s[6:7]
	v_cndmask_b32_e64 v39, 0, v203, s[4:5]
	v_sub_f32_e32 v46, v14, v39
	v_mul_f32_e32 v14, 0x3f317217, v40
	v_fma_f32 v14, v40, s65, -v14
	v_fmac_f32_e32 v14, 0x3377d1cf, v40
	v_fmac_f32_e32 v14, 0x3f317217, v40
	v_cmp_lt_f32_e64 s[4:5], |v40|, s56
	v_cndmask_b32_e32 v39, 0, v203, vcc
	v_mul_f32_e32 v49, v11, v38
	v_cndmask_b32_e64 v14, v40, v14, s[4:5]
	v_sub_f32_e32 v47, v14, v39
	v_add_f32_e32 v14, 1.0, v15
	v_mul_f32_e64 v15, |v16|, s82
	v_rcp_f32_e32 v14, v14
	v_exp_f32_e32 v15, v15
	v_max_f32_e32 v11, v16, v16
	v_mul_f32_e64 v38, |v12|, s82
	v_mul_f32_e32 v48, v14, v43
	v_add_f32_e32 v14, 1.0, v15
	v_cmp_gt_f32_e32 vcc, s81, v14
	v_exp_f32_e32 v39, v38
	v_sub_f32_e32 v41, 1.0, v24
	v_cndmask_b32_e64 v15, 0, 32, vcc
	v_ldexp_f32 v14, v14, v15
	v_log_f32_e32 v15, v14
	v_min_f32_e32 v14, 0, v11
	v_sub_f32_e32 v50, 1.0, v25
	v_mul_f32_e32 v11, 0x3f317217, v15
	v_fma_f32 v11, v15, s65, -v11
	v_fmac_f32_e32 v11, 0x3377d1cf, v15
	v_fmac_f32_e32 v11, 0x3f317217, v15
	v_cmp_lt_f32_e64 s[4:5], |v15|, s56
	s_nop 1
	v_cndmask_b32_e64 v11, v15, v11, s[4:5]
	v_cndmask_b32_e32 v15, 0, v203, vcc
	v_sub_f32_e32 v38, v11, v15
	v_add_f32_e32 v11, 1.0, v39
	v_cmp_gt_f32_e32 vcc, s81, v11
	s_nop 1
	v_cndmask_b32_e64 v15, 0, 32, vcc
	v_ldexp_f32 v11, v11, v15
	v_log_f32_e32 v11, v11
	v_max_f32_e32 v15, v12, v12
	v_min_f32_e32 v40, 0, v15
	v_mul_f32_e32 v12, 0x3fb8aa3b, v12
	v_mul_f32_e32 v15, 0x3f317217, v11
	v_fma_f32 v15, v11, s65, -v15
	v_fmac_f32_e32 v15, 0x3377d1cf, v11
	v_fmac_f32_e32 v15, 0x3f317217, v11
	v_cmp_lt_f32_e64 s[4:5], |v11|, s56
	v_exp_f32_e32 v12, v12
	s_nop 0
	v_cndmask_b32_e64 v11, v11, v15, s[4:5]
	v_cndmask_b32_e32 v15, 0, v203, vcc
	v_sub_f32_e32 v42, v11, v15
	v_mul_f32_e64 v15, |v17|, s82
	v_exp_f32_e32 v15, v15
	v_mul_f32_e32 v11, 0x3fb8aa3b, v16
	v_exp_f32_e32 v11, v11
	v_add_f32_e32 v12, 1.0, v12
	v_add_f32_e32 v15, 1.0, v15
	v_cmp_gt_f32_e32 vcc, s81, v15
	v_add_f32_e32 v11, 1.0, v11
	v_rcp_f32_e32 v11, v11
	v_cndmask_b32_e64 v39, 0, 32, vcc
	v_ldexp_f32 v15, v15, v39
	v_log_f32_e32 v39, v15
	v_max_f32_e32 v15, v17, v17
	v_min_f32_e32 v15, 0, v15
	v_mul_f32_e32 v11, v11, v41
	v_mul_f32_e32 v43, 0x3f317217, v39
	v_fma_f32 v43, v39, s65, -v43
	v_fmac_f32_e32 v43, 0x3377d1cf, v39
	v_fmac_f32_e32 v43, 0x3f317217, v39
	v_cmp_lt_f32_e64 s[4:5], |v39|, s56
	v_rcp_f32_e32 v12, v12
	v_sub_f32_e32 v16, 1.0, v20
	v_cndmask_b32_e64 v39, v39, v43, s[4:5]
	v_cndmask_b32_e32 v43, 0, v203, vcc
	v_sub_f32_e32 v39, v39, v43
	v_pk_add_f32 v[14:15], v[14:15], v[38:39] neg_lo:[0,1] neg_hi:[0,1]
	s_nop 0
	v_mul_f32_e32 v38, 0x3fb8aa3b, v14
	v_exp_f32_e32 v38, v38
	s_nop 0
	v_fma_f32 v38, v38, v41, v24
	v_mul_f32_e32 v41, 0x3fb8aa3b, v15
	v_cmp_gt_f32_e32 vcc, s81, v38
	v_exp_f32_e32 v41, v41
	s_nop 0
	v_cndmask_b32_e64 v39, 0, 32, vcc
	v_ldexp_f32 v38, v38, v39
	v_log_f32_e32 v38, v38
	v_fma_f32 v41, v41, v50, v25
	v_cmp_gt_f32_e64 s[4:5], s81, v41
	v_mul_f32_e32 v39, v12, v16
	v_mul_f32_e32 v12, 0x3f317217, v38
	v_cndmask_b32_e64 v43, 0, 32, s[4:5]
	v_ldexp_f32 v41, v41, v43
	v_fma_f32 v12, v38, s65, -v12
	v_log_f32_e32 v41, v41
	v_fmac_f32_e32 v12, 0x3377d1cf, v38
	v_fmac_f32_e32 v12, 0x3f317217, v38
	v_cmp_lt_f32_e64 s[6:7], |v38|, s56
	v_mul_f32_e64 v43, |v13|, s82
	v_exp_f32_e32 v43, v43
	v_cndmask_b32_e64 v12, v38, v12, s[6:7]
	v_cndmask_b32_e32 v38, 0, v203, vcc
	v_sub_f32_e32 v12, v12, v38
	v_mul_f32_e32 v38, 0x3f317217, v41
	v_fma_f32 v38, v41, s65, -v38
	v_fmac_f32_e32 v38, 0x3377d1cf, v41
	v_fmac_f32_e32 v38, 0x3f317217, v41
	v_cmp_lt_f32_e64 vcc, |v41|, s56
	s_nop 1
	v_cndmask_b32_e32 v38, v41, v38, vcc
	v_cmp_lt_f32_e32 vcc, 0, v23
	v_cndmask_b32_e64 v41, 0, v203, s[4:5]
	v_cmp_lt_f32_e64 s[4:5], 0, v22
	v_cndmask_b32_e32 v23, v35, v31, vcc
	v_add_f32_e32 v31, 1.0, v43
	v_cmp_gt_f32_e32 vcc, s81, v31
	v_cndmask_b32_e64 v22, v34, v45, s[4:5]
	v_max_f32_e32 v34, v13, v13
	v_cndmask_b32_e64 v35, 0, 32, vcc
	v_ldexp_f32 v31, v31, v35
	v_log_f32_e32 v31, v31
	v_sub_f32_e32 v38, v38, v41
	v_min_f32_e32 v41, 0, v34
	v_mul_f32_e32 v13, 0x3fb8aa3b, v13
	v_mul_f32_e32 v34, 0x3f317217, v31
	v_fma_f32 v34, v31, s65, -v34
	v_fmac_f32_e32 v34, 0x3377d1cf, v31
	v_fmac_f32_e32 v34, 0x3f317217, v31
	v_cmp_lt_f32_e64 s[4:5], |v31|, s56
	v_exp_f32_e32 v13, v13
	v_pk_mul_f32 v[22:23], v[22:23], s[68:69] op_sel_hi:[1,0]
	v_cndmask_b32_e64 v31, v31, v34, s[4:5]
	v_cndmask_b32_e32 v34, 0, v203, vcc
	v_sub_f32_e32 v43, v31, v34
	v_pk_add_f32 v[34:35], v[40:41], v[42:43] neg_lo:[0,1] neg_hi:[0,1]
	v_cmp_lt_f32_e32 vcc, 0, v25
	v_mul_f32_e32 v31, 0x3fb8aa3b, v34
	v_exp_f32_e32 v31, v31
	v_cndmask_b32_e32 v15, v15, v38, vcc
	v_cmp_lt_f32_e32 vcc, 0, v24
	s_nop 1
	v_cndmask_b32_e32 v14, v14, v12, vcc
	v_fma_f32 v12, v31, v16, v20
	v_pk_mul_f32 v[24:25], v[14:15], s[68:69] op_sel_hi:[1,0]
	v_mul_f32_e32 v15, 0x3fb8aa3b, v35
	v_cmp_gt_f32_e32 vcc, s81, v12
	v_exp_f32_e32 v15, v15
	s_nop 0
	v_cndmask_b32_e64 v16, 0, 32, vcc
	v_ldexp_f32 v12, v12, v16
	v_log_f32_e32 v12, v12
	v_sub_f32_e32 v16, 1.0, v21
	v_fma_f32 v15, v15, v16, v21
	v_cmp_gt_f32_e64 s[4:5], s81, v15
	v_mul_f32_e32 v14, 0x3f317217, v12
	v_fma_f32 v14, v12, s65, -v14
	v_cndmask_b32_e64 v31, 0, 32, s[4:5]
	v_ldexp_f32 v15, v15, v31
	v_log_f32_e32 v15, v15
	v_fmac_f32_e32 v14, 0x3377d1cf, v12
	v_fmac_f32_e32 v14, 0x3f317217, v12
	v_cmp_lt_f32_e64 s[6:7], |v12|, s56
	s_nop 1
	v_cndmask_b32_e64 v12, v12, v14, s[6:7]
	v_cndmask_b32_e32 v14, 0, v203, vcc
	v_sub_f32_e32 v12, v12, v14
	v_mul_f32_e32 v14, 0x3f317217, v15
	v_fma_f32 v14, v15, s65, -v14
	v_fmac_f32_e32 v14, 0x3377d1cf, v15
	v_fmac_f32_e32 v14, 0x3f317217, v15
	v_cmp_lt_f32_e64 vcc, |v15|, s56
	s_nop 1
	v_cndmask_b32_e32 v14, v15, v14, vcc
	v_cmp_lt_f32_e32 vcc, 0, v19
	v_cndmask_b32_e64 v15, 0, v203, s[4:5]
	v_sub_f32_e32 v14, v14, v15
	v_cndmask_b32_e32 v19, v37, v47, vcc
	v_cmp_lt_f32_e32 vcc, 0, v18
	s_nop 1
	v_cndmask_b32_e32 v18, v36, v46, vcc
	v_cmp_lt_f32_e32 vcc, 0, v21
	s_nop 1
	v_cndmask_b32_e32 v15, v35, v14, vcc
	v_mul_f32_e32 v14, 0x3fb8aa3b, v17
	v_exp_f32_e32 v17, v14
	v_cmp_lt_f32_e32 vcc, 0, v20
	s_nop 1
	v_cndmask_b32_e32 v14, v34, v12, vcc
	v_add_f32_e32 v12, 1.0, v17
	v_rcp_f32_e32 v17, v12
	v_add_f32_e32 v12, 1.0, v13
	v_rcp_f32_e32 v20, v12
	v_pk_mul_f32 v[14:15], v[14:15], s[68:69] op_sel_hi:[1,0]
	v_pk_mul_f32 v[12:13], v[18:19], s[68:69] op_sel_hi:[1,0]
	v_mul_f32_e32 v18, v17, v50
	v_mul_f32_e32 v19, v20, v16
	v_lshl_add_u64 v[16:17], v[28:29], 0, v[32:33]
	global_store_dwordx4 v[16:17], v[22:25], off
	global_store_dwordx4 v[16:17], v[12:15], off offset:16
	v_cvt_pk_bf16_f32 v10, v10, v48
	v_cvt_pk_bf16_f32 v11, v11, v18
	s_nop 1
	v_lshl_add_u64 v[14:15], v[148:149], 1, v[26:27]
	v_cvt_pk_bf16_f32 v12, v44, v49
	v_cvt_pk_bf16_f32 v13, v39, v19
	global_store_dwordx4 v[14:15], v[10:13], off

.LBB0_595:
	v_lshl_add_u64 v[18:19], v[148:149], 2, s[26:27]
	v_lshl_add_u64 v[10:11], s[14:15], 0, v[18:19]
	v_mov_b32_e32 v14, v214
	v_mov_b32_e32 v15, v215
	v_mov_b32_e32 v16, v216
	v_mov_b32_e32 v17, v217
	v_mov_b32_e32 v10, v218
	v_mov_b32_e32 v11, v219
	v_mov_b32_e32 v12, v220
	v_mov_b32_e32 v13, v221
	v_mul_f32_e64 v21, |v6|, s82
	v_mul_f32_e64 v23, |v2|, s82
	v_max_f32_e32 v24, v7, v7
	v_mul_f32_e64 v25, |v7|, s82
	v_exp_f32_e32 v31, v21
	v_max_f32_e32 v22, v2, v2
	v_mul_f32_e32 v2, 0x3fb8aa3b, v2
	v_mul_f32_e64 v30, |v3|, s82
	v_exp_f32_e32 v23, v23
	v_min_f32_e32 v21, 0, v24
	v_exp_f32_e32 v24, v25
	v_exp_f32_e32 v2, v2
	v_exp_f32_e32 v25, v30
	v_add_f32_e32 v30, 1.0, v31
	v_add_f32_e32 v23, 1.0, v23
	v_add_f32_e32 v24, 1.0, v24
	v_cmp_gt_f32_e32 vcc, s81, v30
	v_add_f32_e32 v2, 1.0, v2
	v_add_f32_e32 v31, 1.0, v25
	v_cndmask_b32_e64 v25, 0, 32, vcc
	v_cmp_gt_f32_e64 s[4:5], s81, v23
	v_cmp_gt_f32_e64 s[6:7], s81, v24
	v_rcp_f32_e32 v33, v2
	v_cndmask_b32_e64 v32, 0, 32, s[4:5]
	v_cndmask_b32_e64 v2, 0, 32, s[6:7]
	v_ldexp_f32 v25, v30, v25
	v_ldexp_f32 v23, v23, v32
	v_ldexp_f32 v2, v24, v2
	v_log_f32_e32 v24, v25
	v_log_f32_e32 v23, v23
	v_log_f32_e32 v2, v2
	v_cndmask_b32_e32 v30, 0, v203, vcc
	v_mul_f32_e32 v34, 0x3f317217, v24
	v_mul_f32_e32 v35, 0x3f317217, v23
	v_fma_f32 v34, v24, s65, -v34
	v_mul_f32_e32 v36, 0x3f317217, v2
	v_fma_f32 v35, v23, s65, -v35
	v_fmac_f32_e32 v34, 0x3377d1cf, v24
	v_fma_f32 v36, v2, s65, -v36
	v_fmac_f32_e32 v35, 0x3377d1cf, v23
	v_fmac_f32_e32 v34, 0x3f317217, v24
	v_cmp_lt_f32_e64 vcc, |v24|, s56
	v_max_f32_e32 v20, v6, v6
	v_mul_f32_e32 v6, 0x3fb8aa3b, v6
	v_fmac_f32_e32 v36, 0x3377d1cf, v2
	v_fmac_f32_e32 v35, 0x3f317217, v23
	v_cndmask_b32_e32 v24, v24, v34, vcc
	v_cmp_lt_f32_e64 vcc, |v23|, s56
	v_exp_f32_e32 v6, v6
	v_fmac_f32_e32 v36, 0x3f317217, v2
	v_cndmask_b32_e32 v23, v23, v35, vcc
	v_cmp_lt_f32_e64 vcc, |v2|, s56
	v_cndmask_b32_e64 v25, 0, v203, s[6:7]
	v_min_f32_e32 v20, 0, v20
	v_cndmask_b32_e32 v2, v2, v36, vcc
	v_sub_f32_e32 v24, v24, v30
	v_sub_f32_e32 v25, v2, v25
	v_pk_add_f32 v[20:21], v[20:21], v[24:25] neg_lo:[0,1] neg_hi:[0,1]
	v_add_f32_e32 v6, 1.0, v6
	v_mul_f32_e32 v2, 0x3fb8aa3b, v20
	v_rcp_f32_e32 v6, v6
	v_exp_f32_e32 v24, v2
	v_cndmask_b32_e64 v32, 0, v203, s[4:5]
	v_sub_f32_e32 v30, v23, v32
	v_mul_f32_e32 v23, 0x3fb8aa3b, v21
	v_exp_f32_e32 v23, v23
	v_min_f32_e32 v22, 0, v22
	v_mul_f32_e32 v7, 0x3fb8aa3b, v7
	v_exp_f32_e32 v7, v7
	v_sub_f32_e32 v25, 1.0, v14
	v_mul_f32_e32 v2, v6, v25
	v_fma_f32 v6, v24, v25, v14
	v_cmp_gt_f32_e64 s[4:5], s81, v6
	v_sub_f32_e32 v34, 1.0, v15
	v_fma_f32 v23, v23, v34, v15
	v_cndmask_b32_e64 v24, 0, 32, s[4:5]
	v_ldexp_f32 v6, v6, v24
	v_log_f32_e32 v6, v6
	v_cmp_gt_f32_e32 vcc, s81, v23
	v_sub_f32_e32 v32, 1.0, v10
	v_mul_f32_e32 v35, v33, v32
	v_cndmask_b32_e64 v25, 0, 32, vcc
	v_ldexp_f32 v23, v23, v25
	v_mul_f32_e32 v25, 0x3f317217, v6
	v_fma_f32 v25, v6, s65, -v25
	v_fmac_f32_e32 v25, 0x3377d1cf, v6
	v_log_f32_e32 v24, v23
	v_cndmask_b32_e64 v23, 0, v203, s[4:5]
	v_fmac_f32_e32 v25, 0x3f317217, v6
	v_cmp_lt_f32_e64 s[4:5], |v6|, s56
	v_mul_f32_e32 v33, 0x3f317217, v24
	v_fma_f32 v33, v24, s65, -v33
	v_cndmask_b32_e64 v6, v6, v25, s[4:5]
	v_cmp_gt_f32_e64 s[4:5], s81, v31
	v_sub_f32_e32 v36, v6, v23
	v_max_f32_e32 v23, v3, v3
	v_cndmask_b32_e64 v6, 0, 32, s[4:5]
	v_ldexp_f32 v6, v31, v6
	v_log_f32_e32 v6, v6
	v_min_f32_e32 v23, 0, v23
	v_fmac_f32_e32 v33, 0x3377d1cf, v24
	v_fmac_f32_e32 v33, 0x3f317217, v24
	v_mul_f32_e32 v25, 0x3f317217, v6
	v_fma_f32 v25, v6, s65, -v25
	v_fmac_f32_e32 v25, 0x3377d1cf, v6
	v_fmac_f32_e32 v25, 0x3f317217, v6
	v_cmp_lt_f32_e64 s[6:7], |v6|, s56
	v_mul_f32_e32 v3, 0x3fb8aa3b, v3
	v_exp_f32_e32 v3, v3
	v_cndmask_b32_e64 v6, v6, v25, s[6:7]
	v_cndmask_b32_e64 v25, 0, v203, s[4:5]
	v_sub_f32_e32 v31, v6, v25
	v_pk_add_f32 v[22:23], v[22:23], v[30:31] neg_lo:[0,1] neg_hi:[0,1]
	v_cmp_lt_f32_e64 s[4:5], |v24|, s56
	v_mul_f32_e32 v6, 0x3fb8aa3b, v22
	v_exp_f32_e32 v6, v6
	v_mul_f32_e32 v30, 0x3fb8aa3b, v23
	v_cndmask_b32_e64 v24, v24, v33, s[4:5]
	v_exp_f32_e32 v30, v30
	v_fma_f32 v6, v6, v32, v10
	v_cmp_gt_f32_e64 s[4:5], s81, v6
	v_add_f32_e32 v3, 1.0, v3
	v_rcp_f32_e32 v3, v3
	v_cndmask_b32_e64 v25, 0, 32, s[4:5]
	v_ldexp_f32 v6, v6, v25
	v_cndmask_b32_e32 v25, 0, v203, vcc
	v_log_f32_e32 v6, v6
	v_sub_f32_e32 v31, v24, v25
	v_sub_f32_e32 v24, 1.0, v11
	v_fma_f32 v30, v30, v24, v11
	v_cmp_gt_f32_e32 vcc, s81, v30
	v_mul_f32_e32 v25, 0x3f317217, v6
	v_fma_f32 v25, v6, s65, -v25
	v_cndmask_b32_e64 v32, 0, 32, vcc
	v_ldexp_f32 v30, v30, v32
	v_log_f32_e32 v30, v30
	v_fmac_f32_e32 v25, 0x3377d1cf, v6
	v_fmac_f32_e32 v25, 0x3f317217, v6
	v_cmp_lt_f32_e64 s[6:7], |v6|, s56
	v_mul_f32_e32 v39, v3, v24
	v_max_f32_e32 v3, v8, v8
	v_cndmask_b32_e64 v6, v6, v25, s[6:7]
	v_cndmask_b32_e64 v25, 0, v203, s[4:5]
	v_sub_f32_e32 v37, v6, v25
	v_mul_f32_e32 v6, 0x3f317217, v30
	v_fma_f32 v6, v30, s65, -v6
	v_fmac_f32_e32 v6, 0x3377d1cf, v30
	v_fmac_f32_e32 v6, 0x3f317217, v30
	v_cmp_lt_f32_e64 s[4:5], |v30|, s56
	v_cndmask_b32_e32 v25, 0, v203, vcc
	v_mul_f32_e64 v24, |v4|, s82
	v_cndmask_b32_e64 v6, v30, v6, s[4:5]
	v_sub_f32_e32 v38, v6, v25
	v_add_f32_e32 v6, 1.0, v7
	v_mul_f32_e64 v7, |v8|, s82
	v_rcp_f32_e32 v6, v6
	v_exp_f32_e32 v7, v7
	v_exp_f32_e32 v25, v24
	v_sub_f32_e32 v33, 1.0, v16
	v_mul_f32_e32 v34, v6, v34
	v_add_f32_e32 v6, 1.0, v7
	v_cmp_gt_f32_e32 vcc, s81, v6
	s_nop 1
	v_cndmask_b32_e64 v7, 0, 32, vcc
	v_ldexp_f32 v6, v6, v7
	v_log_f32_e32 v7, v6
	v_min_f32_e32 v6, 0, v3
	v_mul_f32_e32 v3, 0x3f317217, v7
	v_fma_f32 v3, v7, s65, -v3
	v_fmac_f32_e32 v3, 0x3377d1cf, v7
	v_fmac_f32_e32 v3, 0x3f317217, v7
	v_cmp_lt_f32_e64 s[4:5], |v7|, s56
	s_nop 1
	v_cndmask_b32_e64 v3, v7, v3, s[4:5]
	v_cndmask_b32_e32 v7, 0, v203, vcc
	v_sub_f32_e32 v24, v3, v7
	v_add_f32_e32 v3, 1.0, v25
	v_cmp_gt_f32_e32 vcc, s81, v3
	s_nop 1
	v_cndmask_b32_e64 v7, 0, 32, vcc
	v_ldexp_f32 v3, v3, v7
	v_log_f32_e32 v3, v3
	v_max_f32_e32 v7, v4, v4
	v_min_f32_e32 v30, 0, v7
	v_mul_f32_e32 v4, 0x3fb8aa3b, v4
	v_mul_f32_e32 v7, 0x3f317217, v3
	v_fma_f32 v7, v3, s65, -v7
	v_fmac_f32_e32 v7, 0x3377d1cf, v3
	v_fmac_f32_e32 v7, 0x3f317217, v3
	v_cmp_lt_f32_e64 s[4:5], |v3|, s56
	v_exp_f32_e32 v4, v4
	s_nop 0
	v_cndmask_b32_e64 v3, v3, v7, s[4:5]
	v_cndmask_b32_e32 v7, 0, v203, vcc
	v_sub_f32_e32 v32, v3, v7
	v_mul_f32_e64 v7, |v9|, s82
	v_exp_f32_e32 v7, v7
	v_mul_f32_e32 v3, 0x3fb8aa3b, v8
	v_exp_f32_e32 v3, v3
	v_add_f32_e32 v4, 1.0, v4
	v_add_f32_e32 v7, 1.0, v7
	v_cmp_gt_f32_e32 vcc, s81, v7
	v_add_f32_e32 v3, 1.0, v3
	v_rcp_f32_e32 v3, v3
	v_cndmask_b32_e64 v25, 0, 32, vcc
	v_ldexp_f32 v7, v7, v25
	v_log_f32_e32 v25, v7
	v_max_f32_e32 v7, v9, v9
	v_min_f32_e32 v7, 0, v7
	v_mul_f32_e32 v3, v3, v33
	v_mul_f32_e32 v40, 0x3f317217, v25
	v_fma_f32 v40, v25, s65, -v40
	v_fmac_f32_e32 v40, 0x3377d1cf, v25
	v_fmac_f32_e32 v40, 0x3f317217, v25
	v_cmp_lt_f32_e64 s[4:5], |v25|, s56
	v_rcp_f32_e32 v4, v4
	v_sub_f32_e32 v8, 1.0, v12
	v_cndmask_b32_e64 v25, v25, v40, s[4:5]
	v_cndmask_b32_e32 v40, 0, v203, vcc
	v_sub_f32_e32 v25, v25, v40
	v_pk_add_f32 v[6:7], v[6:7], v[24:25] neg_lo:[0,1] neg_hi:[0,1]
	v_sub_f32_e32 v40, 1.0, v17
	v_mul_f32_e32 v24, 0x3fb8aa3b, v6
	v_exp_f32_e32 v24, v24
	s_nop 0
	v_fma_f32 v24, v24, v33, v16
	v_mul_f32_e32 v33, 0x3fb8aa3b, v7
	v_cmp_gt_f32_e32 vcc, s81, v24
	v_exp_f32_e32 v33, v33
	s_nop 0
	v_cndmask_b32_e64 v25, 0, 32, vcc
	v_ldexp_f32 v24, v24, v25
	v_log_f32_e32 v24, v24
	v_fma_f32 v33, v33, v40, v17
	v_cmp_gt_f32_e64 s[4:5], s81, v33
	v_mul_f32_e32 v25, v4, v8
	v_mul_f32_e32 v4, 0x3f317217, v24
	v_cndmask_b32_e64 v41, 0, 32, s[4:5]
	v_ldexp_f32 v33, v33, v41
	v_fma_f32 v4, v24, s65, -v4
	v_log_f32_e32 v33, v33
	v_fmac_f32_e32 v4, 0x3377d1cf, v24
	v_fmac_f32_e32 v4, 0x3f317217, v24
	v_cmp_lt_f32_e64 s[6:7], |v24|, s56
	v_mul_f32_e64 v41, |v5|, s82
	v_exp_f32_e32 v41, v41
	v_cndmask_b32_e64 v4, v24, v4, s[6:7]
	v_cndmask_b32_e32 v24, 0, v203, vcc
	v_sub_f32_e32 v4, v4, v24
	v_mul_f32_e32 v24, 0x3f317217, v33
	v_fma_f32 v24, v33, s65, -v24
	v_fmac_f32_e32 v24, 0x3377d1cf, v33
	v_fmac_f32_e32 v24, 0x3f317217, v33
	v_cmp_lt_f32_e64 vcc, |v33|, s56
	s_nop 1
	v_cndmask_b32_e32 v24, v33, v24, vcc
	v_cmp_lt_f32_e32 vcc, 0, v15
	v_cndmask_b32_e64 v33, 0, v203, s[4:5]
	v_cmp_lt_f32_e64 s[4:5], 0, v14
	v_cndmask_b32_e32 v15, v21, v31, vcc
	v_add_f32_e32 v21, 1.0, v41
	v_cmp_gt_f32_e32 vcc, s81, v21
	v_cndmask_b32_e64 v14, v20, v36, s[4:5]
	v_max_f32_e32 v20, v5, v5
	v_cndmask_b32_e64 v31, 0, 32, vcc
	v_ldexp_f32 v21, v21, v31
	v_log_f32_e32 v21, v21
	v_min_f32_e32 v31, 0, v20
	v_sub_f32_e32 v24, v24, v33
	v_mul_f32_e32 v5, 0x3fb8aa3b, v5
	v_mul_f32_e32 v20, 0x3f317217, v21
	v_fma_f32 v20, v21, s65, -v20
	v_fmac_f32_e32 v20, 0x3377d1cf, v21
	v_fmac_f32_e32 v20, 0x3f317217, v21
	v_cmp_lt_f32_e64 s[4:5], |v21|, s56
	v_exp_f32_e32 v5, v5
	v_pk_mul_f32 v[14:15], v[14:15], s[68:69] op_sel_hi:[1,0]
	v_cndmask_b32_e64 v20, v21, v20, s[4:5]
	v_cndmask_b32_e32 v21, 0, v203, vcc
	v_sub_f32_e32 v33, v20, v21
	v_pk_add_f32 v[20:21], v[30:31], v[32:33] neg_lo:[0,1] neg_hi:[0,1]
	v_cmp_lt_f32_e32 vcc, 0, v17
	v_mul_f32_e32 v30, 0x3fb8aa3b, v20
	v_exp_f32_e32 v30, v30
	v_cndmask_b32_e32 v7, v7, v24, vcc
	v_cmp_lt_f32_e32 vcc, 0, v16
	s_nop 1
	v_cndmask_b32_e32 v6, v6, v4, vcc
	v_fma_f32 v4, v30, v8, v12
	v_pk_mul_f32 v[16:17], v[6:7], s[68:69] op_sel_hi:[1,0]
	v_mul_f32_e32 v7, 0x3fb8aa3b, v21
	v_cmp_gt_f32_e32 vcc, s81, v4
	v_exp_f32_e32 v7, v7
	s_nop 0
	v_cndmask_b32_e64 v8, 0, 32, vcc
	v_ldexp_f32 v4, v4, v8
	v_log_f32_e32 v4, v4
	v_sub_f32_e32 v8, 1.0, v13
	v_fma_f32 v7, v7, v8, v13
	v_cmp_gt_f32_e64 s[4:5], s81, v7
	v_mul_f32_e32 v6, 0x3f317217, v4
	v_fma_f32 v6, v4, s65, -v6
	v_cndmask_b32_e64 v24, 0, 32, s[4:5]
	v_ldexp_f32 v7, v7, v24
	v_log_f32_e32 v7, v7
	v_fmac_f32_e32 v6, 0x3377d1cf, v4
	v_fmac_f32_e32 v6, 0x3f317217, v4
	v_cmp_lt_f32_e64 s[6:7], |v4|, s56
	s_nop 1
	v_cndmask_b32_e64 v4, v4, v6, s[6:7]
	v_cndmask_b32_e32 v6, 0, v203, vcc
	v_sub_f32_e32 v4, v4, v6
	v_mul_f32_e32 v6, 0x3f317217, v7
	v_fma_f32 v6, v7, s65, -v6
	v_fmac_f32_e32 v6, 0x3377d1cf, v7
	v_fmac_f32_e32 v6, 0x3f317217, v7
	v_cmp_lt_f32_e64 vcc, |v7|, s56
	s_nop 1
	v_cndmask_b32_e32 v6, v7, v6, vcc
	v_cmp_lt_f32_e32 vcc, 0, v11
	v_cndmask_b32_e64 v7, 0, v203, s[4:5]
	v_sub_f32_e32 v6, v6, v7
	v_cndmask_b32_e32 v11, v23, v38, vcc
	v_cmp_lt_f32_e32 vcc, 0, v10
	s_nop 1
	v_cndmask_b32_e32 v10, v22, v37, vcc
	v_cmp_lt_f32_e32 vcc, 0, v13
	s_nop 1
	v_cndmask_b32_e32 v7, v21, v6, vcc
	v_mul_f32_e32 v6, 0x3fb8aa3b, v9
	v_exp_f32_e32 v9, v6
	v_cmp_lt_f32_e32 vcc, 0, v12
	s_nop 1
	v_cndmask_b32_e32 v6, v20, v4, vcc
	v_add_f32_e32 v4, 1.0, v9
	v_rcp_f32_e32 v9, v4
	v_add_f32_e32 v4, 1.0, v5
	v_rcp_f32_e32 v12, v4
	v_pk_mul_f32 v[6:7], v[6:7], s[68:69] op_sel_hi:[1,0]
	v_pk_mul_f32 v[4:5], v[10:11], s[68:69] op_sel_hi:[1,0]
	v_mul_f32_e32 v10, v9, v40
	v_mul_f32_e32 v11, v12, v8
	v_lshl_add_u64 v[8:9], v[28:29], 0, v[18:19]
	global_store_dwordx4 v[8:9], v[14:17], off
	global_store_dwordx4 v[8:9], v[4:7], off offset:16
	v_cvt_pk_bf16_f32 v2, v2, v34
	v_cvt_pk_bf16_f32 v3, v3, v10
	s_nop 1
	v_lshl_add_u64 v[6:7], v[148:149], 1, v[26:27]
	v_cvt_pk_bf16_f32 v4, v35, v39
	v_cvt_pk_bf16_f32 v5, v25, v11
	global_store_dwordx4 v[6:7], v[2:5], off offset:256
	s_andn2_b64 vcc, exec, s[88:89]
	s_mov_b64 s[0:1], -1
	s_cbranch_vccnz .LBB0_404
